# GEMM K-loops: 115 LDS-DMA loads use SGPR base + 32-bit VGPR offset (saddr) instead of a v_lshl_add_u64 each, on top of the setprio deletion
# baseline (speedup 1.0000x reference)
.LBB0_95:
	s_add_u32 s12, s18, 0x10000000
	s_addc_u32 s13, s19, 0
	s_add_u32 s44, s18, 0x25000000
	s_addc_u32 s45, s19, 0
	s_add_u32 s18, s18, 0x8000000
	s_addc_u32 s19, s19, 0
	s_lshl_b32 s2, s2, 5
	s_and_b32 s66, s2, 0x60
	s_add_i32 m0, s62, 0x18000
	v_lshl_add_u64 v[8:9], v[8:9], 0, s[24:25]
	s_lshl_b32 s7, s3, 13
	s_lshl_b32 s2, s66, 7
	s_waitcnt vmcnt(2)
	s_barrier
	global_load_lds_dwordx4 v[8:9], off
	v_lshl_add_u64 v[6:7], v[6:7], 0, s[24:25]
	s_add_i32 m0, s62, 0x1a000
	s_add_i32 s67, s62, 0x8000
	s_add_i32 s68, s62, 0xa000
	global_load_lds_dwordx4 v[6:7], off
	v_lshl_add_u64 v[2:3], v[2:3], 0, s[24:25]
	s_mov_b32 m0, s67
	s_add_u32 s20, s8, 0x40080
	global_load_lds_dwordx4 v[2:3], off
	v_lshl_add_u64 v[2:3], v[4:5], 0, s[24:25]
	s_mov_b32 m0, s68
	s_addc_u32 s21, s9, 0
	global_load_lds_dwordx4 v[2:3], off
	s_add_i32 m0, s62, 0x1c000
	global_load_lds_dwordx4 v0, s[20:21]
	v_lshl_add_u64 v[2:3], s[20:21], 0, v[134:135]
	s_add_i32 m0, s62, 0x1e000
	s_cmpk_lt_u32 s5, 0x100
	global_load_lds_dwordx4 v[2:3], off
	s_cselect_b64 s[46:47], -1, 0
	s_lshl_b32 s69, s4, 3
	v_lshrrev_b32_e32 v3, 1, v10
	s_abs_i32 s70, s69
	v_and_b32_e32 v153, 24, v3
	v_cvt_f32_u32_e32 v5, s70
	v_and_b32_e32 v2, 15, v10
	v_lshlrev_b32_e32 v3, 1, v153
	v_lshl_or_b32 v152, s3, 6, v2
	v_lshl_or_b32 v2, v2, 6, v3
	v_lshlrev_b32_e32 v3, 2, v10
	v_and_b32_e32 v3, 32, v3
	v_bitop3_b32 v4, v2, s7, v3 bitop3:0xde
	v_bitop3_b32 v154, v2, s2, v3 bitop3:0xde
	v_rcp_iflag_f32_e32 v2, v5
	v_and_b32_e32 v3, 1, v11
	s_sub_i32 s2, 0, s70
	s_waitcnt vmcnt(6)
	v_mul_f32_e32 v2, 0x4f7ffffe, v2
	v_cvt_u32_f32_e32 v2, v2
	s_ashr_i32 s71, s41, 31
	s_ashr_i32 s72, s58, 31
	s_lshl_b32 s73, s4, 5
	v_readfirstlane_b32 s3, v2
	v_lshlrev_b32_e32 v2, 14, v11
	v_and_b32_e32 v2, 0xffff8000, v2
	v_lshl_add_u32 v2, v12, 11, v2
	v_lshl_or_b32 v2, v3, 6, v2
	v_lshl_add_u32 v136, v13, 1, v2
	v_lshlrev_b32_e32 v2, 14, v14
	v_and_b32_e32 v2, 0xffff8000, v2
	s_mul_i32 s2, s2, s3
	v_lshl_add_u32 v2, v15, 11, v2
	v_and_b32_e32 v3, 1, v14
	s_mul_hi_u32 s2, s3, s2
	v_lshl_or_b32 v2, v3, 6, v2
	s_bfe_i32 s81, s4, 0x1001c
	s_mov_b32 s85, 0
	s_add_i32 s86, s3, s2
	v_mov_b32_e32 v137, v1
	v_lshl_add_u32 v138, v16, 1, v2
	v_mov_b32_e32 v139, v1
	v_mov_b64_e32 v[140:141], s[22:23]
	v_add_u32_e32 v155, 0, v4
	s_barrier
	s_branch .LBB0_98

.LBB0_103:
	s_add_u32 s8, s4, 0xfffc0080
	s_addc_u32 s9, s5, -1
	s_add_i32 s20, 0, 0x10000
	s_cmp_eq_u32 s88, 12
	s_cselect_b32 s55, s51, s9
	s_cselect_b32 s54, s50, s8
	v_add_u32_e32 v150, s20, v154
	s_cselect_b32 s9, s7, s87
	s_cselect_b32 s8, s49, s57
	s_add_i32 s37, 0, 0x14000
	ds_read_b128 v[142:145], v150
	ds_read_b128 v[146:149], v150 offset:1024
	ds_read_b128 v[156:159], v150 offset:2048
	ds_read_b128 v[160:163], v150 offset:3072
	v_add_u32_e32 v150, s37, v154
	ds_read_b128 v[164:167], v150
	ds_read_b128 v[168:171], v150 offset:1024
	ds_read_b128 v[172:175], v150 offset:2048
	ds_read_b128 v[202:205], v150 offset:3072
	s_add_i32 m0, s62, 0xc000
	ds_read_b128 v[206:209], v155
	ds_read_b128 v[222:225], v155 offset:1024
	ds_read_b128 v[226:229], v155 offset:2048
	ds_read_b128 v[230:233], v155 offset:3072
	ds_read_b128 v[234:237], v155 offset:4096
	ds_read_b128 v[238:241], v155 offset:5120
	ds_read_b128 v[242:245], v155 offset:6144
	ds_read_b128 v[246:249], v155 offset:7168
	global_load_lds_dwordx4 v136, s[4:5]
	s_add_i32 m0, s62, 0xe000
	s_nop 0
	global_load_lds_dwordx4 v138, s[4:5]
	s_waitcnt vmcnt(8)
	s_waitcnt lgkmcnt(0)
	s_barrier
	s_waitcnt lgkmcnt(0)
	v_mfma_f32_16x16x32_bf16 v[126:129], v[142:145], v[206:209], v[126:129]
	v_mfma_f32_16x16x32_bf16 v[122:125], v[156:159], v[206:209], v[122:125]
	v_mfma_f32_16x16x32_bf16 v[110:113], v[142:145], v[226:229], v[110:113]
	v_mfma_f32_16x16x32_bf16 v[106:109], v[156:159], v[226:229], v[106:109]
	v_mfma_f32_16x16x32_bf16 v[94:97], v[142:145], v[234:237], v[94:97]
	v_mfma_f32_16x16x32_bf16 v[90:93], v[156:159], v[234:237], v[90:93]
	v_mfma_f32_16x16x32_bf16 v[78:81], v[142:145], v[242:245], v[78:81]
	v_mfma_f32_16x16x32_bf16 v[74:77], v[156:159], v[242:245], v[74:77]
	v_mfma_f32_16x16x32_bf16 v[126:129], v[146:149], v[222:225], v[126:129]
	v_mfma_f32_16x16x32_bf16 v[122:125], v[160:163], v[222:225], v[122:125]
	v_mfma_f32_16x16x32_bf16 v[110:113], v[146:149], v[230:233], v[110:113]
	v_mfma_f32_16x16x32_bf16 v[106:109], v[160:163], v[230:233], v[106:109]
	v_mfma_f32_16x16x32_bf16 v[94:97], v[146:149], v[238:241], v[94:97]
	v_mfma_f32_16x16x32_bf16 v[90:93], v[160:163], v[238:241], v[90:93]
	v_mfma_f32_16x16x32_bf16 v[78:81], v[146:149], v[246:249], v[78:81]
	v_mfma_f32_16x16x32_bf16 v[74:77], v[160:163], v[246:249], v[74:77]
	v_mfma_f32_16x16x32_bf16 v[118:121], v[164:167], v[206:209], v[118:121]
	v_mfma_f32_16x16x32_bf16 v[114:117], v[172:175], v[206:209], v[114:117]
	v_mfma_f32_16x16x32_bf16 v[102:105], v[164:167], v[226:229], v[102:105]
	v_mfma_f32_16x16x32_bf16 v[98:101], v[172:175], v[226:229], v[98:101]
	v_mfma_f32_16x16x32_bf16 v[86:89], v[164:167], v[234:237], v[86:89]
	v_mfma_f32_16x16x32_bf16 v[82:85], v[172:175], v[234:237], v[82:85]
	v_mfma_f32_16x16x32_bf16 v[70:73], v[164:167], v[242:245], v[70:73]
	v_mfma_f32_16x16x32_bf16 v[66:69], v[172:175], v[242:245], v[66:69]
	v_mfma_f32_16x16x32_bf16 v[118:121], v[168:171], v[222:225], v[118:121]
	v_mfma_f32_16x16x32_bf16 v[114:117], v[202:205], v[222:225], v[114:117]
	v_mfma_f32_16x16x32_bf16 v[102:105], v[168:171], v[230:233], v[102:105]
	v_mfma_f32_16x16x32_bf16 v[98:101], v[202:205], v[230:233], v[98:101]
	v_mfma_f32_16x16x32_bf16 v[86:89], v[168:171], v[238:241], v[86:89]
	v_mfma_f32_16x16x32_bf16 v[82:85], v[202:205], v[238:241], v[82:85]
	v_mfma_f32_16x16x32_bf16 v[70:73], v[168:171], v[246:249], v[70:73]
	v_mfma_f32_16x16x32_bf16 v[66:69], v[202:205], v[246:249], v[66:69]
	s_barrier
	s_add_i32 s20, s20, s61
	v_lshl_add_u64 v[150:151], s[8:9], 0, v[0:1]
	s_mov_b32 m0, s20
	ds_read_b128 v[206:209], v155 offset:16384
	ds_read_b128 v[222:225], v155 offset:17408
	ds_read_b128 v[226:229], v155 offset:18432
	ds_read_b128 v[230:233], v155 offset:19456
	ds_read_b128 v[234:237], v155 offset:20480
	ds_read_b128 v[238:241], v155 offset:21504
	ds_read_b128 v[242:245], v155 offset:22528
	ds_read_b128 v[246:249], v155 offset:23552
	global_load_lds_dwordx4 v[150:151], off
	s_add_i32 m0, s20, 0x2000
	s_add_u32 s20, s8, 0x40000
	v_lshl_add_u64 v[176:177], s[8:9], 0, v[134:135]
	s_addc_u32 s21, s9, 0
	s_add_i32 s37, s37, s61
	global_load_lds_dwordx4 v[176:177], off
	s_mov_b32 m0, s37
	v_lshl_add_u64 v[180:181], s[54:55], 0, v[132:133]
	global_load_lds_dwordx4 v0, s[20:21]
	s_add_i32 m0, s37, 0x2000
	s_nop 0
	global_load_lds_dwordx4 v134, s[20:21]
	v_lshl_add_u64 v[178:179], s[54:55], 0, v[130:131]
	s_mov_b32 m0, s62
	s_nop 0
	global_load_lds_dwordx4 v[178:179], off
	s_mov_b32 m0, s63
	s_nop 0
	global_load_lds_dwordx4 v[180:181], off
	s_waitcnt vmcnt(8)
	s_waitcnt lgkmcnt(0)
	s_barrier
	s_waitcnt lgkmcnt(0)
	v_mfma_f32_16x16x32_bf16 v[62:65], v[142:145], v[206:209], v[62:65]
	v_mfma_f32_16x16x32_bf16 v[58:61], v[156:159], v[206:209], v[58:61]
	v_mfma_f32_16x16x32_bf16 v[46:49], v[142:145], v[226:229], v[46:49]
	v_mfma_f32_16x16x32_bf16 v[42:45], v[156:159], v[226:229], v[42:45]
	v_mfma_f32_16x16x32_bf16 v[30:33], v[142:145], v[234:237], v[30:33]
	v_mfma_f32_16x16x32_bf16 v[26:29], v[156:159], v[234:237], v[26:29]
	v_mfma_f32_16x16x32_bf16 v[14:17], v[142:145], v[242:245], v[14:17]
	v_mfma_f32_16x16x32_bf16 v[10:13], v[156:159], v[242:245], v[10:13]
	v_mfma_f32_16x16x32_bf16 v[62:65], v[146:149], v[222:225], v[62:65]
	v_mfma_f32_16x16x32_bf16 v[58:61], v[160:163], v[222:225], v[58:61]
	v_mfma_f32_16x16x32_bf16 v[46:49], v[146:149], v[230:233], v[46:49]
	v_mfma_f32_16x16x32_bf16 v[42:45], v[160:163], v[230:233], v[42:45]
	v_mfma_f32_16x16x32_bf16 v[30:33], v[146:149], v[238:241], v[30:33]
	v_mfma_f32_16x16x32_bf16 v[26:29], v[160:163], v[238:241], v[26:29]
	v_mfma_f32_16x16x32_bf16 v[14:17], v[146:149], v[246:249], v[14:17]
	v_mfma_f32_16x16x32_bf16 v[10:13], v[160:163], v[246:249], v[10:13]
	v_mfma_f32_16x16x32_bf16 v[54:57], v[164:167], v[206:209], v[54:57]
	v_mfma_f32_16x16x32_bf16 v[50:53], v[172:175], v[206:209], v[50:53]
	v_mfma_f32_16x16x32_bf16 v[38:41], v[164:167], v[226:229], v[38:41]
	v_mfma_f32_16x16x32_bf16 v[34:37], v[172:175], v[226:229], v[34:37]
	v_mfma_f32_16x16x32_bf16 v[22:25], v[164:167], v[234:237], v[22:25]
	v_mfma_f32_16x16x32_bf16 v[18:21], v[172:175], v[234:237], v[18:21]
	v_mfma_f32_16x16x32_bf16 v[6:9], v[164:167], v[242:245], v[6:9]
	v_mfma_f32_16x16x32_bf16 v[2:5], v[172:175], v[242:245], v[2:5]
	v_mfma_f32_16x16x32_bf16 v[54:57], v[168:171], v[222:225], v[54:57]
	v_mfma_f32_16x16x32_bf16 v[50:53], v[202:205], v[222:225], v[50:53]
	v_mfma_f32_16x16x32_bf16 v[38:41], v[168:171], v[230:233], v[38:41]
	v_mfma_f32_16x16x32_bf16 v[34:37], v[202:205], v[230:233], v[34:37]
	v_mfma_f32_16x16x32_bf16 v[22:25], v[168:171], v[238:241], v[22:25]
	v_mfma_f32_16x16x32_bf16 v[18:21], v[202:205], v[238:241], v[18:21]
	v_mfma_f32_16x16x32_bf16 v[6:9], v[168:171], v[246:249], v[6:9]
	v_mfma_f32_16x16x32_bf16 v[2:5], v[202:205], v[246:249], v[2:5]
	s_barrier
	s_add_i32 s37, 0, 0x18000
	s_add_i32 s77, 0, 0x1c000
	v_add_u32_e32 v160, s37, v154
	v_add_u32_e32 v182, s77, v154
	ds_read_b128 v[142:145], v160
	ds_read_b128 v[146:149], v160 offset:1024
	ds_read_b128 v[156:159], v160 offset:2048
	ds_read_b128 v[160:163], v160 offset:3072
	ds_read_b128 v[164:167], v182
	ds_read_b128 v[168:171], v182 offset:1024
	ds_read_b128 v[172:175], v182 offset:2048
	ds_read_b128 v[202:205], v182 offset:3072
	s_add_u32 s20, s54, 0x40000
	s_addc_u32 s21, s55, 0
	s_mov_b32 m0, s64
	ds_read_b128 v[206:209], v155 offset:32768
	ds_read_b128 v[222:225], v155 offset:33792
	ds_read_b128 v[226:229], v155 offset:34816
	ds_read_b128 v[230:233], v155 offset:35840
	ds_read_b128 v[234:237], v155 offset:36864
	ds_read_b128 v[238:241], v155 offset:37888
	ds_read_b128 v[242:245], v155 offset:38912
	ds_read_b128 v[246:249], v155 offset:39936
	global_load_lds_dwordx4 v130, s[20:21]
	v_lshl_add_u64 v[182:183], s[20:21], 0, v[132:133]
	s_mov_b32 m0, s65
	s_nop 0
	global_load_lds_dwordx4 v[182:183], off
	s_waitcnt vmcnt(8)
	s_waitcnt lgkmcnt(0)
	s_barrier
	s_waitcnt lgkmcnt(0)
	v_mfma_f32_16x16x32_bf16 v[126:129], v[142:145], v[206:209], v[126:129]
	v_mfma_f32_16x16x32_bf16 v[122:125], v[156:159], v[206:209], v[122:125]
	v_mfma_f32_16x16x32_bf16 v[110:113], v[142:145], v[226:229], v[110:113]
	v_mfma_f32_16x16x32_bf16 v[106:109], v[156:159], v[226:229], v[106:109]
	v_mfma_f32_16x16x32_bf16 v[94:97], v[142:145], v[234:237], v[94:97]
	v_mfma_f32_16x16x32_bf16 v[90:93], v[156:159], v[234:237], v[90:93]
	v_mfma_f32_16x16x32_bf16 v[78:81], v[142:145], v[242:245], v[78:81]
	v_mfma_f32_16x16x32_bf16 v[74:77], v[156:159], v[242:245], v[74:77]
	v_mfma_f32_16x16x32_bf16 v[126:129], v[146:149], v[222:225], v[126:129]
	v_mfma_f32_16x16x32_bf16 v[122:125], v[160:163], v[222:225], v[122:125]
	v_mfma_f32_16x16x32_bf16 v[110:113], v[146:149], v[230:233], v[110:113]
	v_mfma_f32_16x16x32_bf16 v[106:109], v[160:163], v[230:233], v[106:109]
	v_mfma_f32_16x16x32_bf16 v[94:97], v[146:149], v[238:241], v[94:97]
	v_mfma_f32_16x16x32_bf16 v[90:93], v[160:163], v[238:241], v[90:93]
	v_mfma_f32_16x16x32_bf16 v[78:81], v[146:149], v[246:249], v[78:81]
	v_mfma_f32_16x16x32_bf16 v[74:77], v[160:163], v[246:249], v[74:77]
	v_mfma_f32_16x16x32_bf16 v[118:121], v[164:167], v[206:209], v[118:121]
	v_mfma_f32_16x16x32_bf16 v[114:117], v[172:175], v[206:209], v[114:117]
	v_mfma_f32_16x16x32_bf16 v[102:105], v[164:167], v[226:229], v[102:105]
	v_mfma_f32_16x16x32_bf16 v[98:101], v[172:175], v[226:229], v[98:101]
	v_mfma_f32_16x16x32_bf16 v[86:89], v[164:167], v[234:237], v[86:89]
	v_mfma_f32_16x16x32_bf16 v[82:85], v[172:175], v[234:237], v[82:85]
	v_mfma_f32_16x16x32_bf16 v[70:73], v[164:167], v[242:245], v[70:73]
	v_mfma_f32_16x16x32_bf16 v[66:69], v[172:175], v[242:245], v[66:69]
	v_mfma_f32_16x16x32_bf16 v[118:121], v[168:171], v[222:225], v[118:121]
	v_mfma_f32_16x16x32_bf16 v[114:117], v[202:205], v[222:225], v[114:117]
	v_mfma_f32_16x16x32_bf16 v[102:105], v[168:171], v[230:233], v[102:105]
	v_mfma_f32_16x16x32_bf16 v[98:101], v[202:205], v[230:233], v[98:101]
	v_mfma_f32_16x16x32_bf16 v[86:89], v[168:171], v[238:241], v[86:89]
	v_mfma_f32_16x16x32_bf16 v[82:85], v[202:205], v[238:241], v[82:85]
	v_mfma_f32_16x16x32_bf16 v[70:73], v[168:171], v[246:249], v[70:73]
	v_mfma_f32_16x16x32_bf16 v[66:69], v[202:205], v[246:249], v[66:69]
	s_barrier
	s_add_i32 s20, s37, s61
	v_lshl_add_u64 v[150:151], v[150:151], 0, s[24:25]
	s_mov_b32 m0, s20
	ds_read_b128 v[206:209], v155 offset:49152
	ds_read_b128 v[222:225], v155 offset:50176
	ds_read_b128 v[226:229], v155 offset:51200
	ds_read_b128 v[230:233], v155 offset:52224
	ds_read_b128 v[234:237], v155 offset:53248
	ds_read_b128 v[238:241], v155 offset:54272
	ds_read_b128 v[242:245], v155 offset:55296
	ds_read_b128 v[246:249], v155 offset:56320
	global_load_lds_dwordx4 v[150:151], off
	s_add_i32 m0, s20, 0x2000
	s_add_u32 s8, s8, 0x40080
	v_lshl_add_u64 v[150:151], v[176:177], 0, s[24:25]
	s_addc_u32 s9, s9, 0
	s_add_i32 s20, s77, s61
	global_load_lds_dwordx4 v[150:151], off
	s_mov_b32 m0, s20
	s_nop 0
	global_load_lds_dwordx4 v0, s[8:9]
	s_add_i32 m0, s20, 0x2000
	s_nop 0
	global_load_lds_dwordx4 v134, s[8:9]
	v_lshl_add_u64 v[150:151], v[178:179], 0, s[24:25]
	s_mov_b32 m0, s67
	s_nop 0
	global_load_lds_dwordx4 v[150:151], off
	v_lshl_add_u64 v[150:151], v[180:181], 0, s[24:25]
	s_mov_b32 m0, s68
	s_nop 0
	global_load_lds_dwordx4 v[150:151], off
	s_waitcnt vmcnt(8)
	s_waitcnt lgkmcnt(0)
	s_barrier
	s_waitcnt lgkmcnt(0)
	v_mfma_f32_16x16x32_bf16 v[62:65], v[142:145], v[206:209], v[62:65]
	v_mfma_f32_16x16x32_bf16 v[58:61], v[156:159], v[206:209], v[58:61]
	v_mfma_f32_16x16x32_bf16 v[46:49], v[142:145], v[226:229], v[46:49]
	v_mfma_f32_16x16x32_bf16 v[42:45], v[156:159], v[226:229], v[42:45]
	v_mfma_f32_16x16x32_bf16 v[30:33], v[142:145], v[234:237], v[30:33]
	v_mfma_f32_16x16x32_bf16 v[26:29], v[156:159], v[234:237], v[26:29]
	v_mfma_f32_16x16x32_bf16 v[14:17], v[142:145], v[242:245], v[14:17]
	v_mfma_f32_16x16x32_bf16 v[10:13], v[156:159], v[242:245], v[10:13]
	v_mfma_f32_16x16x32_bf16 v[62:65], v[146:149], v[222:225], v[62:65]
	v_mfma_f32_16x16x32_bf16 v[58:61], v[160:163], v[222:225], v[58:61]
	v_mfma_f32_16x16x32_bf16 v[46:49], v[146:149], v[230:233], v[46:49]
	v_mfma_f32_16x16x32_bf16 v[42:45], v[160:163], v[230:233], v[42:45]
	v_mfma_f32_16x16x32_bf16 v[30:33], v[146:149], v[238:241], v[30:33]
	v_mfma_f32_16x16x32_bf16 v[26:29], v[160:163], v[238:241], v[26:29]
	v_mfma_f32_16x16x32_bf16 v[14:17], v[146:149], v[246:249], v[14:17]
	v_mfma_f32_16x16x32_bf16 v[10:13], v[160:163], v[246:249], v[10:13]
	v_mfma_f32_16x16x32_bf16 v[54:57], v[164:167], v[206:209], v[54:57]
	v_mfma_f32_16x16x32_bf16 v[50:53], v[172:175], v[206:209], v[50:53]
	v_mfma_f32_16x16x32_bf16 v[38:41], v[164:167], v[226:229], v[38:41]
	v_mfma_f32_16x16x32_bf16 v[34:37], v[172:175], v[226:229], v[34:37]
	v_mfma_f32_16x16x32_bf16 v[22:25], v[164:167], v[234:237], v[22:25]
	v_mfma_f32_16x16x32_bf16 v[18:21], v[172:175], v[234:237], v[18:21]
	v_mfma_f32_16x16x32_bf16 v[6:9], v[164:167], v[242:245], v[6:9]
	v_mfma_f32_16x16x32_bf16 v[2:5], v[172:175], v[242:245], v[2:5]
	v_mfma_f32_16x16x32_bf16 v[54:57], v[168:171], v[222:225], v[54:57]
	v_mfma_f32_16x16x32_bf16 v[50:53], v[202:205], v[222:225], v[50:53]
	v_mfma_f32_16x16x32_bf16 v[38:41], v[168:171], v[230:233], v[38:41]
	v_mfma_f32_16x16x32_bf16 v[34:37], v[202:205], v[230:233], v[34:37]
	v_mfma_f32_16x16x32_bf16 v[22:25], v[168:171], v[238:241], v[22:25]
	v_mfma_f32_16x16x32_bf16 v[18:21], v[202:205], v[238:241], v[18:21]
	v_mfma_f32_16x16x32_bf16 v[6:9], v[168:171], v[246:249], v[6:9]
	v_mfma_f32_16x16x32_bf16 v[2:5], v[202:205], v[246:249], v[2:5]
	s_barrier
	s_add_i32 s88, s88, 2
	s_add_u32 s4, s4, 0x100
	s_addc_u32 s5, s5, 0
	s_add_u32 s57, s57, 0x100
	s_addc_u32 s87, s87, 0
	s_cmp_gt_u32 s88, 13
	s_cbranch_scc0 .LBB0_103
	s_and_b64 vcc, exec, s[46:47]
	s_cbranch_vccz .LBB0_106
	s_barrier

.LBB0_428:
	s_add_u32 s12, s2, 0x8000000
	s_addc_u32 s13, s3, 0
	s_lshl_b32 s2, s5, 5
	s_and_b32 s85, s2, 0x60
	s_add_i32 m0, s71, 0x18000
	v_lshl_add_u64 v[8:9], v[8:9], 0, s[24:25]
	s_lshl_b32 s17, s4, 13
	s_lshl_b32 s5, s85, 7
	s_waitcnt vmcnt(2)
	s_barrier
	global_load_lds_dwordx4 v[8:9], off
	v_lshl_add_u64 v[6:7], v[6:7], 0, s[24:25]
	s_add_i32 m0, s71, 0x1a000
	s_add_i32 s86, s71, 0x8000
	s_add_i32 s88, s71, 0xa000
	global_load_lds_dwordx4 v[6:7], off
	v_lshl_add_u64 v[2:3], v[2:3], 0, s[24:25]
	s_mov_b32 m0, s86
	s_add_u32 s2, s50, 0x10080
	global_load_lds_dwordx4 v[2:3], off
	v_lshl_add_u64 v[2:3], v[4:5], 0, s[24:25]
	s_mov_b32 m0, s88
	s_addc_u32 s3, s51, 0
	global_load_lds_dwordx4 v[2:3], off
	s_add_i32 m0, s71, 0x1c000
	global_load_lds_dwordx4 v130, s[2:3]
	v_lshl_add_u64 v[2:3], s[2:3], 0, v[132:133]
	s_add_i32 m0, s71, 0x1e000
	v_lshlrev_b32_e32 v4, 2, v10
	global_load_lds_dwordx4 v[2:3], off
	v_bfe_u32 v2, v10, 4, 2
	v_and_b32_e32 v3, 15, v10
	v_lshlrev_b32_e32 v0, 4, v2
	v_lshl_or_b32 v135, s4, 6, v3
	v_lshl_or_b32 v3, v3, 6, v0
	v_and_b32_e32 v4, 32, v4
	s_waitcnt vmcnt(6)
	s_cmpk_lt_u32 s16, 0x100
	v_bitop3_b32 v5, v3, s17, v4 bitop3:0xde
	s_cselect_b64 s[16:17], -1, 0
	s_getpc_b64 s[2:3]
	s_add_u32 s2, s2, _ZN3pg88ROPE_INVE@rel32@lo+4
	s_addc_u32 s3, s3, _ZN3pg88ROPE_INVE@rel32@hi+12
	v_bitop3_b32 v142, v3, s5, v4 bitop3:0xde
	v_lshlrev_b32_e32 v134, 2, v2
	v_lshl_add_u64 v[136:137], s[2:3], 0, v[0:1]
	s_ashr_i32 s92, s22, 31
	s_ashr_i32 s93, s41, 31
	s_mov_b32 s94, 0
	v_add_u32_e32 v143, 0, v5
	s_barrier
	s_branch .LBB0_431

.LBB0_436:
	s_add_u32 s37, s52, s56
	s_addc_u32 s57, s53, 0
	s_add_u32 s58, s37, 0x100
	s_addc_u32 s59, s57, 0
	s_and_b64 s[20:21], s[54:55], exec
	s_cselect_b32 s59, s45, s59
	s_cselect_b32 s58, s44, s58
	s_add_u32 s20, s50, s56
	s_addc_u32 s21, s51, 0
	s_add_u32 s56, s20, 0x100
	s_addc_u32 s60, s21, 0
	s_add_i32 s78, 0, 0x10000
	s_and_b64 s[20:21], s[54:55], exec
	s_cselect_b32 s61, s19, s60
	s_cselect_b32 s60, s49, s56
	s_add_i32 s20, 0, 0x14000
	s_add_u32 s64, s37, 0x10080
	s_addc_u32 s65, s57, 0
	s_add_i32 s37, s78, s70
	s_add_i32 m0, s71, 0xc000
	s_add_i32 s21, s71, 0xe000
	s_add_i32 s77, s37, 0x2000
	v_add_u32_e32 v0, s78, v142
	s_add_u32 s62, s60, 0x10000
	ds_read_b128 v[138:141], v0
	ds_read_b128 v[144:147], v0 offset:1024
	ds_read_b128 v[148:151], v0 offset:2048
	ds_read_b128 v[152:155], v0 offset:3072
	v_add_u32_e32 v0, s20, v142
	s_addc_u32 s63, s61, 0
	s_add_i32 s82, s20, s70
	ds_read_b128 v[156:159], v0
	ds_read_b128 v[160:163], v0 offset:1024
	ds_read_b128 v[164:167], v0 offset:2048
	ds_read_b128 v[168:171], v0 offset:3072
	s_add_i32 s83, s82, 0x2000
	s_add_i32 vcc_hi, 0, 0x18000
	s_add_i32 vcc_lo, 0, 0x1c000
	s_add_u32 s56, s58, 0x10000
	s_addc_u32 s57, s59, 0
	s_add_i32 s97, vcc_hi, s70
	s_add_i32 s96, s97, 0x2000
	s_add_u32 s54, s60, 0x10080
	s_addc_u32 s55, s61, 0
	s_add_i32 s78, vcc_lo, s70
	s_add_i32 s20, s78, 0x2000
	ds_read_b128 v[172:175], v143
	ds_read_b128 v[202:205], v143 offset:1024
	ds_read_b128 v[206:209], v143 offset:2048
	ds_read_b128 v[222:225], v143 offset:3072
	ds_read_b128 v[226:229], v143 offset:4096
	ds_read_b128 v[230:233], v143 offset:5120
	ds_read_b128 v[234:237], v143 offset:6144
	ds_read_b128 v[238:241], v143 offset:7168
	global_load_lds_dwordx4 v130, s[64:65]
	s_mov_b32 m0, s21
	s_nop 0
	global_load_lds_dwordx4 v132, s[64:65]
	s_waitcnt vmcnt(8)
	s_waitcnt lgkmcnt(0)
	s_barrier
	s_waitcnt lgkmcnt(0)
	v_mfma_f32_16x16x32_bf16 v[126:129], v[138:141], v[172:175], v[126:129]
	v_mfma_f32_16x16x32_bf16 v[122:125], v[148:151], v[172:175], v[122:125]
	v_mfma_f32_16x16x32_bf16 v[118:121], v[138:141], v[206:209], v[118:121]
	v_mfma_f32_16x16x32_bf16 v[114:117], v[148:151], v[206:209], v[114:117]
	v_mfma_f32_16x16x32_bf16 v[110:113], v[138:141], v[226:229], v[110:113]
	v_mfma_f32_16x16x32_bf16 v[106:109], v[148:151], v[226:229], v[106:109]
	v_mfma_f32_16x16x32_bf16 v[102:105], v[138:141], v[234:237], v[102:105]
	v_mfma_f32_16x16x32_bf16 v[98:101], v[148:151], v[234:237], v[98:101]
	v_mfma_f32_16x16x32_bf16 v[126:129], v[144:147], v[202:205], v[126:129]
	v_mfma_f32_16x16x32_bf16 v[122:125], v[152:155], v[202:205], v[122:125]
	v_mfma_f32_16x16x32_bf16 v[118:121], v[144:147], v[222:225], v[118:121]
	v_mfma_f32_16x16x32_bf16 v[114:117], v[152:155], v[222:225], v[114:117]
	v_mfma_f32_16x16x32_bf16 v[110:113], v[144:147], v[230:233], v[110:113]
	v_mfma_f32_16x16x32_bf16 v[106:109], v[152:155], v[230:233], v[106:109]
	v_mfma_f32_16x16x32_bf16 v[102:105], v[144:147], v[238:241], v[102:105]
	v_mfma_f32_16x16x32_bf16 v[98:101], v[152:155], v[238:241], v[98:101]
	v_mfma_f32_16x16x32_bf16 v[62:65], v[156:159], v[172:175], v[62:65]
	v_mfma_f32_16x16x32_bf16 v[58:61], v[164:167], v[172:175], v[58:61]
	v_mfma_f32_16x16x32_bf16 v[54:57], v[156:159], v[206:209], v[54:57]
	v_mfma_f32_16x16x32_bf16 v[50:53], v[164:167], v[206:209], v[50:53]
	v_mfma_f32_16x16x32_bf16 v[46:49], v[156:159], v[226:229], v[46:49]
	v_mfma_f32_16x16x32_bf16 v[42:45], v[164:167], v[226:229], v[42:45]
	v_mfma_f32_16x16x32_bf16 v[38:41], v[156:159], v[234:237], v[38:41]
	v_mfma_f32_16x16x32_bf16 v[34:37], v[164:167], v[234:237], v[34:37]
	v_mfma_f32_16x16x32_bf16 v[62:65], v[160:163], v[202:205], v[62:65]
	v_mfma_f32_16x16x32_bf16 v[58:61], v[168:171], v[202:205], v[58:61]
	v_mfma_f32_16x16x32_bf16 v[54:57], v[160:163], v[222:225], v[54:57]
	v_mfma_f32_16x16x32_bf16 v[50:53], v[168:171], v[222:225], v[50:53]
	v_mfma_f32_16x16x32_bf16 v[46:49], v[160:163], v[230:233], v[46:49]
	v_mfma_f32_16x16x32_bf16 v[42:45], v[168:171], v[230:233], v[42:45]
	v_mfma_f32_16x16x32_bf16 v[38:41], v[160:163], v[238:241], v[38:41]
	v_mfma_f32_16x16x32_bf16 v[34:37], v[168:171], v[238:241], v[34:37]
	s_barrier
	s_mov_b32 m0, s37
	v_lshl_add_u64 v[176:177], s[60:61], 0, v[130:131]
	ds_read_b128 v[172:175], v143 offset:16384
	ds_read_b128 v[202:205], v143 offset:17408
	ds_read_b128 v[206:209], v143 offset:18432
	ds_read_b128 v[222:225], v143 offset:19456
	ds_read_b128 v[226:229], v143 offset:20480
	ds_read_b128 v[230:233], v143 offset:21504
	ds_read_b128 v[234:237], v143 offset:22528
	ds_read_b128 v[238:241], v143 offset:23552
	global_load_lds_dwordx4 v[176:177], off
	v_lshl_add_u64 v[178:179], s[60:61], 0, v[132:133]
	s_mov_b32 m0, s77
	global_load_lds_dwordx4 v[178:179], off
	s_mov_b32 m0, s82
	v_lshl_add_u64 v[182:183], s[58:59], 0, v[132:133]
	global_load_lds_dwordx4 v130, s[62:63]
	s_mov_b32 m0, s83
	s_nop 0
	global_load_lds_dwordx4 v132, s[62:63]
	v_lshl_add_u64 v[180:181], s[58:59], 0, v[130:131]
	s_mov_b32 m0, s71
	s_nop 0
	global_load_lds_dwordx4 v[180:181], off
	s_mov_b32 m0, s72
	s_nop 0
	global_load_lds_dwordx4 v[182:183], off
	s_waitcnt vmcnt(8)
	s_waitcnt lgkmcnt(0)
	s_barrier
	s_waitcnt lgkmcnt(0)
	v_mfma_f32_16x16x32_bf16 v[90:93], v[138:141], v[172:175], v[90:93]
	v_mfma_f32_16x16x32_bf16 v[94:97], v[148:151], v[172:175], v[94:97]
	v_mfma_f32_16x16x32_bf16 v[86:89], v[138:141], v[206:209], v[86:89]
	v_mfma_f32_16x16x32_bf16 v[82:85], v[148:151], v[206:209], v[82:85]
	v_mfma_f32_16x16x32_bf16 v[78:81], v[138:141], v[226:229], v[78:81]
	v_mfma_f32_16x16x32_bf16 v[74:77], v[148:151], v[226:229], v[74:77]
	v_mfma_f32_16x16x32_bf16 v[70:73], v[138:141], v[234:237], v[70:73]
	v_mfma_f32_16x16x32_bf16 v[66:69], v[148:151], v[234:237], v[66:69]
	v_mfma_f32_16x16x32_bf16 v[90:93], v[144:147], v[202:205], v[90:93]
	v_mfma_f32_16x16x32_bf16 v[94:97], v[152:155], v[202:205], v[94:97]
	v_mfma_f32_16x16x32_bf16 v[86:89], v[144:147], v[222:225], v[86:89]
	v_mfma_f32_16x16x32_bf16 v[82:85], v[152:155], v[222:225], v[82:85]
	v_mfma_f32_16x16x32_bf16 v[78:81], v[144:147], v[230:233], v[78:81]
	v_mfma_f32_16x16x32_bf16 v[74:77], v[152:155], v[230:233], v[74:77]
	v_mfma_f32_16x16x32_bf16 v[70:73], v[144:147], v[238:241], v[70:73]
	v_mfma_f32_16x16x32_bf16 v[66:69], v[152:155], v[238:241], v[66:69]
	v_mfma_f32_16x16x32_bf16 v[30:33], v[156:159], v[172:175], v[30:33]
	v_mfma_f32_16x16x32_bf16 v[26:29], v[164:167], v[172:175], v[26:29]
	v_mfma_f32_16x16x32_bf16 v[22:25], v[156:159], v[206:209], v[22:25]
	v_mfma_f32_16x16x32_bf16 v[18:21], v[164:167], v[206:209], v[18:21]
	v_mfma_f32_16x16x32_bf16 v[14:17], v[156:159], v[226:229], v[14:17]
	v_mfma_f32_16x16x32_bf16 v[10:13], v[164:167], v[226:229], v[10:13]
	v_mfma_f32_16x16x32_bf16 v[6:9], v[156:159], v[234:237], v[6:9]
	v_mfma_f32_16x16x32_bf16 v[2:5], v[164:167], v[234:237], v[2:5]
	v_mfma_f32_16x16x32_bf16 v[30:33], v[160:163], v[202:205], v[30:33]
	v_mfma_f32_16x16x32_bf16 v[26:29], v[168:171], v[202:205], v[26:29]
	v_mfma_f32_16x16x32_bf16 v[22:25], v[160:163], v[222:225], v[22:25]
	v_mfma_f32_16x16x32_bf16 v[18:21], v[168:171], v[222:225], v[18:21]
	v_mfma_f32_16x16x32_bf16 v[14:17], v[160:163], v[230:233], v[14:17]
	v_mfma_f32_16x16x32_bf16 v[10:13], v[168:171], v[230:233], v[10:13]
	v_mfma_f32_16x16x32_bf16 v[6:9], v[160:163], v[238:241], v[6:9]
	v_mfma_f32_16x16x32_bf16 v[2:5], v[168:171], v[238:241], v[2:5]
	s_barrier
	v_add_u32_e32 v0, vcc_hi, v142
	ds_read_b128 v[138:141], v0
	ds_read_b128 v[144:147], v0 offset:1024
	ds_read_b128 v[148:151], v0 offset:2048
	ds_read_b128 v[152:155], v0 offset:3072
	v_add_u32_e32 v0, vcc_lo, v142
	ds_read_b128 v[156:159], v0
	ds_read_b128 v[160:163], v0 offset:1024
	ds_read_b128 v[164:167], v0 offset:2048
	ds_read_b128 v[168:171], v0 offset:3072
	s_mov_b32 m0, s73
	ds_read_b128 v[172:175], v143 offset:32768
	ds_read_b128 v[202:205], v143 offset:33792
	ds_read_b128 v[206:209], v143 offset:34816
	ds_read_b128 v[222:225], v143 offset:35840
	ds_read_b128 v[226:229], v143 offset:36864
	ds_read_b128 v[230:233], v143 offset:37888
	ds_read_b128 v[234:237], v143 offset:38912
	ds_read_b128 v[238:241], v143 offset:39936
	global_load_lds_dwordx4 v130, s[56:57]
	v_lshl_add_u64 v[184:185], s[56:57], 0, v[132:133]
	s_mov_b32 m0, s81
	s_nop 0
	global_load_lds_dwordx4 v[184:185], off
	s_waitcnt vmcnt(8)
	s_waitcnt lgkmcnt(0)
	s_barrier
	s_waitcnt lgkmcnt(0)
	v_mfma_f32_16x16x32_bf16 v[126:129], v[138:141], v[172:175], v[126:129]
	v_mfma_f32_16x16x32_bf16 v[122:125], v[148:151], v[172:175], v[122:125]
	v_mfma_f32_16x16x32_bf16 v[118:121], v[138:141], v[206:209], v[118:121]
	v_mfma_f32_16x16x32_bf16 v[114:117], v[148:151], v[206:209], v[114:117]
	v_mfma_f32_16x16x32_bf16 v[110:113], v[138:141], v[226:229], v[110:113]
	v_mfma_f32_16x16x32_bf16 v[106:109], v[148:151], v[226:229], v[106:109]
	v_mfma_f32_16x16x32_bf16 v[102:105], v[138:141], v[234:237], v[102:105]
	v_mfma_f32_16x16x32_bf16 v[98:101], v[148:151], v[234:237], v[98:101]
	v_mfma_f32_16x16x32_bf16 v[126:129], v[144:147], v[202:205], v[126:129]
	v_mfma_f32_16x16x32_bf16 v[122:125], v[152:155], v[202:205], v[122:125]
	v_mfma_f32_16x16x32_bf16 v[118:121], v[144:147], v[222:225], v[118:121]
	v_mfma_f32_16x16x32_bf16 v[114:117], v[152:155], v[222:225], v[114:117]
	v_mfma_f32_16x16x32_bf16 v[110:113], v[144:147], v[230:233], v[110:113]
	v_mfma_f32_16x16x32_bf16 v[106:109], v[152:155], v[230:233], v[106:109]
	v_mfma_f32_16x16x32_bf16 v[102:105], v[144:147], v[238:241], v[102:105]
	v_mfma_f32_16x16x32_bf16 v[98:101], v[152:155], v[238:241], v[98:101]
	v_mfma_f32_16x16x32_bf16 v[62:65], v[156:159], v[172:175], v[62:65]
	v_mfma_f32_16x16x32_bf16 v[58:61], v[164:167], v[172:175], v[58:61]
	v_mfma_f32_16x16x32_bf16 v[54:57], v[156:159], v[206:209], v[54:57]
	v_mfma_f32_16x16x32_bf16 v[50:53], v[164:167], v[206:209], v[50:53]
	v_mfma_f32_16x16x32_bf16 v[46:49], v[156:159], v[226:229], v[46:49]
	v_mfma_f32_16x16x32_bf16 v[42:45], v[164:167], v[226:229], v[42:45]
	v_mfma_f32_16x16x32_bf16 v[38:41], v[156:159], v[234:237], v[38:41]
	v_mfma_f32_16x16x32_bf16 v[34:37], v[164:167], v[234:237], v[34:37]
	v_mfma_f32_16x16x32_bf16 v[62:65], v[160:163], v[202:205], v[62:65]
	v_mfma_f32_16x16x32_bf16 v[58:61], v[168:171], v[202:205], v[58:61]
	v_mfma_f32_16x16x32_bf16 v[54:57], v[160:163], v[222:225], v[54:57]
	v_mfma_f32_16x16x32_bf16 v[50:53], v[168:171], v[222:225], v[50:53]
	v_mfma_f32_16x16x32_bf16 v[46:49], v[160:163], v[230:233], v[46:49]
	v_mfma_f32_16x16x32_bf16 v[42:45], v[168:171], v[230:233], v[42:45]
	v_mfma_f32_16x16x32_bf16 v[38:41], v[160:163], v[238:241], v[38:41]
	v_mfma_f32_16x16x32_bf16 v[34:37], v[168:171], v[238:241], v[34:37]
	s_barrier
	s_mov_b32 m0, s97
	v_lshl_add_u64 v[176:177], v[176:177], 0, s[24:25]
	ds_read_b128 v[172:175], v143 offset:49152
	ds_read_b128 v[202:205], v143 offset:50176
	ds_read_b128 v[206:209], v143 offset:51200
	ds_read_b128 v[222:225], v143 offset:52224
	ds_read_b128 v[226:229], v143 offset:53248
	ds_read_b128 v[230:233], v143 offset:54272
	ds_read_b128 v[234:237], v143 offset:55296
	ds_read_b128 v[238:241], v143 offset:56320
	global_load_lds_dwordx4 v[176:177], off
	v_lshl_add_u64 v[176:177], v[178:179], 0, s[24:25]
	s_mov_b32 m0, s96
	s_nop 0
	global_load_lds_dwordx4 v[176:177], off
	s_mov_b32 m0, s78
	s_nop 0
	global_load_lds_dwordx4 v130, s[54:55]
	s_mov_b32 m0, s20
	s_nop 0
	global_load_lds_dwordx4 v132, s[54:55]
	v_lshl_add_u64 v[176:177], v[180:181], 0, s[24:25]
	s_mov_b32 m0, s86
	s_nop 0
	global_load_lds_dwordx4 v[176:177], off
	v_lshl_add_u64 v[176:177], v[182:183], 0, s[24:25]
	s_mov_b32 m0, s88
	s_nop 0
	global_load_lds_dwordx4 v[176:177], off
	s_waitcnt vmcnt(8)
	s_waitcnt lgkmcnt(0)
	s_barrier
	s_waitcnt lgkmcnt(0)
	v_mfma_f32_16x16x32_bf16 v[90:93], v[138:141], v[172:175], v[90:93]
	v_mfma_f32_16x16x32_bf16 v[94:97], v[148:151], v[172:175], v[94:97]
	v_mfma_f32_16x16x32_bf16 v[86:89], v[138:141], v[206:209], v[86:89]
	v_mfma_f32_16x16x32_bf16 v[82:85], v[148:151], v[206:209], v[82:85]
	v_mfma_f32_16x16x32_bf16 v[78:81], v[138:141], v[226:229], v[78:81]
	v_mfma_f32_16x16x32_bf16 v[74:77], v[148:151], v[226:229], v[74:77]
	v_mfma_f32_16x16x32_bf16 v[70:73], v[138:141], v[234:237], v[70:73]
	v_mfma_f32_16x16x32_bf16 v[66:69], v[148:151], v[234:237], v[66:69]
	v_mfma_f32_16x16x32_bf16 v[90:93], v[144:147], v[202:205], v[90:93]
	v_mfma_f32_16x16x32_bf16 v[94:97], v[152:155], v[202:205], v[94:97]
	v_mfma_f32_16x16x32_bf16 v[86:89], v[144:147], v[222:225], v[86:89]
	v_mfma_f32_16x16x32_bf16 v[82:85], v[152:155], v[222:225], v[82:85]
	v_mfma_f32_16x16x32_bf16 v[78:81], v[144:147], v[230:233], v[78:81]
	v_mfma_f32_16x16x32_bf16 v[74:77], v[152:155], v[230:233], v[74:77]
	v_mfma_f32_16x16x32_bf16 v[70:73], v[144:147], v[238:241], v[70:73]
	v_mfma_f32_16x16x32_bf16 v[66:69], v[152:155], v[238:241], v[66:69]
	v_mfma_f32_16x16x32_bf16 v[30:33], v[156:159], v[172:175], v[30:33]
	v_mfma_f32_16x16x32_bf16 v[26:29], v[164:167], v[172:175], v[26:29]
	v_mfma_f32_16x16x32_bf16 v[22:25], v[156:159], v[206:209], v[22:25]
	v_mfma_f32_16x16x32_bf16 v[18:21], v[164:167], v[206:209], v[18:21]
	v_mfma_f32_16x16x32_bf16 v[14:17], v[156:159], v[226:229], v[14:17]
	v_mfma_f32_16x16x32_bf16 v[10:13], v[164:167], v[226:229], v[10:13]
	v_mfma_f32_16x16x32_bf16 v[6:9], v[156:159], v[234:237], v[6:9]
	v_mfma_f32_16x16x32_bf16 v[2:5], v[164:167], v[234:237], v[2:5]
	v_mfma_f32_16x16x32_bf16 v[30:33], v[160:163], v[202:205], v[30:33]
	v_mfma_f32_16x16x32_bf16 v[26:29], v[168:171], v[202:205], v[26:29]
	v_mfma_f32_16x16x32_bf16 v[22:25], v[160:163], v[222:225], v[22:25]
	v_mfma_f32_16x16x32_bf16 v[18:21], v[168:171], v[222:225], v[18:21]
	v_mfma_f32_16x16x32_bf16 v[14:17], v[160:163], v[230:233], v[14:17]
	v_mfma_f32_16x16x32_bf16 v[10:13], v[168:171], v[230:233], v[10:13]
	v_mfma_f32_16x16x32_bf16 v[6:9], v[160:163], v[238:241], v[6:9]
	v_mfma_f32_16x16x32_bf16 v[2:5], v[168:171], v[238:241], v[2:5]
	s_barrier
	s_movk_i32 s56, 0x100
	s_andn2_b64 vcc, exec, s[4:5]
	s_mov_b64 s[54:55], -1
	s_mov_b64 s[4:5], 0
	s_cbranch_vccz .LBB0_436
	s_and_b64 vcc, exec, s[16:17]
	s_cbranch_vccz .LBB0_439
	s_barrier

.LBB0_484:
	s_add_u32 s6, s6, 0x28000000
	s_addc_u32 s7, s7, 0
	s_lshl_b32 s2, s2, 5
	s_and_b32 s2, s2, 0x60
	s_add_i32 m0, s58, 0x18000
	v_lshl_add_u64 v[8:9], v[8:9], 0, s[24:25]
	s_lshl_b32 s13, s3, 13
	s_lshl_b32 s17, s2, 7
	s_waitcnt vmcnt(2)
	s_barrier
	global_load_lds_dwordx4 v[8:9], off
	v_lshl_add_u64 v[6:7], v[6:7], 0, s[24:25]
	s_add_i32 m0, s58, 0x1a000
	s_add_i32 s62, s58, 0x8000
	s_add_i32 s63, s58, 0xa000
	global_load_lds_dwordx4 v[6:7], off
	v_lshl_add_u64 v[2:3], v[2:3], 0, s[24:25]
	s_mov_b32 m0, s62
	s_add_u32 s4, s52, 0x8080
	global_load_lds_dwordx4 v[2:3], off
	v_lshl_add_u64 v[2:3], v[4:5], 0, s[24:25]
	s_mov_b32 m0, s63
	s_addc_u32 s5, s53, 0
	global_load_lds_dwordx4 v[2:3], off
	s_add_i32 m0, s58, 0x1c000
	global_load_lds_dwordx4 v0, s[4:5]
	v_lshl_add_u64 v[2:3], s[4:5], 0, v[134:135]
	s_add_i32 m0, s58, 0x1e000
	s_cmpk_lt_u32 s12, 0x100
	global_load_lds_dwordx4 v[2:3], off
	v_lshrrev_b32_e32 v3, 1, v10
	v_and_b32_e32 v3, 24, v3
	v_and_b32_e32 v2, 15, v10
	v_lshlrev_b32_e32 v4, 1, v3
	v_lshl_or_b32 v140, s3, 6, v2
	v_lshl_or_b32 v2, v2, 6, v4
	v_lshlrev_b32_e32 v4, 2, v10
	v_and_b32_e32 v4, 32, v4
	v_bitop3_b32 v5, v2, s13, v4 bitop3:0xde
	s_waitcnt vmcnt(6)
	s_cselect_b64 s[12:13], -1, 0
	s_ashr_i32 s64, s22, 31
	s_ashr_i32 s3, s16, 31
	s_add_u32 s16, s22, s16
	v_bitop3_b32 v141, v2, s17, v4 bitop3:0xde
	v_or_b32_e32 v142, s2, v3
	s_addc_u32 s17, s64, s3
	v_add_u32_e32 v143, 0, v5
	s_barrier
	s_branch .LBB0_487

.LBB0_495:
	s_ashr_i32 s19, s18, 31
	s_lshl_b64 s[20:21], s[18:19], 16
	s_add_u32 s46, s55, s20
	s_addc_u32 s47, s56, s21
	s_and_b64 s[4:5], s[4:5], exec
	s_cselect_b32 s5, s47, s53
	s_cselect_b32 s4, s46, s52
	s_add_i32 s19, 0, 0x10000
	s_add_i32 s37, 0, 0x14000
	v_add_u32_e32 v14, s19, v141
	v_add_u32_e32 v30, s37, v141
	ds_read_b128 v[2:5], v14
	ds_read_b128 v[6:9], v14 offset:1024
	ds_read_b128 v[10:13], v14 offset:2048
	ds_read_b128 v[14:17], v14 offset:3072
	ds_read_b128 v[18:21], v30
	ds_read_b128 v[22:25], v30 offset:1024
	ds_read_b128 v[26:29], v30 offset:2048
	ds_read_b128 v[30:33], v30 offset:3072
	s_add_u32 s20, s50, 0x8080
	s_addc_u32 s21, s51, 0
	s_add_i32 m0, s58, 0xc000
	ds_read_b128 v[34:37], v143
	ds_read_b128 v[38:41], v143 offset:1024
	ds_read_b128 v[42:45], v143 offset:2048
	ds_read_b128 v[46:49], v143 offset:3072
	ds_read_b128 v[50:53], v143 offset:4096
	ds_read_b128 v[54:57], v143 offset:5120
	ds_read_b128 v[58:61], v143 offset:6144
	ds_read_b128 v[62:65], v143 offset:7168
	global_load_lds_dwordx4 v130, s[20:21]
	s_add_i32 m0, s58, 0xe000
	s_nop 0
	global_load_lds_dwordx4 v132, s[20:21]
	s_waitcnt vmcnt(8)
	s_waitcnt lgkmcnt(0)
	s_barrier
	s_waitcnt lgkmcnt(0)
	v_mfma_f32_16x16x32_bf16 v[90:93], v[2:5], v[58:61], 0
	v_mfma_f32_16x16x32_bf16 v[66:69], v[2:5], v[34:37], 0
	v_mfma_f32_16x16x32_bf16 v[70:73], v[10:13], v[34:37], 0
	v_mfma_f32_16x16x32_bf16 v[74:77], v[2:5], v[42:45], 0
	v_mfma_f32_16x16x32_bf16 v[78:81], v[10:13], v[42:45], 0
	v_mfma_f32_16x16x32_bf16 v[82:85], v[2:5], v[50:53], 0
	v_mfma_f32_16x16x32_bf16 v[86:89], v[10:13], v[50:53], 0
	v_mfma_f32_16x16x32_bf16 v[98:101], v[6:9], v[62:65], v[90:93]
	v_mfma_f32_16x16x32_bf16 v[90:93], v[10:13], v[58:61], 0
	v_mfma_f32_16x16x32_bf16 v[66:69], v[6:9], v[38:41], v[66:69]
	v_mfma_f32_16x16x32_bf16 v[70:73], v[14:17], v[38:41], v[70:73]
	v_mfma_f32_16x16x32_bf16 v[74:77], v[6:9], v[46:49], v[74:77]
	v_mfma_f32_16x16x32_bf16 v[78:81], v[14:17], v[46:49], v[78:81]
	v_mfma_f32_16x16x32_bf16 v[82:85], v[6:9], v[54:57], v[82:85]
	v_mfma_f32_16x16x32_bf16 v[86:89], v[14:17], v[54:57], v[86:89]
	v_mfma_f32_16x16x32_bf16 v[102:105], v[14:17], v[62:65], v[90:93]
	v_mfma_f32_16x16x32_bf16 v[90:93], v[18:21], v[34:37], 0
	v_mfma_f32_16x16x32_bf16 v[34:37], v[26:29], v[34:37], 0
	v_mfma_f32_16x16x32_bf16 v[114:117], v[22:25], v[38:41], v[90:93]
	v_mfma_f32_16x16x32_bf16 v[34:37], v[30:33], v[38:41], v[34:37]
	v_mfma_f32_16x16x32_bf16 v[38:41], v[18:21], v[42:45], 0
	v_mfma_f32_16x16x32_bf16 v[42:45], v[26:29], v[42:45], 0
	v_mfma_f32_16x16x32_bf16 v[38:41], v[22:25], v[46:49], v[38:41]
	v_mfma_f32_16x16x32_bf16 v[42:45], v[30:33], v[46:49], v[42:45]
	v_mfma_f32_16x16x32_bf16 v[46:49], v[18:21], v[50:53], 0
	v_mfma_f32_16x16x32_bf16 v[50:53], v[26:29], v[50:53], 0
	v_mfma_f32_16x16x32_bf16 v[46:49], v[22:25], v[54:57], v[46:49]
	v_mfma_f32_16x16x32_bf16 v[50:53], v[30:33], v[54:57], v[50:53]
	v_mfma_f32_16x16x32_bf16 v[54:57], v[18:21], v[58:61], 0
	v_mfma_f32_16x16x32_bf16 v[58:61], v[26:29], v[58:61], 0
	v_mfma_f32_16x16x32_bf16 v[54:57], v[22:25], v[62:65], v[54:57]
	v_mfma_f32_16x16x32_bf16 v[62:65], v[30:33], v[62:65], v[58:61]
	s_barrier
	s_add_i32 s19, s19, s57
	v_lshl_add_u64 v[184:185], s[4:5], 0, v[0:1]
	s_mov_b32 m0, s19
	s_nop 0
	ds_read_b128 v[58:61], v143 offset:16384
	ds_read_b128 v[90:93], v143 offset:17408
	ds_read_b128 v[94:97], v143 offset:18432
	ds_read_b128 v[106:109], v143 offset:19456
	ds_read_b128 v[110:113], v143 offset:20480
	ds_read_b128 v[118:121], v143 offset:21504
	ds_read_b128 v[122:125], v143 offset:22528
	ds_read_b128 v[126:129], v143 offset:23552
	global_load_lds_dwordx4 v[184:185], off
	s_add_i32 m0, s19, 0x2000
	s_add_u32 s20, s4, 0x8000
	v_lshl_add_u64 v[190:191], s[4:5], 0, v[134:135]
	s_addc_u32 s21, s5, 0
	s_add_i32 s19, s37, s57
	global_load_lds_dwordx4 v[190:191], off
	s_mov_b32 m0, s19
	v_lshl_add_u64 v[192:193], s[44:45], 0, v[130:131]
	global_load_lds_dwordx4 v0, s[20:21]
	s_add_i32 m0, s19, 0x2000
	v_lshl_add_u64 v[194:195], s[44:45], 0, v[132:133]
	global_load_lds_dwordx4 v134, s[20:21]
	s_mov_b32 m0, s58
	s_nop 0
	global_load_lds_dwordx4 v[192:193], off
	s_mov_b32 m0, s59
	s_nop 0
	global_load_lds_dwordx4 v[194:195], off
	s_waitcnt vmcnt(8)
	s_waitcnt lgkmcnt(0)
	s_barrier
	s_waitcnt lgkmcnt(0)
	v_mfma_f32_16x16x32_bf16 v[136:139], v[2:5], v[58:61], 0
	v_mfma_f32_16x16x32_bf16 v[148:151], v[2:5], v[94:97], 0
	v_mfma_f32_16x16x32_bf16 v[156:159], v[2:5], v[110:113], 0
	v_mfma_f32_16x16x32_bf16 v[2:5], v[2:5], v[122:125], 0
	v_mfma_f32_16x16x32_bf16 v[136:139], v[6:9], v[90:93], v[136:139]
	v_mfma_f32_16x16x32_bf16 v[148:151], v[6:9], v[106:109], v[148:151]
	v_mfma_f32_16x16x32_bf16 v[156:159], v[6:9], v[118:121], v[156:159]
	v_mfma_f32_16x16x32_bf16 v[2:5], v[6:9], v[126:129], v[2:5]
	v_mfma_f32_16x16x32_bf16 v[6:9], v[10:13], v[122:125], 0
	v_mfma_f32_16x16x32_bf16 v[144:147], v[10:13], v[58:61], 0
	v_mfma_f32_16x16x32_bf16 v[152:155], v[10:13], v[94:97], 0
	v_mfma_f32_16x16x32_bf16 v[160:163], v[10:13], v[110:113], 0
	v_mfma_f32_16x16x32_bf16 v[6:9], v[14:17], v[126:129], v[6:9]
	v_mfma_f32_16x16x32_bf16 v[144:147], v[14:17], v[90:93], v[144:147]
	v_mfma_f32_16x16x32_bf16 v[152:155], v[14:17], v[106:109], v[152:155]
	v_mfma_f32_16x16x32_bf16 v[160:163], v[14:17], v[118:121], v[160:163]
	v_mfma_f32_16x16x32_bf16 v[10:13], v[18:21], v[58:61], 0
	v_mfma_f32_16x16x32_bf16 v[164:167], v[22:25], v[90:93], v[10:13]
	v_mfma_f32_16x16x32_bf16 v[10:13], v[26:29], v[58:61], 0
	v_mfma_f32_16x16x32_bf16 v[168:171], v[30:33], v[90:93], v[10:13]
	v_mfma_f32_16x16x32_bf16 v[10:13], v[18:21], v[94:97], 0
	v_mfma_f32_16x16x32_bf16 v[172:175], v[22:25], v[106:109], v[10:13]
	v_mfma_f32_16x16x32_bf16 v[10:13], v[26:29], v[94:97], 0
	v_mfma_f32_16x16x32_bf16 v[202:205], v[30:33], v[106:109], v[10:13]
	v_mfma_f32_16x16x32_bf16 v[10:13], v[18:21], v[110:113], 0
	v_mfma_f32_16x16x32_bf16 v[206:209], v[22:25], v[118:121], v[10:13]
	v_mfma_f32_16x16x32_bf16 v[10:13], v[26:29], v[110:113], 0
	v_mfma_f32_16x16x32_bf16 v[222:225], v[30:33], v[118:121], v[10:13]
	v_mfma_f32_16x16x32_bf16 v[10:13], v[18:21], v[122:125], 0
	v_mfma_f32_16x16x32_bf16 v[226:229], v[22:25], v[126:129], v[10:13]
	v_mfma_f32_16x16x32_bf16 v[10:13], v[26:29], v[122:125], 0
	v_mfma_f32_16x16x32_bf16 v[230:233], v[30:33], v[126:129], v[10:13]
	s_barrier
	s_add_i32 s19, 0, 0x18000
	s_add_i32 s37, 0, 0x1c000
	v_add_u32_e32 v22, s19, v141
	v_add_u32_e32 v26, s37, v141
	s_nop 0
	ds_read_b128 v[10:13], v22
	ds_read_b128 v[14:17], v22 offset:1024
	ds_read_b128 v[18:21], v22 offset:2048
	ds_read_b128 v[22:25], v22 offset:3072
	ds_read_b128 v[234:237], v26
	ds_read_b128 v[238:241], v26 offset:1024
	ds_read_b128 v[242:245], v26 offset:2048
	ds_read_b128 v[246:249], v26 offset:3072
	s_add_u32 s20, s44, 0x8000
	s_addc_u32 s21, s45, 0
	s_mov_b32 m0, s60
	ds_read_b128 v[26:29], v143 offset:32768
	ds_read_b128 v[30:33], v143 offset:33792
	ds_read_b128 v[58:61], v143 offset:34816
	ds_read_b128 v[250:253], v143 offset:35840
	ds_read_b128 v[176:179], v143 offset:36864
	ds_read_b128 v[186:189], v143 offset:37888
	ds_read_b128 v[198:201], v143 offset:38912
	ds_read_b128 v[218:221], v143 offset:39936
	global_load_lds_dwordx4 v130, s[20:21]
	s_mov_b32 m0, s61
	s_nop 0
	global_load_lds_dwordx4 v132, s[20:21]
	s_waitcnt vmcnt(8)
	s_waitcnt lgkmcnt(0)
	s_barrier
	s_waitcnt lgkmcnt(0)
	v_mfma_f32_16x16x32_bf16 v[66:69], v[10:13], v[26:29], v[66:69]
	v_mfma_f32_16x16x32_bf16 v[126:129], v[14:17], v[30:33], v[66:69]
	v_mfma_f32_16x16x32_bf16 v[66:69], v[18:21], v[26:29], v[70:73]
	v_mfma_f32_16x16x32_bf16 v[122:125], v[22:25], v[30:33], v[66:69]
	v_mfma_f32_16x16x32_bf16 v[66:69], v[10:13], v[58:61], v[74:77]
	v_mfma_f32_16x16x32_bf16 v[110:113], v[14:17], v[250:253], v[66:69]
	v_mfma_f32_16x16x32_bf16 v[66:69], v[18:21], v[58:61], v[78:81]
	v_mfma_f32_16x16x32_bf16 v[106:109], v[22:25], v[250:253], v[66:69]
	v_mfma_f32_16x16x32_bf16 v[66:69], v[10:13], v[176:179], v[82:85]
	v_mfma_f32_16x16x32_bf16 v[94:97], v[14:17], v[186:189], v[66:69]
	v_mfma_f32_16x16x32_bf16 v[66:69], v[18:21], v[176:179], v[86:89]
	v_mfma_f32_16x16x32_bf16 v[90:93], v[22:25], v[186:189], v[66:69]
	v_mfma_f32_16x16x32_bf16 v[66:69], v[10:13], v[198:201], v[98:101]
	v_mfma_f32_16x16x32_bf16 v[74:77], v[14:17], v[218:221], v[66:69]
	v_mfma_f32_16x16x32_bf16 v[66:69], v[18:21], v[198:201], v[102:105]
	v_mfma_f32_16x16x32_bf16 v[66:69], v[22:25], v[218:221], v[66:69]
	v_mfma_f32_16x16x32_bf16 v[70:73], v[234:237], v[26:29], v[114:117]
	v_mfma_f32_16x16x32_bf16 v[26:29], v[242:245], v[26:29], v[34:37]
	v_mfma_f32_16x16x32_bf16 v[114:117], v[246:249], v[30:33], v[26:29]
	v_mfma_f32_16x16x32_bf16 v[26:29], v[234:237], v[58:61], v[38:41]
	v_mfma_f32_16x16x32_bf16 v[102:105], v[238:241], v[250:253], v[26:29]
	v_mfma_f32_16x16x32_bf16 v[26:29], v[242:245], v[58:61], v[42:45]
	v_mfma_f32_16x16x32_bf16 v[98:101], v[246:249], v[250:253], v[26:29]
	v_mfma_f32_16x16x32_bf16 v[26:29], v[234:237], v[176:179], v[46:49]
	v_mfma_f32_16x16x32_bf16 v[86:89], v[238:241], v[186:189], v[26:29]
	v_mfma_f32_16x16x32_bf16 v[26:29], v[242:245], v[176:179], v[50:53]
	v_mfma_f32_16x16x32_bf16 v[82:85], v[246:249], v[186:189], v[26:29]
	v_mfma_f32_16x16x32_bf16 v[26:29], v[234:237], v[198:201], v[54:57]
	v_mfma_f32_16x16x32_bf16 v[58:61], v[238:241], v[218:221], v[26:29]
	v_mfma_f32_16x16x32_bf16 v[26:29], v[242:245], v[198:201], v[62:65]
	v_mfma_f32_16x16x32_bf16 v[118:121], v[238:241], v[30:33], v[70:73]
	v_mfma_f32_16x16x32_bf16 v[50:53], v[246:249], v[218:221], v[26:29]
	s_barrier
	s_add_i32 s19, s19, s57
	s_nop 2
	v_lshl_add_u64 v[26:27], v[184:185], 0, s[24:25]
	s_mov_b32 m0, s19
	ds_read_b128 v[34:37], v143 offset:49152
	ds_read_b128 v[38:41], v143 offset:50176
	ds_read_b128 v[176:179], v143 offset:51200
	ds_read_b128 v[186:189], v143 offset:52224
	ds_read_b128 v[198:201], v143 offset:53248
	ds_read_b128 v[218:221], v143 offset:54272
	ds_read_b128 v[250:253], v143 offset:55296
	ds_read_b128 v[180:183], v143 offset:56320
	global_load_lds_dwordx4 v[26:27], off
	s_add_i32 m0, s19, 0x2000
	s_add_u32 s4, s4, 0x8080
	v_lshl_add_u64 v[26:27], v[190:191], 0, s[24:25]
	s_addc_u32 s5, s5, 0
	s_add_i32 s19, s37, s57
	global_load_lds_dwordx4 v[26:27], off
	s_mov_b32 m0, s19
	s_nop 0
	global_load_lds_dwordx4 v0, s[4:5]
	s_add_i32 m0, s19, 0x2000
	s_nop 0
	global_load_lds_dwordx4 v134, s[4:5]
	v_lshl_add_u64 v[26:27], v[192:193], 0, s[24:25]
	s_mov_b32 m0, s62
	s_nop 0
	global_load_lds_dwordx4 v[26:27], off
	v_lshl_add_u64 v[26:27], v[194:195], 0, s[24:25]
	s_mov_b32 m0, s63
	s_nop 0
	global_load_lds_dwordx4 v[26:27], off
	s_waitcnt vmcnt(8)
	s_waitcnt lgkmcnt(0)
	s_barrier
	s_waitcnt lgkmcnt(0)
	v_mfma_f32_16x16x32_bf16 v[26:29], v[10:13], v[34:37], v[136:139]
	v_mfma_f32_16x16x32_bf16 v[78:81], v[14:17], v[38:41], v[26:29]
	v_mfma_f32_16x16x32_bf16 v[26:29], v[18:21], v[34:37], v[144:147]
	v_mfma_f32_16x16x32_bf16 v[70:73], v[22:25], v[38:41], v[26:29]
	v_mfma_f32_16x16x32_bf16 v[26:29], v[10:13], v[176:179], v[148:151]
	v_mfma_f32_16x16x32_bf16 v[46:49], v[14:17], v[186:189], v[26:29]
	v_mfma_f32_16x16x32_bf16 v[26:29], v[18:21], v[176:179], v[152:155]
	v_mfma_f32_16x16x32_bf16 v[42:45], v[22:25], v[186:189], v[26:29]
	v_mfma_f32_16x16x32_bf16 v[26:29], v[10:13], v[198:201], v[156:159]
	v_mfma_f32_16x16x32_bf16 v[2:5], v[10:13], v[250:253], v[2:5]
	v_mfma_f32_16x16x32_bf16 v[30:33], v[14:17], v[218:221], v[26:29]
	v_mfma_f32_16x16x32_bf16 v[26:29], v[18:21], v[198:201], v[160:163]
	v_mfma_f32_16x16x32_bf16 v[14:17], v[14:17], v[180:183], v[2:5]
	v_mfma_f32_16x16x32_bf16 v[2:5], v[18:21], v[250:253], v[6:9]
	v_mfma_f32_16x16x32_bf16 v[26:29], v[22:25], v[218:221], v[26:29]
	v_mfma_f32_16x16x32_bf16 v[10:13], v[22:25], v[180:183], v[2:5]
	v_mfma_f32_16x16x32_bf16 v[2:5], v[234:237], v[34:37], v[164:167]
	v_mfma_f32_16x16x32_bf16 v[62:65], v[238:241], v[38:41], v[2:5]
	v_mfma_f32_16x16x32_bf16 v[2:5], v[242:245], v[34:37], v[168:171]
	v_mfma_f32_16x16x32_bf16 v[54:57], v[246:249], v[38:41], v[2:5]
	v_mfma_f32_16x16x32_bf16 v[2:5], v[234:237], v[176:179], v[172:175]
	v_mfma_f32_16x16x32_bf16 v[38:41], v[238:241], v[186:189], v[2:5]
	v_mfma_f32_16x16x32_bf16 v[2:5], v[242:245], v[176:179], v[202:205]
	v_mfma_f32_16x16x32_bf16 v[34:37], v[246:249], v[186:189], v[2:5]
	v_mfma_f32_16x16x32_bf16 v[2:5], v[234:237], v[198:201], v[206:209]
	v_mfma_f32_16x16x32_bf16 v[22:25], v[238:241], v[218:221], v[2:5]
	v_mfma_f32_16x16x32_bf16 v[2:5], v[242:245], v[198:201], v[222:225]
	v_mfma_f32_16x16x32_bf16 v[18:21], v[246:249], v[218:221], v[2:5]
	v_mfma_f32_16x16x32_bf16 v[2:5], v[234:237], v[250:253], v[226:229]
	v_mfma_f32_16x16x32_bf16 v[6:9], v[238:241], v[180:183], v[2:5]
	v_mfma_f32_16x16x32_bf16 v[2:5], v[242:245], v[250:253], v[230:233]
	v_mfma_f32_16x16x32_bf16 v[2:5], v[246:249], v[180:183], v[2:5]
	s_barrier
	s_andn2_b64 vcc, exec, s[12:13]
	s_cbranch_vccnz .LBB0_497
	s_barrier

.LBB0_540:
	s_add_u32 s62, s8, 0x2c000000
	s_addc_u32 s63, s9, 0
	s_lshl_b32 s3, s3, 5
	s_and_b32 s65, s3, 0x60
	s_add_i32 m0, s58, 0x18000
	v_lshl_add_u64 v[8:9], v[8:9], 0, s[24:25]
	s_lshl_b32 s64, s17, 6
	s_lshl_b32 s17, s17, 13
	s_lshl_b32 s18, s65, 7
	s_waitcnt vmcnt(2)
	s_barrier
	global_load_lds_dwordx4 v[8:9], off
	v_lshl_add_u64 v[6:7], v[6:7], 0, s[24:25]
	s_add_i32 m0, s58, 0x1a000
	s_add_i32 s66, s58, 0x8000
	s_add_i32 s67, s58, 0xa000
	global_load_lds_dwordx4 v[6:7], off
	v_lshl_add_u64 v[2:3], v[2:3], 0, s[24:25]
	s_mov_b32 m0, s66
	s_add_u32 s8, s52, 0x8080
	global_load_lds_dwordx4 v[2:3], off
	v_lshl_add_u64 v[2:3], v[4:5], 0, s[24:25]
	s_mov_b32 m0, s67
	s_addc_u32 s9, s53, 0
	global_load_lds_dwordx4 v[2:3], off
	s_add_i32 m0, s58, 0x1c000
	global_load_lds_dwordx4 v0, s[8:9]
	v_lshl_add_u64 v[2:3], s[8:9], 0, v[134:135]
	s_add_i32 m0, s58, 0x1e000
	s_cmpk_lt_u32 s16, 0x100
	global_load_lds_dwordx4 v[2:3], off
	v_lshrrev_b32_e32 v2, 1, v10
	v_lshlrev_b32_e32 v3, 6, v10
	s_sext_i32_i16 s47, s2
	v_and_b32_e32 v2, 24, v2
	v_and_b32_e32 v3, 0x3c0, v3
	v_lshlrev_b32_e32 v5, 2, v10
	s_cselect_b64 s[8:9], -1, 0
	s_and_b32 s2, s3, 32
	v_lshl_or_b32 v4, v2, 1, v3
	v_and_b32_e32 v5, 32, v5
	s_waitcnt vmcnt(6)
	v_or3_b32 v2, v2, s2, v3
	s_ashr_i32 s68, s22, 31
	v_bitop3_b32 v7, v4, s17, v5 bitop3:0xde
	v_bitop3_b32 v136, v4, s18, v5 bitop3:0xde
	v_or_b32_e32 v4, 0x800, v2
	v_or_b32_e32 v6, 0xc00, v2
	s_add_u32 s16, s22, s4
	s_addc_u32 s17, s68, s5
	v_add_u32_e32 v137, 0, v7
	v_lshlrev_b32_e32 v138, 1, v2
	v_lshlrev_b32_e32 v139, 1, v4
	v_lshlrev_b32_e32 v140, 1, v6
	s_barrier
	s_branch .LBB0_543

.LBB0_551:
	s_ashr_i32 s19, s18, 31
	s_lshl_b64 s[20:21], s[18:19], 16
	s_add_u32 s48, s55, s20
	s_addc_u32 s49, s56, s21
	s_and_b64 s[4:5], s[4:5], exec
	s_cselect_b32 s5, s49, s53
	s_cselect_b32 s4, s48, s52
	s_add_i32 s19, 0, 0x10000
	s_add_i32 s37, 0, 0x14000
	v_add_u32_e32 v14, s19, v136
	v_add_u32_e32 v30, s37, v136
	ds_read_b128 v[2:5], v14
	ds_read_b128 v[6:9], v14 offset:1024
	ds_read_b128 v[10:13], v14 offset:2048
	ds_read_b128 v[14:17], v14 offset:3072
	ds_read_b128 v[18:21], v30
	ds_read_b128 v[22:25], v30 offset:1024
	ds_read_b128 v[26:29], v30 offset:2048
	ds_read_b128 v[30:33], v30 offset:3072
	s_add_u32 s20, s50, 0x8080
	s_addc_u32 s21, s51, 0
	s_add_i32 m0, s58, 0xc000
	ds_read_b128 v[34:37], v137
	ds_read_b128 v[38:41], v137 offset:1024
	ds_read_b128 v[42:45], v137 offset:2048
	ds_read_b128 v[46:49], v137 offset:3072
	ds_read_b128 v[50:53], v137 offset:4096
	ds_read_b128 v[54:57], v137 offset:5120
	ds_read_b128 v[58:61], v137 offset:6144
	ds_read_b128 v[62:65], v137 offset:7168
	global_load_lds_dwordx4 v130, s[20:21]
	s_add_i32 m0, s58, 0xe000
	s_nop 0
	global_load_lds_dwordx4 v132, s[20:21]
	s_waitcnt vmcnt(8)
	s_waitcnt lgkmcnt(0)
	s_barrier
	s_waitcnt lgkmcnt(0)
	v_mfma_f32_16x16x32_bf16 v[90:93], v[2:5], v[58:61], 0
	v_mfma_f32_16x16x32_bf16 v[66:69], v[2:5], v[34:37], 0
	v_mfma_f32_16x16x32_bf16 v[70:73], v[10:13], v[34:37], 0
	v_mfma_f32_16x16x32_bf16 v[74:77], v[2:5], v[42:45], 0
	v_mfma_f32_16x16x32_bf16 v[78:81], v[10:13], v[42:45], 0
	v_mfma_f32_16x16x32_bf16 v[82:85], v[2:5], v[50:53], 0
	v_mfma_f32_16x16x32_bf16 v[86:89], v[10:13], v[50:53], 0
	v_mfma_f32_16x16x32_bf16 v[94:97], v[6:9], v[62:65], v[90:93]
	v_mfma_f32_16x16x32_bf16 v[90:93], v[10:13], v[58:61], 0
	v_mfma_f32_16x16x32_bf16 v[66:69], v[6:9], v[38:41], v[66:69]
	v_mfma_f32_16x16x32_bf16 v[70:73], v[14:17], v[38:41], v[70:73]
	v_mfma_f32_16x16x32_bf16 v[74:77], v[6:9], v[46:49], v[74:77]
	v_mfma_f32_16x16x32_bf16 v[78:81], v[14:17], v[46:49], v[78:81]
	v_mfma_f32_16x16x32_bf16 v[82:85], v[6:9], v[54:57], v[82:85]
	v_mfma_f32_16x16x32_bf16 v[86:89], v[14:17], v[54:57], v[86:89]
	v_mfma_f32_16x16x32_bf16 v[102:105], v[14:17], v[62:65], v[90:93]
	v_mfma_f32_16x16x32_bf16 v[90:93], v[18:21], v[34:37], 0
	v_mfma_f32_16x16x32_bf16 v[34:37], v[26:29], v[34:37], 0
	v_mfma_f32_16x16x32_bf16 v[110:113], v[22:25], v[38:41], v[90:93]
	v_mfma_f32_16x16x32_bf16 v[34:37], v[30:33], v[38:41], v[34:37]
	v_mfma_f32_16x16x32_bf16 v[38:41], v[18:21], v[42:45], 0
	v_mfma_f32_16x16x32_bf16 v[42:45], v[26:29], v[42:45], 0
	v_mfma_f32_16x16x32_bf16 v[38:41], v[22:25], v[46:49], v[38:41]
	v_mfma_f32_16x16x32_bf16 v[42:45], v[30:33], v[46:49], v[42:45]
	v_mfma_f32_16x16x32_bf16 v[46:49], v[18:21], v[50:53], 0
	v_mfma_f32_16x16x32_bf16 v[50:53], v[26:29], v[50:53], 0
	v_mfma_f32_16x16x32_bf16 v[46:49], v[22:25], v[54:57], v[46:49]
	v_mfma_f32_16x16x32_bf16 v[54:57], v[30:33], v[54:57], v[50:53]
	v_mfma_f32_16x16x32_bf16 v[50:53], v[18:21], v[58:61], 0
	v_mfma_f32_16x16x32_bf16 v[142:145], v[22:25], v[62:65], v[50:53]
	v_mfma_f32_16x16x32_bf16 v[50:53], v[26:29], v[58:61], 0
	v_mfma_f32_16x16x32_bf16 v[146:149], v[30:33], v[62:65], v[50:53]
	s_barrier
	s_add_i32 s19, s19, s57
	v_lshl_add_u64 v[190:191], s[4:5], 0, v[0:1]
	s_mov_b32 m0, s19
	s_nop 1
	ds_read_b128 v[50:53], v137 offset:16384
	ds_read_b128 v[58:61], v137 offset:17408
	ds_read_b128 v[62:65], v137 offset:18432
	ds_read_b128 v[90:93], v137 offset:19456
	ds_read_b128 v[98:101], v137 offset:20480
	ds_read_b128 v[106:109], v137 offset:21504
	ds_read_b128 v[114:117], v137 offset:22528
	ds_read_b128 v[118:121], v137 offset:23552
	global_load_lds_dwordx4 v[190:191], off
	s_add_i32 m0, s19, 0x2000
	s_add_u32 s20, s4, 0x8000
	v_lshl_add_u64 v[192:193], s[4:5], 0, v[134:135]
	s_addc_u32 s21, s5, 0
	s_add_i32 s19, s37, s57
	global_load_lds_dwordx4 v[192:193], off
	s_mov_b32 m0, s19
	v_lshl_add_u64 v[210:211], s[44:45], 0, v[130:131]
	global_load_lds_dwordx4 v0, s[20:21]
	s_add_i32 m0, s19, 0x2000
	v_lshl_add_u64 v[214:215], s[44:45], 0, v[132:133]
	global_load_lds_dwordx4 v134, s[20:21]
	s_mov_b32 m0, s58
	s_nop 0
	global_load_lds_dwordx4 v[210:211], off
	s_mov_b32 m0, s59
	s_nop 0
	global_load_lds_dwordx4 v[214:215], off
	s_waitcnt vmcnt(8)
	s_waitcnt lgkmcnt(0)
	s_barrier
	s_waitcnt lgkmcnt(0)
	v_mfma_f32_16x16x32_bf16 v[122:125], v[2:5], v[50:53], 0
	v_mfma_f32_16x16x32_bf16 v[150:153], v[6:9], v[58:61], v[122:125]
	v_mfma_f32_16x16x32_bf16 v[122:125], v[10:13], v[50:53], 0
	v_mfma_f32_16x16x32_bf16 v[154:157], v[14:17], v[58:61], v[122:125]
	v_mfma_f32_16x16x32_bf16 v[122:125], v[2:5], v[62:65], 0
	v_mfma_f32_16x16x32_bf16 v[158:161], v[6:9], v[90:93], v[122:125]
	v_mfma_f32_16x16x32_bf16 v[122:125], v[10:13], v[62:65], 0
	v_mfma_f32_16x16x32_bf16 v[162:165], v[14:17], v[90:93], v[122:125]
	v_mfma_f32_16x16x32_bf16 v[122:125], v[2:5], v[98:101], 0
	v_mfma_f32_16x16x32_bf16 v[2:5], v[2:5], v[114:117], 0
	v_mfma_f32_16x16x32_bf16 v[166:169], v[6:9], v[106:109], v[122:125]
	v_mfma_f32_16x16x32_bf16 v[2:5], v[6:9], v[118:121], v[2:5]
	v_mfma_f32_16x16x32_bf16 v[6:9], v[10:13], v[114:117], 0
	v_mfma_f32_16x16x32_bf16 v[122:125], v[10:13], v[98:101], 0
	v_mfma_f32_16x16x32_bf16 v[6:9], v[14:17], v[118:121], v[6:9]
	v_mfma_f32_16x16x32_bf16 v[170:173], v[14:17], v[106:109], v[122:125]
	v_mfma_f32_16x16x32_bf16 v[10:13], v[18:21], v[50:53], 0
	v_mfma_f32_16x16x32_bf16 v[14:17], v[22:25], v[58:61], v[10:13]
	v_mfma_f32_16x16x32_bf16 v[10:13], v[26:29], v[50:53], 0
	v_mfma_f32_16x16x32_bf16 v[174:177], v[30:33], v[58:61], v[10:13]
	v_mfma_f32_16x16x32_bf16 v[10:13], v[18:21], v[62:65], 0
	v_mfma_f32_16x16x32_bf16 v[178:181], v[22:25], v[90:93], v[10:13]
	v_mfma_f32_16x16x32_bf16 v[10:13], v[26:29], v[62:65], 0
	v_mfma_f32_16x16x32_bf16 v[186:189], v[30:33], v[90:93], v[10:13]
	v_mfma_f32_16x16x32_bf16 v[10:13], v[18:21], v[98:101], 0
	v_mfma_f32_16x16x32_bf16 v[198:201], v[22:25], v[106:109], v[10:13]
	v_mfma_f32_16x16x32_bf16 v[10:13], v[26:29], v[98:101], 0
	v_mfma_f32_16x16x32_bf16 v[202:205], v[30:33], v[106:109], v[10:13]
	v_mfma_f32_16x16x32_bf16 v[10:13], v[18:21], v[114:117], 0
	v_mfma_f32_16x16x32_bf16 v[206:209], v[22:25], v[118:121], v[10:13]
	v_mfma_f32_16x16x32_bf16 v[10:13], v[26:29], v[114:117], 0
	v_mfma_f32_16x16x32_bf16 v[218:221], v[30:33], v[118:121], v[10:13]
	s_barrier
	s_add_i32 s19, 0, 0x18000
	v_add_u32_e32 v18, s19, v136
	s_add_i32 s37, 0, 0x1c000
	s_nop 1
	ds_read_b128 v[10:13], v18
	ds_read_b128 v[22:25], v18 offset:1024
	ds_read_b128 v[30:33], v18 offset:2048
	ds_read_b128 v[222:225], v18 offset:3072
	v_add_u32_e32 v18, s37, v136
	ds_read_b128 v[226:229], v18
	ds_read_b128 v[230:233], v18 offset:1024
	ds_read_b128 v[234:237], v18 offset:2048
	ds_read_b128 v[238:241], v18 offset:3072
	s_add_u32 s20, s44, 0x8000
	s_addc_u32 s21, s45, 0
	s_mov_b32 m0, s60
	ds_read_b128 v[18:21], v137 offset:32768
	ds_read_b128 v[26:29], v137 offset:33792
	ds_read_b128 v[62:65], v137 offset:34816
	ds_read_b128 v[242:245], v137 offset:35840
	ds_read_b128 v[246:249], v137 offset:36864
	ds_read_b128 v[250:253], v137 offset:37888
	ds_read_b128 v[182:185], v137 offset:38912
	ds_read_b128 v[194:197], v137 offset:39936
	global_load_lds_dwordx4 v130, s[20:21]
	s_mov_b32 m0, s61
	s_nop 0
	global_load_lds_dwordx4 v132, s[20:21]
	s_waitcnt vmcnt(8)
	s_waitcnt lgkmcnt(0)
	s_barrier
	s_waitcnt lgkmcnt(0)
	v_mfma_f32_16x16x32_bf16 v[50:53], v[10:13], v[18:21], v[66:69]
	v_mfma_f32_16x16x32_bf16 v[126:129], v[22:25], v[26:29], v[50:53]
	v_mfma_f32_16x16x32_bf16 v[50:53], v[30:33], v[18:21], v[70:73]
	v_mfma_f32_16x16x32_bf16 v[122:125], v[222:225], v[26:29], v[50:53]
	v_mfma_f32_16x16x32_bf16 v[50:53], v[10:13], v[62:65], v[74:77]
	v_mfma_f32_16x16x32_bf16 v[106:109], v[22:25], v[242:245], v[50:53]
	v_mfma_f32_16x16x32_bf16 v[50:53], v[30:33], v[62:65], v[78:81]
	v_mfma_f32_16x16x32_bf16 v[98:101], v[222:225], v[242:245], v[50:53]
	v_mfma_f32_16x16x32_bf16 v[50:53], v[10:13], v[246:249], v[82:85]
	v_mfma_f32_16x16x32_bf16 v[90:93], v[22:25], v[250:253], v[50:53]
	v_mfma_f32_16x16x32_bf16 v[50:53], v[30:33], v[246:249], v[86:89]
	v_mfma_f32_16x16x32_bf16 v[78:81], v[222:225], v[250:253], v[50:53]
	v_mfma_f32_16x16x32_bf16 v[50:53], v[10:13], v[182:185], v[94:97]
	v_mfma_f32_16x16x32_bf16 v[58:61], v[22:25], v[194:197], v[50:53]
	v_mfma_f32_16x16x32_bf16 v[50:53], v[30:33], v[182:185], v[102:105]
	v_mfma_f32_16x16x32_bf16 v[50:53], v[222:225], v[194:197], v[50:53]
	v_mfma_f32_16x16x32_bf16 v[66:69], v[226:229], v[18:21], v[110:113]
	v_mfma_f32_16x16x32_bf16 v[18:21], v[234:237], v[18:21], v[34:37]
	v_mfma_f32_16x16x32_bf16 v[114:117], v[238:241], v[26:29], v[18:21]
	v_mfma_f32_16x16x32_bf16 v[18:21], v[226:229], v[62:65], v[38:41]
	v_mfma_f32_16x16x32_bf16 v[110:113], v[230:233], v[242:245], v[18:21]
	v_mfma_f32_16x16x32_bf16 v[18:21], v[234:237], v[62:65], v[42:45]
	v_mfma_f32_16x16x32_bf16 v[102:105], v[238:241], v[242:245], v[18:21]
	v_mfma_f32_16x16x32_bf16 v[18:21], v[226:229], v[246:249], v[46:49]
	v_mfma_f32_16x16x32_bf16 v[94:97], v[230:233], v[250:253], v[18:21]
	v_mfma_f32_16x16x32_bf16 v[18:21], v[234:237], v[246:249], v[54:57]
	v_mfma_f32_16x16x32_bf16 v[82:85], v[238:241], v[250:253], v[18:21]
	v_mfma_f32_16x16x32_bf16 v[18:21], v[226:229], v[182:185], v[142:145]
	v_mfma_f32_16x16x32_bf16 v[62:65], v[230:233], v[194:197], v[18:21]
	v_mfma_f32_16x16x32_bf16 v[18:21], v[234:237], v[182:185], v[146:149]
	v_mfma_f32_16x16x32_bf16 v[118:121], v[230:233], v[26:29], v[66:69]
	v_mfma_f32_16x16x32_bf16 v[54:57], v[238:241], v[194:197], v[18:21]
	s_barrier
	s_add_i32 s19, s19, s57
	s_nop 2
	v_lshl_add_u64 v[18:19], v[190:191], 0, s[24:25]
	s_mov_b32 m0, s19
	ds_read_b128 v[38:41], v137 offset:49152
	ds_read_b128 v[46:49], v137 offset:50176
	ds_read_b128 v[142:145], v137 offset:51200
	ds_read_b128 v[146:149], v137 offset:52224
	ds_read_b128 v[182:185], v137 offset:53248
	ds_read_b128 v[194:197], v137 offset:54272
	ds_read_b128 v[242:245], v137 offset:55296
	ds_read_b128 v[246:249], v137 offset:56320
	global_load_lds_dwordx4 v[18:19], off
	s_add_i32 m0, s19, 0x2000
	s_add_u32 s4, s4, 0x8080
	v_lshl_add_u64 v[18:19], v[192:193], 0, s[24:25]
	s_addc_u32 s5, s5, 0
	s_add_i32 s19, s37, s57
	global_load_lds_dwordx4 v[18:19], off
	s_mov_b32 m0, s19
	s_nop 0
	global_load_lds_dwordx4 v0, s[4:5]
	s_add_i32 m0, s19, 0x2000
	s_nop 0
	global_load_lds_dwordx4 v134, s[4:5]
	v_lshl_add_u64 v[18:19], v[210:211], 0, s[24:25]
	s_mov_b32 m0, s66
	s_nop 0
	global_load_lds_dwordx4 v[18:19], off
	v_lshl_add_u64 v[18:19], v[214:215], 0, s[24:25]
	s_mov_b32 m0, s67
	s_nop 0
	global_load_lds_dwordx4 v[18:19], off
	s_waitcnt vmcnt(8)
	s_waitcnt lgkmcnt(0)
	s_barrier
	s_waitcnt lgkmcnt(0)
	v_mfma_f32_16x16x32_bf16 v[18:21], v[10:13], v[38:41], v[150:153]
	v_mfma_f32_16x16x32_bf16 v[86:89], v[22:25], v[46:49], v[18:21]
	v_mfma_f32_16x16x32_bf16 v[18:21], v[30:33], v[38:41], v[154:157]
	v_mfma_f32_16x16x32_bf16 v[74:77], v[222:225], v[46:49], v[18:21]
	v_mfma_f32_16x16x32_bf16 v[18:21], v[10:13], v[142:145], v[158:161]
	v_mfma_f32_16x16x32_bf16 v[42:45], v[22:25], v[146:149], v[18:21]
	v_mfma_f32_16x16x32_bf16 v[18:21], v[30:33], v[142:145], v[162:165]
	v_mfma_f32_16x16x32_bf16 v[34:37], v[222:225], v[146:149], v[18:21]
	v_mfma_f32_16x16x32_bf16 v[18:21], v[10:13], v[182:185], v[166:169]
	v_mfma_f32_16x16x32_bf16 v[2:5], v[10:13], v[242:245], v[2:5]
	v_mfma_f32_16x16x32_bf16 v[26:29], v[22:25], v[194:197], v[18:21]
	v_mfma_f32_16x16x32_bf16 v[18:21], v[30:33], v[182:185], v[170:173]
	v_mfma_f32_16x16x32_bf16 v[10:13], v[22:25], v[246:249], v[2:5]
	v_mfma_f32_16x16x32_bf16 v[2:5], v[30:33], v[242:245], v[6:9]
	v_mfma_f32_16x16x32_bf16 v[18:21], v[222:225], v[194:197], v[18:21]
	v_mfma_f32_16x16x32_bf16 v[2:5], v[222:225], v[246:249], v[2:5]
	v_mfma_f32_16x16x32_bf16 v[6:9], v[226:229], v[38:41], v[14:17]
	v_mfma_f32_16x16x32_bf16 v[70:73], v[230:233], v[46:49], v[6:9]
	v_mfma_f32_16x16x32_bf16 v[6:9], v[234:237], v[38:41], v[174:177]
	v_mfma_f32_16x16x32_bf16 v[66:69], v[238:241], v[46:49], v[6:9]
	v_mfma_f32_16x16x32_bf16 v[6:9], v[226:229], v[142:145], v[178:181]
	v_mfma_f32_16x16x32_bf16 v[46:49], v[230:233], v[146:149], v[6:9]
	v_mfma_f32_16x16x32_bf16 v[6:9], v[234:237], v[142:145], v[186:189]
	v_mfma_f32_16x16x32_bf16 v[38:41], v[238:241], v[146:149], v[6:9]
	v_mfma_f32_16x16x32_bf16 v[6:9], v[226:229], v[182:185], v[198:201]
	v_mfma_f32_16x16x32_bf16 v[30:33], v[230:233], v[194:197], v[6:9]
	v_mfma_f32_16x16x32_bf16 v[6:9], v[234:237], v[182:185], v[202:205]
	v_mfma_f32_16x16x32_bf16 v[22:25], v[238:241], v[194:197], v[6:9]
	v_mfma_f32_16x16x32_bf16 v[6:9], v[226:229], v[242:245], v[206:209]
	v_mfma_f32_16x16x32_bf16 v[14:17], v[230:233], v[246:249], v[6:9]
	v_mfma_f32_16x16x32_bf16 v[6:9], v[234:237], v[242:245], v[218:221]
	v_mfma_f32_16x16x32_bf16 v[6:9], v[238:241], v[246:249], v[6:9]
	s_barrier
	s_andn2_b64 vcc, exec, s[8:9]
	s_cbranch_vccnz .LBB0_553
	s_barrier

.LBB0_564:
	s_lshl_b32 s93, s20, 6
	s_lshl_b32 s9, s20, 13
	s_lshl_b32 s20, s21, 5
	s_and_b32 s94, s20, 0x60
	s_lshl_b32 s20, s94, 7
	s_add_u32 s44, s6, 0x30000000
	s_addc_u32 s45, s7, 0
	s_lshl_b64 s[6:7], s[22:23], 2
	s_add_u32 s46, s46, s6
	s_addc_u32 s47, s47, s7
	s_add_u32 s48, s4, s6
	s_addc_u32 s49, s5, s7
	s_add_i32 m0, s71, 0x18000
	v_lshl_add_u64 v[8:9], v[8:9], 0, s[24:25]
	s_waitcnt vmcnt(2)
	s_barrier
	global_load_lds_dwordx4 v[8:9], off
	v_lshl_add_u64 v[6:7], v[6:7], 0, s[24:25]
	s_add_i32 m0, s71, 0x1a000
	s_add_i32 s95, s71, 0x8000
	s_add_i32 s96, s71, 0xa000
	global_load_lds_dwordx4 v[6:7], off
	v_lshl_add_u64 v[2:3], v[2:3], 0, s[24:25]
	s_mov_b32 m0, s95
	s_add_u32 s4, s60, 0x8080
	global_load_lds_dwordx4 v[2:3], off
	v_lshl_add_u64 v[2:3], v[4:5], 0, s[24:25]
	s_mov_b32 m0, s96
	s_addc_u32 s5, s61, 0
	global_load_lds_dwordx4 v[2:3], off
	s_add_i32 m0, s71, 0x1c000
	global_load_lds_dwordx4 v0, s[4:5]
	v_lshl_add_u64 v[2:3], s[4:5], 0, v[142:143]
	s_add_i32 m0, s71, 0x1e000
	v_bfe_u32 v158, v10, 4, 2
	global_load_lds_dwordx4 v[2:3], off
	v_and_b32_e32 v159, 15, v10
	v_lshlrev_b32_e32 v2, 4, v158
	v_lshlrev_b32_e32 v3, 2, v10
	s_cmpk_lt_u32 s17, 0x100
	v_lshl_or_b32 v2, v159, 6, v2
	v_and_b32_e32 v3, 32, v3
	s_cselect_b64 s[50:51], -1, 0
	s_lshl_b32 s97, s52, 3
	v_bitop3_b32 v4, v2, s9, v3 bitop3:0xde
	v_bitop3_b32 v160, v2, s20, v3 bitop3:0xde
	v_cvt_f32_ubyte0_e32 v2, s97
	v_rcp_iflag_f32_e32 v2, v2
	s_sub_i32 s5, 0, s97
	s_waitcnt vmcnt(6)
	s_ashr_i32 s86, s41, 31
	v_mul_f32_e32 v2, 0x4f7ffffe, v2
	v_cvt_u32_f32_e32 v2, v2
	s_ashr_i32 s4, s53, 31
	s_lshl_b32 s81, s52, 5
	s_mov_b32 s17, s23
	v_readfirstlane_b32 s6, v2
	s_mul_i32 s5, s5, s6
	s_mul_hi_u32 s5, s6, s5
	s_add_i32 s88, s6, s5
	s_add_u32 s52, s41, s53
	s_addc_u32 s53, s86, s4
	v_add_u32_e32 v161, 0, v4
	s_barrier
	s_branch .LBB0_567

.LBB0_571:
	s_ashr_i32 s55, s54, 31
	s_lshl_b64 s[20:21], s[54:55], 16
	s_add_u32 s58, s69, s20
	s_addc_u32 s59, s70, s21
	s_and_b64 s[6:7], s[6:7], exec
	s_cselect_b32 s7, s59, s61
	s_cselect_b32 s6, s58, s60
	s_add_i32 s9, 0, 0x10000
	s_add_i32 s37, 0, 0x14000
	v_add_u32_e32 v14, s9, v160
	v_add_u32_e32 v30, s37, v160
	ds_read_b128 v[2:5], v14
	ds_read_b128 v[6:9], v14 offset:1024
	ds_read_b128 v[10:13], v14 offset:2048
	ds_read_b128 v[14:17], v14 offset:3072
	ds_read_b128 v[18:21], v30
	ds_read_b128 v[22:25], v30 offset:1024
	ds_read_b128 v[26:29], v30 offset:2048
	ds_read_b128 v[30:33], v30 offset:3072
	s_add_u32 s20, s62, 0x10080
	s_addc_u32 s21, s63, 0
	s_add_i32 m0, s71, 0xc000
	ds_read_b128 v[34:37], v161
	ds_read_b128 v[38:41], v161 offset:1024
	ds_read_b128 v[42:45], v161 offset:2048
	ds_read_b128 v[46:49], v161 offset:3072
	ds_read_b128 v[50:53], v161 offset:4096
	ds_read_b128 v[54:57], v161 offset:5120
	ds_read_b128 v[58:61], v161 offset:6144
	ds_read_b128 v[62:65], v161 offset:7168
	global_load_lds_dwordx4 v138, s[20:21]
	s_add_i32 m0, s71, 0xe000
	s_nop 0
	global_load_lds_dwordx4 v140, s[20:21]
	s_waitcnt vmcnt(8)
	s_waitcnt lgkmcnt(0)
	s_barrier
	s_waitcnt lgkmcnt(0)
	v_mfma_f32_16x16x32_bf16 v[66:69], v[2:5], v[34:37], 0
	v_mfma_f32_16x16x32_bf16 v[70:73], v[10:13], v[34:37], 0
	v_mfma_f32_16x16x32_bf16 v[74:77], v[2:5], v[42:45], 0
	v_mfma_f32_16x16x32_bf16 v[78:81], v[10:13], v[42:45], 0
	v_mfma_f32_16x16x32_bf16 v[82:85], v[2:5], v[50:53], 0
	v_mfma_f32_16x16x32_bf16 v[86:89], v[10:13], v[50:53], 0
	v_mfma_f32_16x16x32_bf16 v[90:93], v[2:5], v[58:61], 0
	v_mfma_f32_16x16x32_bf16 v[94:97], v[10:13], v[58:61], 0
	v_mfma_f32_16x16x32_bf16 v[66:69], v[6:9], v[38:41], v[66:69]
	v_mfma_f32_16x16x32_bf16 v[70:73], v[14:17], v[38:41], v[70:73]
	v_mfma_f32_16x16x32_bf16 v[74:77], v[6:9], v[46:49], v[74:77]
	v_mfma_f32_16x16x32_bf16 v[78:81], v[14:17], v[46:49], v[78:81]
	v_mfma_f32_16x16x32_bf16 v[82:85], v[6:9], v[54:57], v[82:85]
	v_mfma_f32_16x16x32_bf16 v[86:89], v[14:17], v[54:57], v[86:89]
	v_mfma_f32_16x16x32_bf16 v[90:93], v[6:9], v[62:65], v[90:93]
	v_mfma_f32_16x16x32_bf16 v[94:97], v[14:17], v[62:65], v[94:97]
	v_mfma_f32_16x16x32_bf16 v[98:101], v[18:21], v[34:37], 0
	v_mfma_f32_16x16x32_bf16 v[34:37], v[26:29], v[34:37], 0
	v_mfma_f32_16x16x32_bf16 v[98:101], v[22:25], v[38:41], v[98:101]
	v_mfma_f32_16x16x32_bf16 v[34:37], v[30:33], v[38:41], v[34:37]
	v_mfma_f32_16x16x32_bf16 v[38:41], v[18:21], v[42:45], 0
	v_mfma_f32_16x16x32_bf16 v[42:45], v[26:29], v[42:45], 0
	v_mfma_f32_16x16x32_bf16 v[38:41], v[22:25], v[46:49], v[38:41]
	v_mfma_f32_16x16x32_bf16 v[42:45], v[30:33], v[46:49], v[42:45]
	v_mfma_f32_16x16x32_bf16 v[46:49], v[18:21], v[50:53], 0
	v_mfma_f32_16x16x32_bf16 v[50:53], v[26:29], v[50:53], 0
	v_mfma_f32_16x16x32_bf16 v[46:49], v[22:25], v[54:57], v[46:49]
	v_mfma_f32_16x16x32_bf16 v[50:53], v[30:33], v[54:57], v[50:53]
	v_mfma_f32_16x16x32_bf16 v[54:57], v[18:21], v[58:61], 0
	v_mfma_f32_16x16x32_bf16 v[58:61], v[26:29], v[58:61], 0
	v_mfma_f32_16x16x32_bf16 v[54:57], v[22:25], v[62:65], v[54:57]
	v_mfma_f32_16x16x32_bf16 v[102:105], v[30:33], v[62:65], v[58:61]
	s_barrier
	s_add_i32 s9, s9, s66
	v_lshl_add_u64 v[156:157], s[6:7], 0, v[0:1]
	s_mov_b32 m0, s9
	s_nop 0
	ds_read_b128 v[58:61], v161 offset:16384
	ds_read_b128 v[62:65], v161 offset:17408
	ds_read_b128 v[106:109], v161 offset:18432
	ds_read_b128 v[110:113], v161 offset:19456
	ds_read_b128 v[114:117], v161 offset:20480
	ds_read_b128 v[118:121], v161 offset:21504
	ds_read_b128 v[122:125], v161 offset:22528
	ds_read_b128 v[126:129], v161 offset:23552
	global_load_lds_dwordx4 v[156:157], off
	s_add_i32 m0, s9, 0x2000
	s_add_u32 s20, s6, 0x8000
	v_lshl_add_u64 v[210:211], s[6:7], 0, v[142:143]
	s_addc_u32 s21, s7, 0
	s_add_i32 s9, s37, s66
	global_load_lds_dwordx4 v[210:211], off
	s_mov_b32 m0, s9
	v_lshl_add_u64 v[214:215], s[56:57], 0, v[138:139]
	global_load_lds_dwordx4 v0, s[20:21]
	s_add_i32 m0, s9, 0x2000
	v_lshl_add_u64 v[216:217], s[56:57], 0, v[140:141]
	global_load_lds_dwordx4 v142, s[20:21]
	s_mov_b32 m0, s71
	s_nop 0
	global_load_lds_dwordx4 v[214:215], off
	s_mov_b32 m0, s72
	s_nop 0
	global_load_lds_dwordx4 v[216:217], off
	s_waitcnt vmcnt(8)
	s_waitcnt lgkmcnt(0)
	s_barrier
	s_waitcnt lgkmcnt(0)
	v_mfma_f32_16x16x32_bf16 v[130:133], v[2:5], v[58:61], 0
	v_mfma_f32_16x16x32_bf16 v[144:147], v[6:9], v[62:65], v[130:133]
	v_mfma_f32_16x16x32_bf16 v[130:133], v[10:13], v[58:61], 0
	v_mfma_f32_16x16x32_bf16 v[148:151], v[14:17], v[62:65], v[130:133]
	v_mfma_f32_16x16x32_bf16 v[130:133], v[2:5], v[106:109], 0
	v_mfma_f32_16x16x32_bf16 v[152:155], v[6:9], v[110:113], v[130:133]
	v_mfma_f32_16x16x32_bf16 v[130:133], v[10:13], v[106:109], 0
	v_mfma_f32_16x16x32_bf16 v[162:165], v[14:17], v[110:113], v[130:133]
	v_mfma_f32_16x16x32_bf16 v[130:133], v[2:5], v[114:117], 0
	v_mfma_f32_16x16x32_bf16 v[2:5], v[2:5], v[122:125], 0
	v_mfma_f32_16x16x32_bf16 v[166:169], v[6:9], v[118:121], v[130:133]
	v_mfma_f32_16x16x32_bf16 v[130:133], v[10:13], v[114:117], 0
	v_mfma_f32_16x16x32_bf16 v[174:177], v[6:9], v[126:129], v[2:5]
	v_mfma_f32_16x16x32_bf16 v[2:5], v[10:13], v[122:125], 0
	v_mfma_f32_16x16x32_bf16 v[170:173], v[14:17], v[118:121], v[130:133]
	v_mfma_f32_16x16x32_bf16 v[10:13], v[14:17], v[126:129], v[2:5]
	v_mfma_f32_16x16x32_bf16 v[2:5], v[18:21], v[58:61], 0
	v_mfma_f32_16x16x32_bf16 v[14:17], v[22:25], v[62:65], v[2:5]
	v_mfma_f32_16x16x32_bf16 v[2:5], v[26:29], v[58:61], 0
	v_mfma_f32_16x16x32_bf16 v[178:181], v[30:33], v[62:65], v[2:5]
	v_mfma_f32_16x16x32_bf16 v[2:5], v[18:21], v[106:109], 0
	v_mfma_f32_16x16x32_bf16 v[182:185], v[22:25], v[110:113], v[2:5]
	v_mfma_f32_16x16x32_bf16 v[2:5], v[26:29], v[106:109], 0
	v_mfma_f32_16x16x32_bf16 v[186:189], v[30:33], v[110:113], v[2:5]
	v_mfma_f32_16x16x32_bf16 v[2:5], v[18:21], v[114:117], 0
	v_mfma_f32_16x16x32_bf16 v[194:197], v[22:25], v[118:121], v[2:5]
	v_mfma_f32_16x16x32_bf16 v[2:5], v[26:29], v[114:117], 0
	v_mfma_f32_16x16x32_bf16 v[198:201], v[30:33], v[118:121], v[2:5]
	v_mfma_f32_16x16x32_bf16 v[2:5], v[18:21], v[122:125], 0
	v_mfma_f32_16x16x32_bf16 v[18:21], v[22:25], v[126:129], v[2:5]
	v_mfma_f32_16x16x32_bf16 v[2:5], v[26:29], v[122:125], 0
	v_mfma_f32_16x16x32_bf16 v[202:205], v[30:33], v[126:129], v[2:5]
	s_barrier
	s_add_i32 s9, 0, 0x18000
	s_nop 3
	v_add_u32_e32 v2, s9, v160
	s_add_i32 s37, 0, 0x1c000
	ds_read_b128 v[22:25], v2
	ds_read_b128 v[26:29], v2 offset:1024
	ds_read_b128 v[30:33], v2 offset:2048
	ds_read_b128 v[206:209], v2 offset:3072
	v_add_u32_e32 v2, s37, v160
	ds_read_b128 v[218:221], v2
	ds_read_b128 v[222:225], v2 offset:1024
	ds_read_b128 v[226:229], v2 offset:2048
	ds_read_b128 v[230:233], v2 offset:3072
	s_add_u32 s20, s56, 0x10000
	s_addc_u32 s21, s57, 0
	s_mov_b32 m0, s73
	ds_read_b128 v[58:61], v161 offset:32768
	ds_read_b128 v[62:65], v161 offset:33792
	ds_read_b128 v[106:109], v161 offset:34816
	ds_read_b128 v[110:113], v161 offset:35840
	ds_read_b128 v[234:237], v161 offset:36864
	ds_read_b128 v[238:241], v161 offset:37888
	ds_read_b128 v[242:245], v161 offset:38912
	ds_read_b128 v[246:249], v161 offset:39936
	global_load_lds_dwordx4 v138, s[20:21]
	s_mov_b32 m0, s92
	s_nop 0
	global_load_lds_dwordx4 v140, s[20:21]
	s_waitcnt vmcnt(8)
	s_waitcnt lgkmcnt(0)
	s_barrier
	s_waitcnt lgkmcnt(0)
	v_mfma_f32_16x16x32_bf16 v[2:5], v[22:25], v[58:61], v[66:69]
	v_mfma_f32_16x16x32_bf16 v[66:69], v[22:25], v[106:109], v[74:77]
	v_mfma_f32_16x16x32_bf16 v[134:137], v[26:29], v[110:113], v[66:69]
	v_mfma_f32_16x16x32_bf16 v[66:69], v[30:33], v[106:109], v[78:81]
	v_mfma_f32_16x16x32_bf16 v[130:133], v[206:209], v[110:113], v[66:69]
	v_mfma_f32_16x16x32_bf16 v[66:69], v[22:25], v[234:237], v[82:85]
	v_mfma_f32_16x16x32_bf16 v[126:129], v[26:29], v[238:241], v[66:69]
	v_mfma_f32_16x16x32_bf16 v[66:69], v[30:33], v[234:237], v[86:89]
	v_mfma_f32_16x16x32_bf16 v[122:125], v[206:209], v[238:241], v[66:69]
	v_mfma_f32_16x16x32_bf16 v[66:69], v[22:25], v[242:245], v[90:93]
	v_mfma_f32_16x16x32_bf16 v[6:9], v[26:29], v[62:65], v[2:5]
	v_mfma_f32_16x16x32_bf16 v[2:5], v[30:33], v[58:61], v[70:73]
	v_mfma_f32_16x16x32_bf16 v[118:121], v[26:29], v[246:249], v[66:69]
	v_mfma_f32_16x16x32_bf16 v[66:69], v[30:33], v[242:245], v[94:97]
	v_mfma_f32_16x16x32_bf16 v[2:5], v[206:209], v[62:65], v[2:5]
	v_mfma_f32_16x16x32_bf16 v[114:117], v[206:209], v[246:249], v[66:69]
	v_mfma_f32_16x16x32_bf16 v[34:37], v[226:229], v[58:61], v[34:37]
	v_mfma_f32_16x16x32_bf16 v[74:77], v[230:233], v[62:65], v[34:37]
	v_mfma_f32_16x16x32_bf16 v[34:37], v[218:221], v[106:109], v[38:41]
	v_mfma_f32_16x16x32_bf16 v[66:69], v[218:221], v[58:61], v[98:101]
	v_mfma_f32_16x16x32_bf16 v[70:73], v[222:225], v[110:113], v[34:37]
	v_mfma_f32_16x16x32_bf16 v[34:37], v[226:229], v[106:109], v[42:45]
	v_mfma_f32_16x16x32_bf16 v[78:81], v[222:225], v[62:65], v[66:69]
	v_mfma_f32_16x16x32_bf16 v[66:69], v[230:233], v[110:113], v[34:37]
	v_mfma_f32_16x16x32_bf16 v[34:37], v[218:221], v[234:237], v[46:49]
	v_mfma_f32_16x16x32_bf16 v[62:65], v[222:225], v[238:241], v[34:37]
	v_mfma_f32_16x16x32_bf16 v[34:37], v[226:229], v[234:237], v[50:53]
	v_mfma_f32_16x16x32_bf16 v[58:61], v[230:233], v[238:241], v[34:37]
	v_mfma_f32_16x16x32_bf16 v[34:37], v[218:221], v[242:245], v[54:57]
	v_mfma_f32_16x16x32_bf16 v[54:57], v[222:225], v[246:249], v[34:37]
	v_mfma_f32_16x16x32_bf16 v[34:37], v[226:229], v[242:245], v[102:105]
	v_mfma_f32_16x16x32_bf16 v[50:53], v[230:233], v[246:249], v[34:37]
	s_barrier
	s_add_i32 s9, s9, s66
	v_lshl_add_u64 v[42:43], v[156:157], 0, s[24:25]
	s_mov_b32 m0, s9
	s_nop 1
	ds_read_b128 v[34:37], v161 offset:49152
	ds_read_b128 v[38:41], v161 offset:50176
	ds_read_b128 v[234:237], v161 offset:51200
	ds_read_b128 v[238:241], v161 offset:52224
	ds_read_b128 v[242:245], v161 offset:53248
	ds_read_b128 v[246:249], v161 offset:54272
	ds_read_b128 v[250:253], v161 offset:55296
	ds_read_b128 v[190:193], v161 offset:56320
	global_load_lds_dwordx4 v[42:43], off
	s_add_i32 m0, s9, 0x2000
	s_add_u32 s6, s6, 0x8080
	v_lshl_add_u64 v[42:43], v[210:211], 0, s[24:25]
	s_addc_u32 s7, s7, 0
	s_add_i32 s9, s37, s66
	global_load_lds_dwordx4 v[42:43], off
	s_mov_b32 m0, s9
	s_nop 0
	global_load_lds_dwordx4 v0, s[6:7]
	s_add_i32 m0, s9, 0x2000
	s_nop 0
	global_load_lds_dwordx4 v142, s[6:7]
	v_lshl_add_u64 v[42:43], v[214:215], 0, s[24:25]
	s_mov_b32 m0, s95
	s_nop 0
	global_load_lds_dwordx4 v[42:43], off
	v_lshl_add_u64 v[42:43], v[216:217], 0, s[24:25]
	s_mov_b32 m0, s96
	s_nop 0
	global_load_lds_dwordx4 v[42:43], off
	s_waitcnt vmcnt(8)
	s_waitcnt lgkmcnt(0)
	s_barrier
	s_waitcnt lgkmcnt(0)
	v_mfma_f32_16x16x32_bf16 v[42:45], v[22:25], v[34:37], v[144:147]
	v_mfma_f32_16x16x32_bf16 v[110:113], v[26:29], v[38:41], v[42:45]
	v_mfma_f32_16x16x32_bf16 v[42:45], v[30:33], v[34:37], v[148:151]
	v_mfma_f32_16x16x32_bf16 v[106:109], v[206:209], v[38:41], v[42:45]
	v_mfma_f32_16x16x32_bf16 v[42:45], v[22:25], v[234:237], v[152:155]
	v_mfma_f32_16x16x32_bf16 v[102:105], v[26:29], v[238:241], v[42:45]
	v_mfma_f32_16x16x32_bf16 v[42:45], v[30:33], v[234:237], v[162:165]
	v_mfma_f32_16x16x32_bf16 v[98:101], v[206:209], v[238:241], v[42:45]
	v_mfma_f32_16x16x32_bf16 v[42:45], v[22:25], v[242:245], v[166:169]
	v_mfma_f32_16x16x32_bf16 v[94:97], v[26:29], v[246:249], v[42:45]
	v_mfma_f32_16x16x32_bf16 v[42:45], v[30:33], v[242:245], v[170:173]
	v_mfma_f32_16x16x32_bf16 v[22:25], v[22:25], v[250:253], v[174:177]
	v_mfma_f32_16x16x32_bf16 v[10:13], v[30:33], v[250:253], v[10:13]
	v_mfma_f32_16x16x32_bf16 v[90:93], v[206:209], v[246:249], v[42:45]
	v_mfma_f32_16x16x32_bf16 v[86:89], v[26:29], v[190:193], v[22:25]
	v_mfma_f32_16x16x32_bf16 v[82:85], v[206:209], v[190:193], v[10:13]
	v_mfma_f32_16x16x32_bf16 v[10:13], v[218:221], v[34:37], v[14:17]
	v_mfma_f32_16x16x32_bf16 v[46:49], v[222:225], v[38:41], v[10:13]
	v_mfma_f32_16x16x32_bf16 v[10:13], v[226:229], v[34:37], v[178:181]
	v_mfma_f32_16x16x32_bf16 v[42:45], v[230:233], v[38:41], v[10:13]
	v_mfma_f32_16x16x32_bf16 v[10:13], v[218:221], v[234:237], v[182:185]
	v_mfma_f32_16x16x32_bf16 v[38:41], v[222:225], v[238:241], v[10:13]
	v_mfma_f32_16x16x32_bf16 v[10:13], v[226:229], v[234:237], v[186:189]
	v_mfma_f32_16x16x32_bf16 v[34:37], v[230:233], v[238:241], v[10:13]
	v_mfma_f32_16x16x32_bf16 v[10:13], v[218:221], v[242:245], v[194:197]
	v_mfma_f32_16x16x32_bf16 v[30:33], v[222:225], v[246:249], v[10:13]
	v_mfma_f32_16x16x32_bf16 v[10:13], v[226:229], v[242:245], v[198:201]
	v_mfma_f32_16x16x32_bf16 v[26:29], v[230:233], v[246:249], v[10:13]
	v_mfma_f32_16x16x32_bf16 v[10:13], v[218:221], v[250:253], v[18:21]
	v_mfma_f32_16x16x32_bf16 v[22:25], v[222:225], v[190:193], v[10:13]
	v_mfma_f32_16x16x32_bf16 v[10:13], v[226:229], v[250:253], v[202:205]
	v_mfma_f32_16x16x32_bf16 v[18:21], v[230:233], v[190:193], v[10:13]
	s_barrier
	s_andn2_b64 vcc, exec, s[50:51]
	s_cbranch_vccnz .LBB0_573
	s_barrier

.LBB0_1513:
	s_add_u32 s10, s10, 0x2b00000
	s_addc_u32 s11, s11, 0
	s_lshl_b32 s4, s4, 5
	s_and_b32 s4, s4, 0x60
	s_add_i32 m0, s58, 0x18000
	v_lshl_add_u64 v[8:9], v[8:9], 0, s[24:25]
	s_lshl_b32 s13, s5, 13
	s_lshl_b32 s16, s4, 7
	s_waitcnt vmcnt(2)
	s_barrier
	global_load_lds_dwordx4 v[8:9], off
	v_lshl_add_u64 v[6:7], v[6:7], 0, s[24:25]
	s_add_i32 m0, s58, 0x1a000
	s_add_i32 s62, s58, 0x8000
	s_add_i32 s63, s58, 0xa000
	global_load_lds_dwordx4 v[6:7], off
	v_lshl_add_u64 v[2:3], v[2:3], 0, s[24:25]
	s_mov_b32 m0, s62
	s_add_u32 s6, s48, 0x40080
	global_load_lds_dwordx4 v[2:3], off
	v_lshl_add_u64 v[2:3], v[4:5], 0, s[24:25]
	s_mov_b32 m0, s63
	s_addc_u32 s7, s49, 0
	global_load_lds_dwordx4 v[2:3], off
	s_add_i32 m0, s58, 0x1c000
	global_load_lds_dwordx4 v0, s[6:7]
	v_lshl_add_u64 v[2:3], s[6:7], 0, v[134:135]
	s_add_i32 m0, s58, 0x1e000
	s_cmpk_lt_u32 s12, 0x100
	global_load_lds_dwordx4 v[2:3], off
	v_lshrrev_b32_e32 v3, 1, v10
	v_and_b32_e32 v3, 24, v3
	v_and_b32_e32 v2, 15, v10
	v_lshlrev_b32_e32 v4, 1, v3
	v_lshl_or_b32 v144, s5, 6, v2
	v_lshl_or_b32 v2, v2, 6, v4
	v_lshlrev_b32_e32 v4, 2, v10
	v_and_b32_e32 v4, 32, v4
	v_bitop3_b32 v5, v2, s13, v4 bitop3:0xde
	v_bitop3_b32 v145, v2, s16, v4 bitop3:0xde
	v_lshlrev_b32_e32 v2, 14, v11
	v_and_b32_e32 v2, 0xffff8000, v2
	v_or_b32_e32 v146, s4, v3
	v_lshl_add_u32 v2, v12, 11, v2
	v_and_b32_e32 v3, 1, v11
	v_lshl_or_b32 v2, v3, 6, v2
	v_lshl_add_u32 v136, v13, 1, v2
	v_lshlrev_b32_e32 v2, 14, v14
	v_and_b32_e32 v2, 0xffff8000, v2
	s_waitcnt vmcnt(6)
	v_lshl_add_u32 v2, v15, 11, v2
	v_and_b32_e32 v3, 1, v14
	v_lshl_or_b32 v2, v3, 6, v2
	s_cselect_b64 s[12:13], -1, 0
	s_ashr_i32 s64, s41, 31
	s_ashr_i32 s65, s52, 31
	v_mov_b32_e32 v137, v1
	v_lshl_add_u32 v138, v16, 1, v2
	v_mov_b32_e32 v139, v1
	s_mov_b32 s66, 0
	v_add_u32_e32 v147, 0, v5
	s_barrier
	s_branch .LBB0_1516

.LBB0_1525:
	s_add_u32 s20, s6, 0xfffc0080
	s_addc_u32 s21, s7, -1
	s_add_i32 s37, 0, 0x10000
	s_cmp_eq_u32 s71, 12
	s_cselect_b32 s51, s19, s21
	s_cselect_b32 s50, s18, s20
	s_cselect_b32 s49, s17, s70
	s_cselect_b32 s48, s47, s69
	s_add_i32 s72, 0, 0x14000
	v_add_u32_e32 v156, s37, v145
	v_add_u32_e32 v172, s72, v145
	ds_read_b128 v[140:143], v156
	ds_read_b128 v[148:151], v156 offset:1024
	ds_read_b128 v[152:155], v156 offset:2048
	ds_read_b128 v[156:159], v156 offset:3072
	ds_read_b128 v[160:163], v172
	ds_read_b128 v[164:167], v172 offset:1024
	ds_read_b128 v[168:171], v172 offset:2048
	ds_read_b128 v[172:175], v172 offset:3072
	s_add_i32 m0, s58, 0xc000
	ds_read_b128 v[176:179], v147
	ds_read_b128 v[180:183], v147 offset:1024
	ds_read_b128 v[184:187], v147 offset:2048
	ds_read_b128 v[188:191], v147 offset:3072
	ds_read_b128 v[192:195], v147 offset:4096
	ds_read_b128 v[196:199], v147 offset:5120
	ds_read_b128 v[200:203], v147 offset:6144
	ds_read_b128 v[204:207], v147 offset:7168
	global_load_lds_dwordx4 v136, s[6:7]
	s_add_i32 m0, s58, 0xe000
	s_nop 0
	global_load_lds_dwordx4 v138, s[6:7]
	s_waitcnt vmcnt(8)
	s_waitcnt lgkmcnt(0)
	s_barrier
	s_waitcnt lgkmcnt(0)
	v_mfma_f32_16x16x32_bf16 v[126:129], v[140:143], v[176:179], v[126:129]
	v_mfma_f32_16x16x32_bf16 v[122:125], v[152:155], v[176:179], v[122:125]
	v_mfma_f32_16x16x32_bf16 v[114:117], v[140:143], v[184:187], v[114:117]
	v_mfma_f32_16x16x32_bf16 v[106:109], v[152:155], v[184:187], v[106:109]
	v_mfma_f32_16x16x32_bf16 v[98:101], v[140:143], v[192:195], v[98:101]
	v_mfma_f32_16x16x32_bf16 v[90:93], v[152:155], v[192:195], v[90:93]
	v_mfma_f32_16x16x32_bf16 v[82:85], v[140:143], v[200:203], v[82:85]
	v_mfma_f32_16x16x32_bf16 v[74:77], v[152:155], v[200:203], v[74:77]
	v_mfma_f32_16x16x32_bf16 v[126:129], v[148:151], v[180:183], v[126:129]
	v_mfma_f32_16x16x32_bf16 v[122:125], v[156:159], v[180:183], v[122:125]
	v_mfma_f32_16x16x32_bf16 v[114:117], v[148:151], v[188:191], v[114:117]
	v_mfma_f32_16x16x32_bf16 v[106:109], v[156:159], v[188:191], v[106:109]
	v_mfma_f32_16x16x32_bf16 v[98:101], v[148:151], v[196:199], v[98:101]
	v_mfma_f32_16x16x32_bf16 v[90:93], v[156:159], v[196:199], v[90:93]
	v_mfma_f32_16x16x32_bf16 v[82:85], v[148:151], v[204:207], v[82:85]
	v_mfma_f32_16x16x32_bf16 v[74:77], v[156:159], v[204:207], v[74:77]
	v_mfma_f32_16x16x32_bf16 v[118:121], v[160:163], v[176:179], v[118:121]
	v_mfma_f32_16x16x32_bf16 v[110:113], v[168:171], v[176:179], v[110:113]
	v_mfma_f32_16x16x32_bf16 v[102:105], v[160:163], v[184:187], v[102:105]
	v_mfma_f32_16x16x32_bf16 v[94:97], v[168:171], v[184:187], v[94:97]
	v_mfma_f32_16x16x32_bf16 v[86:89], v[160:163], v[192:195], v[86:89]
	v_mfma_f32_16x16x32_bf16 v[78:81], v[168:171], v[192:195], v[78:81]
	v_mfma_f32_16x16x32_bf16 v[70:73], v[160:163], v[200:203], v[70:73]
	v_mfma_f32_16x16x32_bf16 v[66:69], v[168:171], v[200:203], v[66:69]
	v_mfma_f32_16x16x32_bf16 v[118:121], v[164:167], v[180:183], v[118:121]
	v_mfma_f32_16x16x32_bf16 v[110:113], v[172:175], v[180:183], v[110:113]
	v_mfma_f32_16x16x32_bf16 v[102:105], v[164:167], v[188:191], v[102:105]
	v_mfma_f32_16x16x32_bf16 v[94:97], v[172:175], v[188:191], v[94:97]
	v_mfma_f32_16x16x32_bf16 v[86:89], v[164:167], v[196:199], v[86:89]
	v_mfma_f32_16x16x32_bf16 v[78:81], v[172:175], v[196:199], v[78:81]
	v_mfma_f32_16x16x32_bf16 v[70:73], v[164:167], v[204:207], v[70:73]
	v_mfma_f32_16x16x32_bf16 v[66:69], v[172:175], v[204:207], v[66:69]
	s_barrier
	s_add_i32 s20, s37, s57
	v_lshl_add_u64 v[208:209], s[48:49], 0, v[0:1]
	s_mov_b32 m0, s20
	ds_read_b128 v[176:179], v147 offset:16384
	ds_read_b128 v[180:183], v147 offset:17408
	ds_read_b128 v[184:187], v147 offset:18432
	ds_read_b128 v[188:191], v147 offset:19456
	ds_read_b128 v[192:195], v147 offset:20480
	ds_read_b128 v[196:199], v147 offset:21504
	ds_read_b128 v[200:203], v147 offset:22528
	ds_read_b128 v[204:207], v147 offset:23552
	global_load_lds_dwordx4 v[208:209], off
	s_add_i32 m0, s20, 0x2000
	s_add_u32 s20, s48, 0x40000
	v_lshl_add_u64 v[210:211], s[48:49], 0, v[134:135]
	s_addc_u32 s21, s49, 0
	s_add_i32 s37, s72, s57
	global_load_lds_dwordx4 v[210:211], off
	s_mov_b32 m0, s37
	v_lshl_add_u64 v[216:217], s[50:51], 0, v[132:133]
	global_load_lds_dwordx4 v0, s[20:21]
	s_add_i32 m0, s37, 0x2000
	s_nop 0
	global_load_lds_dwordx4 v134, s[20:21]
	v_lshl_add_u64 v[214:215], s[50:51], 0, v[130:131]
	s_mov_b32 m0, s58
	s_nop 0
	global_load_lds_dwordx4 v[214:215], off
	s_mov_b32 m0, s59
	s_nop 0
	global_load_lds_dwordx4 v[216:217], off
	s_waitcnt vmcnt(8)
	s_waitcnt lgkmcnt(0)
	s_barrier
	s_waitcnt lgkmcnt(0)
	v_mfma_f32_16x16x32_bf16 v[62:65], v[140:143], v[176:179], v[62:65]
	v_mfma_f32_16x16x32_bf16 v[58:61], v[152:155], v[176:179], v[58:61]
	v_mfma_f32_16x16x32_bf16 v[50:53], v[140:143], v[184:187], v[50:53]
	v_mfma_f32_16x16x32_bf16 v[42:45], v[152:155], v[184:187], v[42:45]
	v_mfma_f32_16x16x32_bf16 v[34:37], v[140:143], v[192:195], v[34:37]
	v_mfma_f32_16x16x32_bf16 v[26:29], v[152:155], v[192:195], v[26:29]
	v_mfma_f32_16x16x32_bf16 v[18:21], v[140:143], v[200:203], v[18:21]
	v_mfma_f32_16x16x32_bf16 v[10:13], v[152:155], v[200:203], v[10:13]
	v_mfma_f32_16x16x32_bf16 v[62:65], v[148:151], v[180:183], v[62:65]
	v_mfma_f32_16x16x32_bf16 v[58:61], v[156:159], v[180:183], v[58:61]
	v_mfma_f32_16x16x32_bf16 v[50:53], v[148:151], v[188:191], v[50:53]
	v_mfma_f32_16x16x32_bf16 v[42:45], v[156:159], v[188:191], v[42:45]
	v_mfma_f32_16x16x32_bf16 v[34:37], v[148:151], v[196:199], v[34:37]
	v_mfma_f32_16x16x32_bf16 v[26:29], v[156:159], v[196:199], v[26:29]
	v_mfma_f32_16x16x32_bf16 v[18:21], v[148:151], v[204:207], v[18:21]
	v_mfma_f32_16x16x32_bf16 v[10:13], v[156:159], v[204:207], v[10:13]
	v_mfma_f32_16x16x32_bf16 v[54:57], v[160:163], v[176:179], v[54:57]
	v_mfma_f32_16x16x32_bf16 v[46:49], v[168:171], v[176:179], v[46:49]
	v_mfma_f32_16x16x32_bf16 v[38:41], v[160:163], v[184:187], v[38:41]
	v_mfma_f32_16x16x32_bf16 v[30:33], v[168:171], v[184:187], v[30:33]
	v_mfma_f32_16x16x32_bf16 v[22:25], v[160:163], v[192:195], v[22:25]
	v_mfma_f32_16x16x32_bf16 v[14:17], v[168:171], v[192:195], v[14:17]
	v_mfma_f32_16x16x32_bf16 v[6:9], v[160:163], v[200:203], v[6:9]
	v_mfma_f32_16x16x32_bf16 v[2:5], v[168:171], v[200:203], v[2:5]
	v_mfma_f32_16x16x32_bf16 v[54:57], v[164:167], v[180:183], v[54:57]
	v_mfma_f32_16x16x32_bf16 v[46:49], v[172:175], v[180:183], v[46:49]
	v_mfma_f32_16x16x32_bf16 v[38:41], v[164:167], v[188:191], v[38:41]
	v_mfma_f32_16x16x32_bf16 v[30:33], v[172:175], v[188:191], v[30:33]
	v_mfma_f32_16x16x32_bf16 v[22:25], v[164:167], v[196:199], v[22:25]
	v_mfma_f32_16x16x32_bf16 v[14:17], v[172:175], v[196:199], v[14:17]
	v_mfma_f32_16x16x32_bf16 v[6:9], v[164:167], v[204:207], v[6:9]
	v_mfma_f32_16x16x32_bf16 v[2:5], v[172:175], v[204:207], v[2:5]
	s_barrier
	s_add_i32 s37, 0, 0x18000
	s_add_i32 s72, 0, 0x1c000
	v_add_u32_e32 v156, s37, v145
	v_add_u32_e32 v172, s72, v145
	ds_read_b128 v[140:143], v156
	ds_read_b128 v[148:151], v156 offset:1024
	ds_read_b128 v[152:155], v156 offset:2048
	ds_read_b128 v[156:159], v156 offset:3072
	ds_read_b128 v[160:163], v172
	ds_read_b128 v[164:167], v172 offset:1024
	ds_read_b128 v[168:171], v172 offset:2048
	ds_read_b128 v[172:175], v172 offset:3072
	s_add_u32 s20, s50, 0x40000
	s_addc_u32 s21, s51, 0
	s_mov_b32 m0, s60
	ds_read_b128 v[176:179], v147 offset:32768
	ds_read_b128 v[180:183], v147 offset:33792
	ds_read_b128 v[184:187], v147 offset:34816
	ds_read_b128 v[188:191], v147 offset:35840
	ds_read_b128 v[192:195], v147 offset:36864
	ds_read_b128 v[196:199], v147 offset:37888
	ds_read_b128 v[200:203], v147 offset:38912
	ds_read_b128 v[204:207], v147 offset:39936
	global_load_lds_dwordx4 v130, s[20:21]
	v_lshl_add_u64 v[218:219], s[20:21], 0, v[132:133]
	s_mov_b32 m0, s61
	s_nop 0
	global_load_lds_dwordx4 v[218:219], off
	s_waitcnt vmcnt(8)
	s_waitcnt lgkmcnt(0)
	s_barrier
	s_waitcnt lgkmcnt(0)
	v_mfma_f32_16x16x32_bf16 v[126:129], v[140:143], v[176:179], v[126:129]
	v_mfma_f32_16x16x32_bf16 v[122:125], v[152:155], v[176:179], v[122:125]
	v_mfma_f32_16x16x32_bf16 v[114:117], v[140:143], v[184:187], v[114:117]
	v_mfma_f32_16x16x32_bf16 v[106:109], v[152:155], v[184:187], v[106:109]
	v_mfma_f32_16x16x32_bf16 v[98:101], v[140:143], v[192:195], v[98:101]
	v_mfma_f32_16x16x32_bf16 v[90:93], v[152:155], v[192:195], v[90:93]
	v_mfma_f32_16x16x32_bf16 v[82:85], v[140:143], v[200:203], v[82:85]
	v_mfma_f32_16x16x32_bf16 v[74:77], v[152:155], v[200:203], v[74:77]
	v_mfma_f32_16x16x32_bf16 v[126:129], v[148:151], v[180:183], v[126:129]
	v_mfma_f32_16x16x32_bf16 v[122:125], v[156:159], v[180:183], v[122:125]
	v_mfma_f32_16x16x32_bf16 v[114:117], v[148:151], v[188:191], v[114:117]
	v_mfma_f32_16x16x32_bf16 v[106:109], v[156:159], v[188:191], v[106:109]
	v_mfma_f32_16x16x32_bf16 v[98:101], v[148:151], v[196:199], v[98:101]
	v_mfma_f32_16x16x32_bf16 v[90:93], v[156:159], v[196:199], v[90:93]
	v_mfma_f32_16x16x32_bf16 v[82:85], v[148:151], v[204:207], v[82:85]
	v_mfma_f32_16x16x32_bf16 v[74:77], v[156:159], v[204:207], v[74:77]
	v_mfma_f32_16x16x32_bf16 v[118:121], v[160:163], v[176:179], v[118:121]
	v_mfma_f32_16x16x32_bf16 v[110:113], v[168:171], v[176:179], v[110:113]
	v_mfma_f32_16x16x32_bf16 v[102:105], v[160:163], v[184:187], v[102:105]
	v_mfma_f32_16x16x32_bf16 v[94:97], v[168:171], v[184:187], v[94:97]
	v_mfma_f32_16x16x32_bf16 v[86:89], v[160:163], v[192:195], v[86:89]
	v_mfma_f32_16x16x32_bf16 v[78:81], v[168:171], v[192:195], v[78:81]
	v_mfma_f32_16x16x32_bf16 v[70:73], v[160:163], v[200:203], v[70:73]
	v_mfma_f32_16x16x32_bf16 v[66:69], v[168:171], v[200:203], v[66:69]
	v_mfma_f32_16x16x32_bf16 v[118:121], v[164:167], v[180:183], v[118:121]
	v_mfma_f32_16x16x32_bf16 v[110:113], v[172:175], v[180:183], v[110:113]
	v_mfma_f32_16x16x32_bf16 v[102:105], v[164:167], v[188:191], v[102:105]
	v_mfma_f32_16x16x32_bf16 v[94:97], v[172:175], v[188:191], v[94:97]
	v_mfma_f32_16x16x32_bf16 v[86:89], v[164:167], v[196:199], v[86:89]
	v_mfma_f32_16x16x32_bf16 v[78:81], v[172:175], v[196:199], v[78:81]
	v_mfma_f32_16x16x32_bf16 v[70:73], v[164:167], v[204:207], v[70:73]
	v_mfma_f32_16x16x32_bf16 v[66:69], v[172:175], v[204:207], v[66:69]
	s_barrier
	s_add_i32 s20, s37, s57
	v_lshl_add_u64 v[208:209], v[208:209], 0, s[24:25]
	s_mov_b32 m0, s20
	ds_read_b128 v[176:179], v147 offset:49152
	ds_read_b128 v[180:183], v147 offset:50176
	ds_read_b128 v[184:187], v147 offset:51200
	ds_read_b128 v[188:191], v147 offset:52224
	ds_read_b128 v[192:195], v147 offset:53248
	ds_read_b128 v[196:199], v147 offset:54272
	ds_read_b128 v[200:203], v147 offset:55296
	ds_read_b128 v[204:207], v147 offset:56320
	global_load_lds_dwordx4 v[208:209], off
	s_add_i32 m0, s20, 0x2000
	s_add_u32 s20, s48, 0x40080
	v_lshl_add_u64 v[208:209], v[210:211], 0, s[24:25]
	s_addc_u32 s21, s49, 0
	s_add_i32 s37, s72, s57
	global_load_lds_dwordx4 v[208:209], off
	s_mov_b32 m0, s37
	s_nop 0
	global_load_lds_dwordx4 v0, s[20:21]
	s_add_i32 m0, s37, 0x2000
	s_nop 0
	global_load_lds_dwordx4 v134, s[20:21]
	v_lshl_add_u64 v[208:209], v[214:215], 0, s[24:25]
	s_mov_b32 m0, s62
	s_nop 0
	global_load_lds_dwordx4 v[208:209], off
	v_lshl_add_u64 v[208:209], v[216:217], 0, s[24:25]
	s_mov_b32 m0, s63
	s_nop 0
	global_load_lds_dwordx4 v[208:209], off
	s_waitcnt vmcnt(8)
	s_waitcnt lgkmcnt(0)
	s_barrier
	s_waitcnt lgkmcnt(0)
	v_mfma_f32_16x16x32_bf16 v[62:65], v[140:143], v[176:179], v[62:65]
	v_mfma_f32_16x16x32_bf16 v[58:61], v[152:155], v[176:179], v[58:61]
	v_mfma_f32_16x16x32_bf16 v[50:53], v[140:143], v[184:187], v[50:53]
	v_mfma_f32_16x16x32_bf16 v[42:45], v[152:155], v[184:187], v[42:45]
	v_mfma_f32_16x16x32_bf16 v[34:37], v[140:143], v[192:195], v[34:37]
	v_mfma_f32_16x16x32_bf16 v[26:29], v[152:155], v[192:195], v[26:29]
	v_mfma_f32_16x16x32_bf16 v[18:21], v[140:143], v[200:203], v[18:21]
	v_mfma_f32_16x16x32_bf16 v[10:13], v[152:155], v[200:203], v[10:13]
	v_mfma_f32_16x16x32_bf16 v[62:65], v[148:151], v[180:183], v[62:65]
	v_mfma_f32_16x16x32_bf16 v[58:61], v[156:159], v[180:183], v[58:61]
	v_mfma_f32_16x16x32_bf16 v[50:53], v[148:151], v[188:191], v[50:53]
	v_mfma_f32_16x16x32_bf16 v[42:45], v[156:159], v[188:191], v[42:45]
	v_mfma_f32_16x16x32_bf16 v[34:37], v[148:151], v[196:199], v[34:37]
	v_mfma_f32_16x16x32_bf16 v[26:29], v[156:159], v[196:199], v[26:29]
	v_mfma_f32_16x16x32_bf16 v[18:21], v[148:151], v[204:207], v[18:21]
	v_mfma_f32_16x16x32_bf16 v[10:13], v[156:159], v[204:207], v[10:13]
	v_mfma_f32_16x16x32_bf16 v[54:57], v[160:163], v[176:179], v[54:57]
	v_mfma_f32_16x16x32_bf16 v[46:49], v[168:171], v[176:179], v[46:49]
	v_mfma_f32_16x16x32_bf16 v[38:41], v[160:163], v[184:187], v[38:41]
	v_mfma_f32_16x16x32_bf16 v[30:33], v[168:171], v[184:187], v[30:33]
	v_mfma_f32_16x16x32_bf16 v[22:25], v[160:163], v[192:195], v[22:25]
	v_mfma_f32_16x16x32_bf16 v[14:17], v[168:171], v[192:195], v[14:17]
	v_mfma_f32_16x16x32_bf16 v[6:9], v[160:163], v[200:203], v[6:9]
	v_mfma_f32_16x16x32_bf16 v[2:5], v[168:171], v[200:203], v[2:5]
	v_mfma_f32_16x16x32_bf16 v[54:57], v[164:167], v[180:183], v[54:57]
	v_mfma_f32_16x16x32_bf16 v[46:49], v[172:175], v[180:183], v[46:49]
	v_mfma_f32_16x16x32_bf16 v[38:41], v[164:167], v[188:191], v[38:41]
	v_mfma_f32_16x16x32_bf16 v[30:33], v[172:175], v[188:191], v[30:33]
	v_mfma_f32_16x16x32_bf16 v[22:25], v[164:167], v[196:199], v[22:25]
	v_mfma_f32_16x16x32_bf16 v[14:17], v[172:175], v[196:199], v[14:17]
	v_mfma_f32_16x16x32_bf16 v[6:9], v[164:167], v[204:207], v[6:9]
	v_mfma_f32_16x16x32_bf16 v[2:5], v[172:175], v[204:207], v[2:5]
	s_barrier
	s_add_i32 s71, s71, 2
	s_add_u32 s6, s6, 0x100
	s_addc_u32 s7, s7, 0
	s_add_u32 s69, s69, 0x100
	s_addc_u32 s70, s70, 0
	s_cmp_gt_u32 s71, 13
	s_cbranch_scc0 .LBB0_1525
	s_and_b64 vcc, exec, s[12:13]
	s_cbranch_vccz .LBB0_1528
	s_barrier

.LBB0_1868:
	s_and_b32 s64, s2, 3
	s_add_i32 m0, s60, 0x18000
	v_lshl_add_u64 v[8:9], v[8:9], 0, s[24:25]
	s_lshl_b32 s65, s3, 6
	s_lshl_b32 s4, s3, 13
	s_lshl_b32 s66, s64, 5
	s_lshl_b32 s5, s64, 12
	s_waitcnt vmcnt(2)
	s_barrier
	global_load_lds_dwordx4 v[8:9], off
	v_lshl_add_u64 v[6:7], v[6:7], 0, s[24:25]
	s_add_i32 m0, s60, 0x1a000
	s_add_i32 s67, s60, 0x8000
	s_add_i32 s68, s60, 0xa000
	global_load_lds_dwordx4 v[6:7], off
	v_lshl_add_u64 v[2:3], v[2:3], 0, s[24:25]
	s_mov_b32 m0, s67
	s_add_u32 s2, s50, 0x40080
	global_load_lds_dwordx4 v[2:3], off
	v_lshl_add_u64 v[2:3], v[4:5], 0, s[24:25]
	s_mov_b32 m0, s68
	s_addc_u32 s3, s51, 0
	global_load_lds_dwordx4 v[2:3], off
	s_add_i32 m0, s60, 0x1c000
	global_load_lds_dwordx4 v0, s[2:3]
	v_lshl_add_u64 v[2:3], s[2:3], 0, v[130:131]
	s_add_i32 m0, s60, 0x1e000
	v_bfe_u32 v140, v10, 4, 2
	global_load_lds_dwordx4 v[2:3], off
	v_and_b32_e32 v141, 15, v10
	v_lshlrev_b32_e32 v2, 4, v140
	v_lshlrev_b32_e32 v3, 2, v10
	v_lshl_or_b32 v2, v141, 6, v2
	v_and_b32_e32 v3, 32, v3
	v_bitop3_b32 v4, v2, s4, v3 bitop3:0xde
	v_bitop3_b32 v142, v2, s5, v3 bitop3:0xde
	v_lshlrev_b32_e32 v2, 14, v11
	v_and_b32_e32 v2, 0xffff8000, v2
	v_lshl_add_u32 v2, v12, 11, v2
	v_and_b32_e32 v3, 1, v11
	v_lshl_or_b32 v2, v3, 6, v2
	v_lshl_add_u32 v132, v13, 1, v2
	v_lshlrev_b32_e32 v2, 14, v14
	v_and_b32_e32 v2, 0xffff8000, v2
	s_waitcnt vmcnt(6)
	v_lshl_add_u32 v2, v15, 11, v2
	v_and_b32_e32 v3, 1, v14
	s_cmpk_lt_u32 s18, 0x100
	v_lshl_or_b32 v2, v3, 6, v2
	s_cselect_b64 s[18:19], -1, 0
	s_ashr_i32 s69, s57, 31
	s_ashr_i32 s70, s58, 31
	v_mov_b32_e32 v133, v1
	v_lshl_add_u32 v134, v16, 1, v2
	v_mov_b32_e32 v135, v1
	s_mov_b32 s71, 0
	v_add_u32_e32 v143, 0, v4
	s_barrier
	s_branch .LBB0_1871

.LBB0_1880:
	s_add_u32 s20, s4, 0xfffc0080
	s_addc_u32 s21, s5, -1
	s_add_i32 s37, 0, 0x10000
	s_cmp_eq_u32 s85, 12
	s_cselect_b32 s53, s45, s21
	s_cselect_b32 s52, s44, s20
	s_cselect_b32 s51, s43, s81
	s_cselect_b32 s50, s49, s73
	s_add_i32 s77, 0, 0x14000
	v_add_u32_e32 v152, s37, v142
	v_add_u32_e32 v168, s77, v142
	ds_read_b128 v[136:139], v152
	ds_read_b128 v[144:147], v152 offset:1024
	ds_read_b128 v[148:151], v152 offset:2048
	ds_read_b128 v[152:155], v152 offset:3072
	ds_read_b128 v[156:159], v168
	ds_read_b128 v[160:163], v168 offset:1024
	ds_read_b128 v[164:167], v168 offset:2048
	ds_read_b128 v[168:171], v168 offset:3072
	s_add_i32 m0, s60, 0xc000
	ds_read_b128 v[172:175], v143
	ds_read_b128 v[176:179], v143 offset:1024
	ds_read_b128 v[180:183], v143 offset:2048
	ds_read_b128 v[184:187], v143 offset:3072
	ds_read_b128 v[188:191], v143 offset:4096
	ds_read_b128 v[192:195], v143 offset:5120
	ds_read_b128 v[196:199], v143 offset:6144
	ds_read_b128 v[200:203], v143 offset:7168
	global_load_lds_dwordx4 v132, s[4:5]
	s_add_i32 m0, s60, 0xe000
	s_nop 0
	global_load_lds_dwordx4 v134, s[4:5]
	s_waitcnt vmcnt(8)
	s_waitcnt lgkmcnt(0)
	s_barrier
	s_waitcnt lgkmcnt(0)
	v_mfma_f32_16x16x32_bf16 v[126:129], v[136:139], v[172:175], v[126:129]
	v_mfma_f32_16x16x32_bf16 v[122:125], v[148:151], v[172:175], v[122:125]
	v_mfma_f32_16x16x32_bf16 v[110:113], v[136:139], v[180:183], v[110:113]
	v_mfma_f32_16x16x32_bf16 v[106:109], v[148:151], v[180:183], v[106:109]
	v_mfma_f32_16x16x32_bf16 v[94:97], v[136:139], v[188:191], v[94:97]
	v_mfma_f32_16x16x32_bf16 v[90:93], v[148:151], v[188:191], v[90:93]
	v_mfma_f32_16x16x32_bf16 v[78:81], v[136:139], v[196:199], v[78:81]
	v_mfma_f32_16x16x32_bf16 v[74:77], v[148:151], v[196:199], v[74:77]
	v_mfma_f32_16x16x32_bf16 v[126:129], v[144:147], v[176:179], v[126:129]
	v_mfma_f32_16x16x32_bf16 v[122:125], v[152:155], v[176:179], v[122:125]
	v_mfma_f32_16x16x32_bf16 v[110:113], v[144:147], v[184:187], v[110:113]
	v_mfma_f32_16x16x32_bf16 v[106:109], v[152:155], v[184:187], v[106:109]
	v_mfma_f32_16x16x32_bf16 v[94:97], v[144:147], v[192:195], v[94:97]
	v_mfma_f32_16x16x32_bf16 v[90:93], v[152:155], v[192:195], v[90:93]
	v_mfma_f32_16x16x32_bf16 v[78:81], v[144:147], v[200:203], v[78:81]
	v_mfma_f32_16x16x32_bf16 v[74:77], v[152:155], v[200:203], v[74:77]
	v_mfma_f32_16x16x32_bf16 v[118:121], v[156:159], v[172:175], v[118:121]
	v_mfma_f32_16x16x32_bf16 v[114:117], v[164:167], v[172:175], v[114:117]
	v_mfma_f32_16x16x32_bf16 v[102:105], v[156:159], v[180:183], v[102:105]
	v_mfma_f32_16x16x32_bf16 v[98:101], v[164:167], v[180:183], v[98:101]
	v_mfma_f32_16x16x32_bf16 v[86:89], v[156:159], v[188:191], v[86:89]
	v_mfma_f32_16x16x32_bf16 v[82:85], v[164:167], v[188:191], v[82:85]
	v_mfma_f32_16x16x32_bf16 v[70:73], v[156:159], v[196:199], v[70:73]
	v_mfma_f32_16x16x32_bf16 v[66:69], v[164:167], v[196:199], v[66:69]
	v_mfma_f32_16x16x32_bf16 v[118:121], v[160:163], v[176:179], v[118:121]
	v_mfma_f32_16x16x32_bf16 v[114:117], v[168:171], v[176:179], v[114:117]
	v_mfma_f32_16x16x32_bf16 v[102:105], v[160:163], v[184:187], v[102:105]
	v_mfma_f32_16x16x32_bf16 v[98:101], v[168:171], v[184:187], v[98:101]
	v_mfma_f32_16x16x32_bf16 v[86:89], v[160:163], v[192:195], v[86:89]
	v_mfma_f32_16x16x32_bf16 v[82:85], v[168:171], v[192:195], v[82:85]
	v_mfma_f32_16x16x32_bf16 v[70:73], v[160:163], v[200:203], v[70:73]
	v_mfma_f32_16x16x32_bf16 v[66:69], v[168:171], v[200:203], v[66:69]
	s_barrier
	s_add_i32 s20, s37, s59
	v_lshl_add_u64 v[204:205], s[50:51], 0, v[0:1]
	s_mov_b32 m0, s20
	ds_read_b128 v[172:175], v143 offset:16384
	ds_read_b128 v[176:179], v143 offset:17408
	ds_read_b128 v[180:183], v143 offset:18432
	ds_read_b128 v[184:187], v143 offset:19456
	ds_read_b128 v[188:191], v143 offset:20480
	ds_read_b128 v[192:195], v143 offset:21504
	ds_read_b128 v[196:199], v143 offset:22528
	ds_read_b128 v[200:203], v143 offset:23552
	global_load_lds_dwordx4 v[204:205], off
	s_add_i32 m0, s20, 0x2000
	s_add_u32 s20, s50, 0x40000
	v_lshl_add_u64 v[206:207], s[50:51], 0, v[130:131]
	s_addc_u32 s21, s51, 0
	s_add_i32 s37, s77, s59
	global_load_lds_dwordx4 v[206:207], off
	s_mov_b32 m0, s37
	v_lshl_add_u64 v[210:211], s[52:53], 0, v[130:131]
	global_load_lds_dwordx4 v0, s[20:21]
	s_add_i32 m0, s37, 0x2000
	s_nop 0
	global_load_lds_dwordx4 v130, s[20:21]
	v_lshl_add_u64 v[208:209], s[52:53], 0, v[0:1]
	s_mov_b32 m0, s60
	s_nop 0
	global_load_lds_dwordx4 v[208:209], off
	s_mov_b32 m0, s61
	s_nop 0
	global_load_lds_dwordx4 v[210:211], off
	s_waitcnt vmcnt(8)
	s_waitcnt lgkmcnt(0)
	s_barrier
	s_waitcnt lgkmcnt(0)
	v_mfma_f32_16x16x32_bf16 v[62:65], v[136:139], v[172:175], v[62:65]
	v_mfma_f32_16x16x32_bf16 v[58:61], v[148:151], v[172:175], v[58:61]
	v_mfma_f32_16x16x32_bf16 v[46:49], v[136:139], v[180:183], v[46:49]
	v_mfma_f32_16x16x32_bf16 v[42:45], v[148:151], v[180:183], v[42:45]
	v_mfma_f32_16x16x32_bf16 v[30:33], v[136:139], v[188:191], v[30:33]
	v_mfma_f32_16x16x32_bf16 v[26:29], v[148:151], v[188:191], v[26:29]
	v_mfma_f32_16x16x32_bf16 v[14:17], v[136:139], v[196:199], v[14:17]
	v_mfma_f32_16x16x32_bf16 v[10:13], v[148:151], v[196:199], v[10:13]
	v_mfma_f32_16x16x32_bf16 v[62:65], v[144:147], v[176:179], v[62:65]
	v_mfma_f32_16x16x32_bf16 v[58:61], v[152:155], v[176:179], v[58:61]
	v_mfma_f32_16x16x32_bf16 v[46:49], v[144:147], v[184:187], v[46:49]
	v_mfma_f32_16x16x32_bf16 v[42:45], v[152:155], v[184:187], v[42:45]
	v_mfma_f32_16x16x32_bf16 v[30:33], v[144:147], v[192:195], v[30:33]
	v_mfma_f32_16x16x32_bf16 v[26:29], v[152:155], v[192:195], v[26:29]
	v_mfma_f32_16x16x32_bf16 v[14:17], v[144:147], v[200:203], v[14:17]
	v_mfma_f32_16x16x32_bf16 v[10:13], v[152:155], v[200:203], v[10:13]
	v_mfma_f32_16x16x32_bf16 v[54:57], v[156:159], v[172:175], v[54:57]
	v_mfma_f32_16x16x32_bf16 v[50:53], v[164:167], v[172:175], v[50:53]
	v_mfma_f32_16x16x32_bf16 v[38:41], v[156:159], v[180:183], v[38:41]
	v_mfma_f32_16x16x32_bf16 v[34:37], v[164:167], v[180:183], v[34:37]
	v_mfma_f32_16x16x32_bf16 v[22:25], v[156:159], v[188:191], v[22:25]
	v_mfma_f32_16x16x32_bf16 v[18:21], v[164:167], v[188:191], v[18:21]
	v_mfma_f32_16x16x32_bf16 v[6:9], v[156:159], v[196:199], v[6:9]
	v_mfma_f32_16x16x32_bf16 v[2:5], v[164:167], v[196:199], v[2:5]
	v_mfma_f32_16x16x32_bf16 v[54:57], v[160:163], v[176:179], v[54:57]
	v_mfma_f32_16x16x32_bf16 v[50:53], v[168:171], v[176:179], v[50:53]
	v_mfma_f32_16x16x32_bf16 v[38:41], v[160:163], v[184:187], v[38:41]
	v_mfma_f32_16x16x32_bf16 v[34:37], v[168:171], v[184:187], v[34:37]
	v_mfma_f32_16x16x32_bf16 v[22:25], v[160:163], v[192:195], v[22:25]
	v_mfma_f32_16x16x32_bf16 v[18:21], v[168:171], v[192:195], v[18:21]
	v_mfma_f32_16x16x32_bf16 v[6:9], v[160:163], v[200:203], v[6:9]
	v_mfma_f32_16x16x32_bf16 v[2:5], v[168:171], v[200:203], v[2:5]
	s_barrier
	s_add_i32 s37, 0, 0x18000
	s_add_i32 s77, 0, 0x1c000
	v_add_u32_e32 v152, s37, v142
	v_add_u32_e32 v168, s77, v142
	ds_read_b128 v[136:139], v152
	ds_read_b128 v[144:147], v152 offset:1024
	ds_read_b128 v[148:151], v152 offset:2048
	ds_read_b128 v[152:155], v152 offset:3072
	ds_read_b128 v[156:159], v168
	ds_read_b128 v[160:163], v168 offset:1024
	ds_read_b128 v[164:167], v168 offset:2048
	ds_read_b128 v[168:171], v168 offset:3072
	s_add_u32 s20, s52, 0x40000
	s_addc_u32 s21, s53, 0
	s_mov_b32 m0, s62
	ds_read_b128 v[172:175], v143 offset:32768
	ds_read_b128 v[176:179], v143 offset:33792
	ds_read_b128 v[180:183], v143 offset:34816
	ds_read_b128 v[184:187], v143 offset:35840
	ds_read_b128 v[188:191], v143 offset:36864
	ds_read_b128 v[192:195], v143 offset:37888
	ds_read_b128 v[196:199], v143 offset:38912
	ds_read_b128 v[200:203], v143 offset:39936
	global_load_lds_dwordx4 v0, s[20:21]
	v_lshl_add_u64 v[214:215], s[20:21], 0, v[130:131]
	s_mov_b32 m0, s63
	s_nop 0
	global_load_lds_dwordx4 v[214:215], off
	s_waitcnt vmcnt(8)
	s_waitcnt lgkmcnt(0)
	s_barrier
	s_waitcnt lgkmcnt(0)
	v_mfma_f32_16x16x32_bf16 v[126:129], v[136:139], v[172:175], v[126:129]
	v_mfma_f32_16x16x32_bf16 v[122:125], v[148:151], v[172:175], v[122:125]
	v_mfma_f32_16x16x32_bf16 v[110:113], v[136:139], v[180:183], v[110:113]
	v_mfma_f32_16x16x32_bf16 v[106:109], v[148:151], v[180:183], v[106:109]
	v_mfma_f32_16x16x32_bf16 v[94:97], v[136:139], v[188:191], v[94:97]
	v_mfma_f32_16x16x32_bf16 v[90:93], v[148:151], v[188:191], v[90:93]
	v_mfma_f32_16x16x32_bf16 v[78:81], v[136:139], v[196:199], v[78:81]
	v_mfma_f32_16x16x32_bf16 v[74:77], v[148:151], v[196:199], v[74:77]
	v_mfma_f32_16x16x32_bf16 v[126:129], v[144:147], v[176:179], v[126:129]
	v_mfma_f32_16x16x32_bf16 v[122:125], v[152:155], v[176:179], v[122:125]
	v_mfma_f32_16x16x32_bf16 v[110:113], v[144:147], v[184:187], v[110:113]
	v_mfma_f32_16x16x32_bf16 v[106:109], v[152:155], v[184:187], v[106:109]
	v_mfma_f32_16x16x32_bf16 v[94:97], v[144:147], v[192:195], v[94:97]
	v_mfma_f32_16x16x32_bf16 v[90:93], v[152:155], v[192:195], v[90:93]
	v_mfma_f32_16x16x32_bf16 v[78:81], v[144:147], v[200:203], v[78:81]
	v_mfma_f32_16x16x32_bf16 v[74:77], v[152:155], v[200:203], v[74:77]
	v_mfma_f32_16x16x32_bf16 v[118:121], v[156:159], v[172:175], v[118:121]
	v_mfma_f32_16x16x32_bf16 v[114:117], v[164:167], v[172:175], v[114:117]
	v_mfma_f32_16x16x32_bf16 v[102:105], v[156:159], v[180:183], v[102:105]
	v_mfma_f32_16x16x32_bf16 v[98:101], v[164:167], v[180:183], v[98:101]
	v_mfma_f32_16x16x32_bf16 v[86:89], v[156:159], v[188:191], v[86:89]
	v_mfma_f32_16x16x32_bf16 v[82:85], v[164:167], v[188:191], v[82:85]
	v_mfma_f32_16x16x32_bf16 v[70:73], v[156:159], v[196:199], v[70:73]
	v_mfma_f32_16x16x32_bf16 v[66:69], v[164:167], v[196:199], v[66:69]
	v_mfma_f32_16x16x32_bf16 v[118:121], v[160:163], v[176:179], v[118:121]
	v_mfma_f32_16x16x32_bf16 v[114:117], v[168:171], v[176:179], v[114:117]
	v_mfma_f32_16x16x32_bf16 v[102:105], v[160:163], v[184:187], v[102:105]
	v_mfma_f32_16x16x32_bf16 v[98:101], v[168:171], v[184:187], v[98:101]
	v_mfma_f32_16x16x32_bf16 v[86:89], v[160:163], v[192:195], v[86:89]
	v_mfma_f32_16x16x32_bf16 v[82:85], v[168:171], v[192:195], v[82:85]
	v_mfma_f32_16x16x32_bf16 v[70:73], v[160:163], v[200:203], v[70:73]
	v_mfma_f32_16x16x32_bf16 v[66:69], v[168:171], v[200:203], v[66:69]
	s_barrier
	s_add_i32 s20, s37, s59
	v_lshl_add_u64 v[204:205], v[204:205], 0, s[24:25]
	s_mov_b32 m0, s20
	ds_read_b128 v[172:175], v143 offset:49152
	ds_read_b128 v[176:179], v143 offset:50176
	ds_read_b128 v[180:183], v143 offset:51200
	ds_read_b128 v[184:187], v143 offset:52224
	ds_read_b128 v[188:191], v143 offset:53248
	ds_read_b128 v[192:195], v143 offset:54272
	ds_read_b128 v[196:199], v143 offset:55296
	ds_read_b128 v[200:203], v143 offset:56320
	global_load_lds_dwordx4 v[204:205], off
	s_add_i32 m0, s20, 0x2000
	s_add_u32 s20, s50, 0x40080
	v_lshl_add_u64 v[204:205], v[206:207], 0, s[24:25]
	s_addc_u32 s21, s51, 0
	s_add_i32 s37, s77, s59
	global_load_lds_dwordx4 v[204:205], off
	s_mov_b32 m0, s37
	s_nop 0
	global_load_lds_dwordx4 v0, s[20:21]
	s_add_i32 m0, s37, 0x2000
	s_nop 0
	global_load_lds_dwordx4 v130, s[20:21]
	v_lshl_add_u64 v[204:205], v[208:209], 0, s[24:25]
	s_mov_b32 m0, s67
	s_nop 0
	global_load_lds_dwordx4 v[204:205], off
	v_lshl_add_u64 v[204:205], v[210:211], 0, s[24:25]
	s_mov_b32 m0, s68
	s_nop 0
	global_load_lds_dwordx4 v[204:205], off
	s_waitcnt vmcnt(8)
	s_waitcnt lgkmcnt(0)
	s_barrier
	s_waitcnt lgkmcnt(0)
	v_mfma_f32_16x16x32_bf16 v[62:65], v[136:139], v[172:175], v[62:65]
	v_mfma_f32_16x16x32_bf16 v[58:61], v[148:151], v[172:175], v[58:61]
	v_mfma_f32_16x16x32_bf16 v[46:49], v[136:139], v[180:183], v[46:49]
	v_mfma_f32_16x16x32_bf16 v[42:45], v[148:151], v[180:183], v[42:45]
	v_mfma_f32_16x16x32_bf16 v[30:33], v[136:139], v[188:191], v[30:33]
	v_mfma_f32_16x16x32_bf16 v[26:29], v[148:151], v[188:191], v[26:29]
	v_mfma_f32_16x16x32_bf16 v[14:17], v[136:139], v[196:199], v[14:17]
	v_mfma_f32_16x16x32_bf16 v[10:13], v[148:151], v[196:199], v[10:13]
	v_mfma_f32_16x16x32_bf16 v[62:65], v[144:147], v[176:179], v[62:65]
	v_mfma_f32_16x16x32_bf16 v[58:61], v[152:155], v[176:179], v[58:61]
	v_mfma_f32_16x16x32_bf16 v[46:49], v[144:147], v[184:187], v[46:49]
	v_mfma_f32_16x16x32_bf16 v[42:45], v[152:155], v[184:187], v[42:45]
	v_mfma_f32_16x16x32_bf16 v[30:33], v[144:147], v[192:195], v[30:33]
	v_mfma_f32_16x16x32_bf16 v[26:29], v[152:155], v[192:195], v[26:29]
	v_mfma_f32_16x16x32_bf16 v[14:17], v[144:147], v[200:203], v[14:17]
	v_mfma_f32_16x16x32_bf16 v[10:13], v[152:155], v[200:203], v[10:13]
	v_mfma_f32_16x16x32_bf16 v[54:57], v[156:159], v[172:175], v[54:57]
	v_mfma_f32_16x16x32_bf16 v[50:53], v[164:167], v[172:175], v[50:53]
	v_mfma_f32_16x16x32_bf16 v[38:41], v[156:159], v[180:183], v[38:41]
	v_mfma_f32_16x16x32_bf16 v[34:37], v[164:167], v[180:183], v[34:37]
	v_mfma_f32_16x16x32_bf16 v[22:25], v[156:159], v[188:191], v[22:25]
	v_mfma_f32_16x16x32_bf16 v[18:21], v[164:167], v[188:191], v[18:21]
	v_mfma_f32_16x16x32_bf16 v[6:9], v[156:159], v[196:199], v[6:9]
	v_mfma_f32_16x16x32_bf16 v[2:5], v[164:167], v[196:199], v[2:5]
	v_mfma_f32_16x16x32_bf16 v[54:57], v[160:163], v[176:179], v[54:57]
	v_mfma_f32_16x16x32_bf16 v[50:53], v[168:171], v[176:179], v[50:53]
	v_mfma_f32_16x16x32_bf16 v[38:41], v[160:163], v[184:187], v[38:41]
	v_mfma_f32_16x16x32_bf16 v[34:37], v[168:171], v[184:187], v[34:37]
	v_mfma_f32_16x16x32_bf16 v[22:25], v[160:163], v[192:195], v[22:25]
	v_mfma_f32_16x16x32_bf16 v[18:21], v[168:171], v[192:195], v[18:21]
	v_mfma_f32_16x16x32_bf16 v[6:9], v[160:163], v[200:203], v[6:9]
	v_mfma_f32_16x16x32_bf16 v[2:5], v[168:171], v[200:203], v[2:5]
	s_barrier
	s_add_i32 s85, s85, 2
	s_add_u32 s4, s4, 0x100
	s_addc_u32 s5, s5, 0
	s_add_u32 s73, s73, 0x100
	s_addc_u32 s81, s81, 0
	s_cmp_gt_u32 s85, 13
	s_cbranch_scc0 .LBB0_1880
	s_and_b64 vcc, exec, s[18:19]
	s_cbranch_vccz .LBB0_1883
	s_barrier

.LBB0_1958:
	s_add_u32 s6, s6, 0x18000000
	s_addc_u32 s7, s7, 0
	s_lshl_b32 s2, s2, 5
	s_and_b32 s2, s2, 0x60
	s_add_i32 m0, s67, 0x18000
	v_lshl_add_u64 v[8:9], v[8:9], 0, s[24:25]
	s_lshl_b32 s13, s3, 13
	s_lshl_b32 s16, s2, 7
	s_waitcnt vmcnt(2)
	s_barrier
	global_load_lds_dwordx4 v[8:9], off
	v_lshl_add_u64 v[6:7], v[6:7], 0, s[24:25]
	s_add_i32 m0, s67, 0x1a000
	s_add_i32 s71, s67, 0x8000
	s_add_i32 s72, s67, 0xa000
	global_load_lds_dwordx4 v[6:7], off
	v_lshl_add_u64 v[2:3], v[2:3], 0, s[24:25]
	s_mov_b32 m0, s71
	s_add_u32 s4, s46, 0x40080
	global_load_lds_dwordx4 v[2:3], off
	v_lshl_add_u64 v[2:3], v[4:5], 0, s[24:25]
	s_mov_b32 m0, s72
	s_addc_u32 s5, s47, 0
	global_load_lds_dwordx4 v[2:3], off
	s_add_i32 m0, s67, 0x1c000
	global_load_lds_dwordx4 v0, s[4:5]
	v_lshl_add_u64 v[2:3], s[4:5], 0, v[134:135]
	s_add_i32 m0, s67, 0x1e000
	s_cmpk_lt_u32 s12, 0x100
	global_load_lds_dwordx4 v[2:3], off
	v_lshrrev_b32_e32 v3, 1, v10
	v_and_b32_e32 v3, 24, v3
	v_and_b32_e32 v2, 15, v10
	v_lshlrev_b32_e32 v4, 1, v3
	v_lshl_or_b32 v140, s3, 6, v2
	v_lshl_or_b32 v2, v2, 6, v4
	v_lshlrev_b32_e32 v4, 2, v10
	v_and_b32_e32 v4, 32, v4
	s_waitcnt vmcnt(6)
	v_bitop3_b32 v5, v2, s13, v4 bitop3:0xde
	v_bitop3_b32 v141, v2, s16, v4 bitop3:0xde
	s_cselect_b64 s[12:13], -1, 0
	s_ashr_i32 s73, s22, 31
	s_ashr_i32 s81, s41, 31
	v_or_b32_e32 v142, s2, v3
	s_mov_b32 s85, 0
	v_add_u32_e32 v143, 0, v5
	s_barrier
	s_branch .LBB0_1961

.LBB0_1972:
	s_add_u32 s37, s48, s17
	s_addc_u32 s45, s49, 0
	s_add_u32 s52, s37, 0x100
	s_addc_u32 s53, s45, 0
	s_and_b64 s[20:21], s[50:51], exec
	s_cselect_b32 s55, s19, s53
	s_cselect_b32 s54, s18, s52
	s_add_u32 s17, s46, s17
	s_addc_u32 s20, s47, 0
	s_add_u32 s17, s17, 0x100
	s_addc_u32 s52, s20, 0
	s_add_i32 s78, 0, 0x10000
	s_and_b64 s[20:21], s[50:51], exec
	s_cselect_b32 s57, s43, s52
	s_cselect_b32 s56, s42, s17
	s_add_i32 s20, 0, 0x14000
	s_add_u32 s60, s37, 0x80080
	s_addc_u32 s61, s45, 0
	s_add_i32 s77, s78, s66
	s_add_i32 m0, s67, 0xc000
	s_add_i32 s21, s67, 0xe000
	s_add_i32 s37, s77, 0x2000
	s_add_u32 s58, s56, 0x40000
	v_add_u32_e32 v152, s78, v141
	v_add_u32_e32 v168, s20, v141
	s_addc_u32 s59, s57, 0
	s_add_i32 s83, s20, s66
	ds_read_b128 v[136:139], v152
	ds_read_b128 v[144:147], v152 offset:1024
	ds_read_b128 v[148:151], v152 offset:2048
	ds_read_b128 v[152:155], v152 offset:3072
	ds_read_b128 v[156:159], v168
	ds_read_b128 v[160:163], v168 offset:1024
	ds_read_b128 v[164:167], v168 offset:2048
	ds_read_b128 v[168:171], v168 offset:3072
	s_add_i32 s82, s83, 0x2000
	s_add_i32 s92, 0, 0x18000
	s_add_i32 s88, 0, 0x1c000
	s_add_u32 s52, s54, 0x80000
	s_addc_u32 s53, s55, 0
	s_add_i32 s45, s92, s66
	s_add_i32 s17, s45, 0x2000
	s_add_u32 s50, s56, 0x40080
	s_addc_u32 s51, s57, 0
	s_add_i32 s20, s88, s66
	s_add_i32 s78, s20, 0x2000
	ds_read_b128 v[172:175], v143
	ds_read_b128 v[176:179], v143 offset:1024
	ds_read_b128 v[180:183], v143 offset:2048
	ds_read_b128 v[184:187], v143 offset:3072
	ds_read_b128 v[188:191], v143 offset:4096
	ds_read_b128 v[192:195], v143 offset:5120
	ds_read_b128 v[196:199], v143 offset:6144
	ds_read_b128 v[200:203], v143 offset:7168
	global_load_lds_dwordx4 v130, s[60:61]
	s_mov_b32 m0, s21
	s_nop 0
	global_load_lds_dwordx4 v132, s[60:61]
	s_waitcnt vmcnt(8)
	s_waitcnt lgkmcnt(0)
	s_barrier
	s_waitcnt lgkmcnt(0)
	v_mfma_f32_16x16x32_bf16 v[126:129], v[136:139], v[172:175], v[126:129]
	v_mfma_f32_16x16x32_bf16 v[122:125], v[148:151], v[172:175], v[122:125]
	v_mfma_f32_16x16x32_bf16 v[114:117], v[136:139], v[180:183], v[114:117]
	v_mfma_f32_16x16x32_bf16 v[106:109], v[148:151], v[180:183], v[106:109]
	v_mfma_f32_16x16x32_bf16 v[98:101], v[136:139], v[188:191], v[98:101]
	v_mfma_f32_16x16x32_bf16 v[90:93], v[148:151], v[188:191], v[90:93]
	v_mfma_f32_16x16x32_bf16 v[82:85], v[136:139], v[196:199], v[82:85]
	v_mfma_f32_16x16x32_bf16 v[74:77], v[148:151], v[196:199], v[74:77]
	v_mfma_f32_16x16x32_bf16 v[126:129], v[144:147], v[176:179], v[126:129]
	v_mfma_f32_16x16x32_bf16 v[122:125], v[152:155], v[176:179], v[122:125]
	v_mfma_f32_16x16x32_bf16 v[114:117], v[144:147], v[184:187], v[114:117]
	v_mfma_f32_16x16x32_bf16 v[106:109], v[152:155], v[184:187], v[106:109]
	v_mfma_f32_16x16x32_bf16 v[98:101], v[144:147], v[192:195], v[98:101]
	v_mfma_f32_16x16x32_bf16 v[90:93], v[152:155], v[192:195], v[90:93]
	v_mfma_f32_16x16x32_bf16 v[82:85], v[144:147], v[200:203], v[82:85]
	v_mfma_f32_16x16x32_bf16 v[74:77], v[152:155], v[200:203], v[74:77]
	v_mfma_f32_16x16x32_bf16 v[118:121], v[156:159], v[172:175], v[118:121]
	v_mfma_f32_16x16x32_bf16 v[110:113], v[164:167], v[172:175], v[110:113]
	v_mfma_f32_16x16x32_bf16 v[102:105], v[156:159], v[180:183], v[102:105]
	v_mfma_f32_16x16x32_bf16 v[94:97], v[164:167], v[180:183], v[94:97]
	v_mfma_f32_16x16x32_bf16 v[86:89], v[156:159], v[188:191], v[86:89]
	v_mfma_f32_16x16x32_bf16 v[78:81], v[164:167], v[188:191], v[78:81]
	v_mfma_f32_16x16x32_bf16 v[70:73], v[156:159], v[196:199], v[70:73]
	v_mfma_f32_16x16x32_bf16 v[66:69], v[164:167], v[196:199], v[66:69]
	v_mfma_f32_16x16x32_bf16 v[118:121], v[160:163], v[176:179], v[118:121]
	v_mfma_f32_16x16x32_bf16 v[110:113], v[168:171], v[176:179], v[110:113]
	v_mfma_f32_16x16x32_bf16 v[102:105], v[160:163], v[184:187], v[102:105]
	v_mfma_f32_16x16x32_bf16 v[94:97], v[168:171], v[184:187], v[94:97]
	v_mfma_f32_16x16x32_bf16 v[86:89], v[160:163], v[192:195], v[86:89]
	v_mfma_f32_16x16x32_bf16 v[78:81], v[168:171], v[192:195], v[78:81]
	v_mfma_f32_16x16x32_bf16 v[70:73], v[160:163], v[200:203], v[70:73]
	v_mfma_f32_16x16x32_bf16 v[66:69], v[168:171], v[200:203], v[66:69]
	s_barrier
	s_mov_b32 m0, s77
	v_lshl_add_u64 v[204:205], s[56:57], 0, v[0:1]
	ds_read_b128 v[172:175], v143 offset:16384
	ds_read_b128 v[176:179], v143 offset:17408
	ds_read_b128 v[180:183], v143 offset:18432
	ds_read_b128 v[184:187], v143 offset:19456
	ds_read_b128 v[188:191], v143 offset:20480
	ds_read_b128 v[192:195], v143 offset:21504
	ds_read_b128 v[196:199], v143 offset:22528
	ds_read_b128 v[200:203], v143 offset:23552
	global_load_lds_dwordx4 v[204:205], off
	v_lshl_add_u64 v[206:207], s[56:57], 0, v[134:135]
	s_mov_b32 m0, s37
	global_load_lds_dwordx4 v[206:207], off
	s_mov_b32 m0, s83
	v_lshl_add_u64 v[210:211], s[54:55], 0, v[132:133]
	global_load_lds_dwordx4 v0, s[58:59]
	s_mov_b32 m0, s82
	s_nop 0
	global_load_lds_dwordx4 v134, s[58:59]
	v_lshl_add_u64 v[208:209], s[54:55], 0, v[130:131]
	s_mov_b32 m0, s67
	s_nop 0
	global_load_lds_dwordx4 v[208:209], off
	s_mov_b32 m0, s68
	s_nop 0
	global_load_lds_dwordx4 v[210:211], off
	s_waitcnt vmcnt(8)
	s_waitcnt lgkmcnt(0)
	s_barrier
	s_waitcnt lgkmcnt(0)
	v_mfma_f32_16x16x32_bf16 v[62:65], v[136:139], v[172:175], v[62:65]
	v_mfma_f32_16x16x32_bf16 v[58:61], v[148:151], v[172:175], v[58:61]
	v_mfma_f32_16x16x32_bf16 v[50:53], v[136:139], v[180:183], v[50:53]
	v_mfma_f32_16x16x32_bf16 v[42:45], v[148:151], v[180:183], v[42:45]
	v_mfma_f32_16x16x32_bf16 v[34:37], v[136:139], v[188:191], v[34:37]
	v_mfma_f32_16x16x32_bf16 v[26:29], v[148:151], v[188:191], v[26:29]
	v_mfma_f32_16x16x32_bf16 v[18:21], v[136:139], v[196:199], v[18:21]
	v_mfma_f32_16x16x32_bf16 v[10:13], v[148:151], v[196:199], v[10:13]
	v_mfma_f32_16x16x32_bf16 v[62:65], v[144:147], v[176:179], v[62:65]
	v_mfma_f32_16x16x32_bf16 v[58:61], v[152:155], v[176:179], v[58:61]
	v_mfma_f32_16x16x32_bf16 v[50:53], v[144:147], v[184:187], v[50:53]
	v_mfma_f32_16x16x32_bf16 v[42:45], v[152:155], v[184:187], v[42:45]
	v_mfma_f32_16x16x32_bf16 v[34:37], v[144:147], v[192:195], v[34:37]
	v_mfma_f32_16x16x32_bf16 v[26:29], v[152:155], v[192:195], v[26:29]
	v_mfma_f32_16x16x32_bf16 v[18:21], v[144:147], v[200:203], v[18:21]
	v_mfma_f32_16x16x32_bf16 v[10:13], v[152:155], v[200:203], v[10:13]
	v_mfma_f32_16x16x32_bf16 v[54:57], v[156:159], v[172:175], v[54:57]
	v_mfma_f32_16x16x32_bf16 v[46:49], v[164:167], v[172:175], v[46:49]
	v_mfma_f32_16x16x32_bf16 v[38:41], v[156:159], v[180:183], v[38:41]
	v_mfma_f32_16x16x32_bf16 v[30:33], v[164:167], v[180:183], v[30:33]
	v_mfma_f32_16x16x32_bf16 v[22:25], v[156:159], v[188:191], v[22:25]
	v_mfma_f32_16x16x32_bf16 v[14:17], v[164:167], v[188:191], v[14:17]
	v_mfma_f32_16x16x32_bf16 v[6:9], v[156:159], v[196:199], v[6:9]
	v_mfma_f32_16x16x32_bf16 v[2:5], v[164:167], v[196:199], v[2:5]
	v_mfma_f32_16x16x32_bf16 v[54:57], v[160:163], v[176:179], v[54:57]
	v_mfma_f32_16x16x32_bf16 v[46:49], v[168:171], v[176:179], v[46:49]
	v_mfma_f32_16x16x32_bf16 v[38:41], v[160:163], v[184:187], v[38:41]
	v_mfma_f32_16x16x32_bf16 v[30:33], v[168:171], v[184:187], v[30:33]
	v_mfma_f32_16x16x32_bf16 v[22:25], v[160:163], v[192:195], v[22:25]
	v_mfma_f32_16x16x32_bf16 v[14:17], v[168:171], v[192:195], v[14:17]
	v_mfma_f32_16x16x32_bf16 v[6:9], v[160:163], v[200:203], v[6:9]
	v_mfma_f32_16x16x32_bf16 v[2:5], v[168:171], v[200:203], v[2:5]
	s_barrier
	v_add_u32_e32 v152, s92, v141
	v_add_u32_e32 v168, s88, v141
	ds_read_b128 v[136:139], v152
	ds_read_b128 v[144:147], v152 offset:1024
	ds_read_b128 v[148:151], v152 offset:2048
	ds_read_b128 v[152:155], v152 offset:3072
	ds_read_b128 v[156:159], v168
	ds_read_b128 v[160:163], v168 offset:1024
	ds_read_b128 v[164:167], v168 offset:2048
	ds_read_b128 v[168:171], v168 offset:3072
	s_mov_b32 m0, s69
	ds_read_b128 v[172:175], v143 offset:32768
	ds_read_b128 v[176:179], v143 offset:33792
	ds_read_b128 v[180:183], v143 offset:34816
	ds_read_b128 v[184:187], v143 offset:35840
	ds_read_b128 v[188:191], v143 offset:36864
	ds_read_b128 v[192:195], v143 offset:37888
	ds_read_b128 v[196:199], v143 offset:38912
	ds_read_b128 v[200:203], v143 offset:39936
	global_load_lds_dwordx4 v130, s[52:53]
	v_lshl_add_u64 v[214:215], s[52:53], 0, v[132:133]
	s_mov_b32 m0, s70
	s_nop 0
	global_load_lds_dwordx4 v[214:215], off
	s_waitcnt vmcnt(8)
	s_waitcnt lgkmcnt(0)
	s_barrier
	s_waitcnt lgkmcnt(0)
	v_mfma_f32_16x16x32_bf16 v[126:129], v[136:139], v[172:175], v[126:129]
	v_mfma_f32_16x16x32_bf16 v[122:125], v[148:151], v[172:175], v[122:125]
	v_mfma_f32_16x16x32_bf16 v[114:117], v[136:139], v[180:183], v[114:117]
	v_mfma_f32_16x16x32_bf16 v[106:109], v[148:151], v[180:183], v[106:109]
	v_mfma_f32_16x16x32_bf16 v[98:101], v[136:139], v[188:191], v[98:101]
	v_mfma_f32_16x16x32_bf16 v[90:93], v[148:151], v[188:191], v[90:93]
	v_mfma_f32_16x16x32_bf16 v[82:85], v[136:139], v[196:199], v[82:85]
	v_mfma_f32_16x16x32_bf16 v[74:77], v[148:151], v[196:199], v[74:77]
	v_mfma_f32_16x16x32_bf16 v[126:129], v[144:147], v[176:179], v[126:129]
	v_mfma_f32_16x16x32_bf16 v[122:125], v[152:155], v[176:179], v[122:125]
	v_mfma_f32_16x16x32_bf16 v[114:117], v[144:147], v[184:187], v[114:117]
	v_mfma_f32_16x16x32_bf16 v[106:109], v[152:155], v[184:187], v[106:109]
	v_mfma_f32_16x16x32_bf16 v[98:101], v[144:147], v[192:195], v[98:101]
	v_mfma_f32_16x16x32_bf16 v[90:93], v[152:155], v[192:195], v[90:93]
	v_mfma_f32_16x16x32_bf16 v[82:85], v[144:147], v[200:203], v[82:85]
	v_mfma_f32_16x16x32_bf16 v[74:77], v[152:155], v[200:203], v[74:77]
	v_mfma_f32_16x16x32_bf16 v[118:121], v[156:159], v[172:175], v[118:121]
	v_mfma_f32_16x16x32_bf16 v[110:113], v[164:167], v[172:175], v[110:113]
	v_mfma_f32_16x16x32_bf16 v[102:105], v[156:159], v[180:183], v[102:105]
	v_mfma_f32_16x16x32_bf16 v[94:97], v[164:167], v[180:183], v[94:97]
	v_mfma_f32_16x16x32_bf16 v[86:89], v[156:159], v[188:191], v[86:89]
	v_mfma_f32_16x16x32_bf16 v[78:81], v[164:167], v[188:191], v[78:81]
	v_mfma_f32_16x16x32_bf16 v[70:73], v[156:159], v[196:199], v[70:73]
	v_mfma_f32_16x16x32_bf16 v[66:69], v[164:167], v[196:199], v[66:69]
	v_mfma_f32_16x16x32_bf16 v[118:121], v[160:163], v[176:179], v[118:121]
	v_mfma_f32_16x16x32_bf16 v[110:113], v[168:171], v[176:179], v[110:113]
	v_mfma_f32_16x16x32_bf16 v[102:105], v[160:163], v[184:187], v[102:105]
	v_mfma_f32_16x16x32_bf16 v[94:97], v[168:171], v[184:187], v[94:97]
	v_mfma_f32_16x16x32_bf16 v[86:89], v[160:163], v[192:195], v[86:89]
	v_mfma_f32_16x16x32_bf16 v[78:81], v[168:171], v[192:195], v[78:81]
	v_mfma_f32_16x16x32_bf16 v[70:73], v[160:163], v[200:203], v[70:73]
	v_mfma_f32_16x16x32_bf16 v[66:69], v[168:171], v[200:203], v[66:69]
	s_barrier
	s_mov_b32 m0, s45
	v_lshl_add_u64 v[204:205], v[204:205], 0, s[24:25]
	ds_read_b128 v[172:175], v143 offset:49152
	ds_read_b128 v[176:179], v143 offset:50176
	ds_read_b128 v[180:183], v143 offset:51200
	ds_read_b128 v[184:187], v143 offset:52224
	ds_read_b128 v[188:191], v143 offset:53248
	ds_read_b128 v[192:195], v143 offset:54272
	ds_read_b128 v[196:199], v143 offset:55296
	ds_read_b128 v[200:203], v143 offset:56320
	global_load_lds_dwordx4 v[204:205], off
	v_lshl_add_u64 v[204:205], v[206:207], 0, s[24:25]
	s_mov_b32 m0, s17
	s_nop 0
	global_load_lds_dwordx4 v[204:205], off
	s_mov_b32 m0, s20
	s_nop 0
	global_load_lds_dwordx4 v0, s[50:51]
	s_mov_b32 m0, s78
	s_nop 0
	global_load_lds_dwordx4 v134, s[50:51]
	v_lshl_add_u64 v[204:205], v[208:209], 0, s[24:25]
	s_mov_b32 m0, s71
	s_nop 0
	global_load_lds_dwordx4 v[204:205], off
	v_lshl_add_u64 v[204:205], v[210:211], 0, s[24:25]
	s_mov_b32 m0, s72
	s_nop 0
	global_load_lds_dwordx4 v[204:205], off
	s_waitcnt vmcnt(8)
	s_waitcnt lgkmcnt(0)
	s_barrier
	s_waitcnt lgkmcnt(0)
	v_mfma_f32_16x16x32_bf16 v[62:65], v[136:139], v[172:175], v[62:65]
	v_mfma_f32_16x16x32_bf16 v[58:61], v[148:151], v[172:175], v[58:61]
	v_mfma_f32_16x16x32_bf16 v[50:53], v[136:139], v[180:183], v[50:53]
	v_mfma_f32_16x16x32_bf16 v[42:45], v[148:151], v[180:183], v[42:45]
	v_mfma_f32_16x16x32_bf16 v[34:37], v[136:139], v[188:191], v[34:37]
	v_mfma_f32_16x16x32_bf16 v[26:29], v[148:151], v[188:191], v[26:29]
	v_mfma_f32_16x16x32_bf16 v[18:21], v[136:139], v[196:199], v[18:21]
	v_mfma_f32_16x16x32_bf16 v[10:13], v[148:151], v[196:199], v[10:13]
	v_mfma_f32_16x16x32_bf16 v[62:65], v[144:147], v[176:179], v[62:65]
	v_mfma_f32_16x16x32_bf16 v[58:61], v[152:155], v[176:179], v[58:61]
	v_mfma_f32_16x16x32_bf16 v[50:53], v[144:147], v[184:187], v[50:53]
	v_mfma_f32_16x16x32_bf16 v[42:45], v[152:155], v[184:187], v[42:45]
	v_mfma_f32_16x16x32_bf16 v[34:37], v[144:147], v[192:195], v[34:37]
	v_mfma_f32_16x16x32_bf16 v[26:29], v[152:155], v[192:195], v[26:29]
	v_mfma_f32_16x16x32_bf16 v[18:21], v[144:147], v[200:203], v[18:21]
	v_mfma_f32_16x16x32_bf16 v[10:13], v[152:155], v[200:203], v[10:13]
	v_mfma_f32_16x16x32_bf16 v[54:57], v[156:159], v[172:175], v[54:57]
	v_mfma_f32_16x16x32_bf16 v[46:49], v[164:167], v[172:175], v[46:49]
	v_mfma_f32_16x16x32_bf16 v[38:41], v[156:159], v[180:183], v[38:41]
	v_mfma_f32_16x16x32_bf16 v[30:33], v[164:167], v[180:183], v[30:33]
	v_mfma_f32_16x16x32_bf16 v[22:25], v[156:159], v[188:191], v[22:25]
	v_mfma_f32_16x16x32_bf16 v[14:17], v[164:167], v[188:191], v[14:17]
	v_mfma_f32_16x16x32_bf16 v[6:9], v[156:159], v[196:199], v[6:9]
	v_mfma_f32_16x16x32_bf16 v[2:5], v[164:167], v[196:199], v[2:5]
	v_mfma_f32_16x16x32_bf16 v[54:57], v[160:163], v[176:179], v[54:57]
	v_mfma_f32_16x16x32_bf16 v[46:49], v[168:171], v[176:179], v[46:49]
	v_mfma_f32_16x16x32_bf16 v[38:41], v[160:163], v[184:187], v[38:41]
	v_mfma_f32_16x16x32_bf16 v[30:33], v[168:171], v[184:187], v[30:33]
	v_mfma_f32_16x16x32_bf16 v[22:25], v[160:163], v[192:195], v[22:25]
	v_mfma_f32_16x16x32_bf16 v[14:17], v[168:171], v[192:195], v[14:17]
	v_mfma_f32_16x16x32_bf16 v[6:9], v[160:163], v[200:203], v[6:9]
	v_mfma_f32_16x16x32_bf16 v[2:5], v[168:171], v[200:203], v[2:5]
	s_barrier
	s_movk_i32 s17, 0x100
	s_andn2_b64 vcc, exec, s[4:5]
	s_mov_b64 s[50:51], -1
	s_mov_b64 s[4:5], 0
	s_cbranch_vccz .LBB0_1972
	s_and_b64 vcc, exec, s[12:13]
	s_cbranch_vccz .LBB0_1975
	s_barrier

.LBB0_2020:
	s_add_u32 s8, s8, 0x1a000000
	s_addc_u32 s9, s9, 0
	s_lshl_b32 s2, s2, 5
	s_and_b32 s2, s2, 0x60
	s_add_i32 m0, s65, 0x18000
	v_lshl_add_u64 v[8:9], v[8:9], 0, s[24:25]
	s_lshl_b32 s11, s3, 13
	s_lshl_b32 s12, s2, 7
	s_waitcnt vmcnt(2)
	s_barrier
	global_load_lds_dwordx4 v[8:9], off
	v_lshl_add_u64 v[6:7], v[6:7], 0, s[24:25]
	s_add_i32 m0, s65, 0x1a000
	s_add_i32 s69, s65, 0x8000
	s_add_i32 s70, s65, 0xa000
	global_load_lds_dwordx4 v[6:7], off
	v_lshl_add_u64 v[2:3], v[2:3], 0, s[24:25]
	s_mov_b32 m0, s69
	s_add_u32 s4, s44, 0x80080
	global_load_lds_dwordx4 v[2:3], off
	v_lshl_add_u64 v[2:3], v[4:5], 0, s[24:25]
	s_mov_b32 m0, s70
	s_addc_u32 s5, s45, 0
	global_load_lds_dwordx4 v[2:3], off
	s_add_i32 m0, s65, 0x1c000
	global_load_lds_dwordx4 v0, s[4:5]
	v_lshl_add_u64 v[2:3], s[4:5], 0, v[134:135]
	s_add_i32 m0, s65, 0x1e000
	s_cmpk_lt_u32 s10, 0x100
	global_load_lds_dwordx4 v[2:3], off
	v_lshrrev_b32_e32 v3, 1, v10
	v_and_b32_e32 v3, 24, v3
	v_and_b32_e32 v2, 15, v10
	v_lshlrev_b32_e32 v4, 1, v3
	v_lshl_or_b32 v140, s3, 6, v2
	v_lshl_or_b32 v2, v2, 6, v4
	v_lshlrev_b32_e32 v4, 2, v10
	v_and_b32_e32 v4, 32, v4
	s_waitcnt vmcnt(6)
	v_bitop3_b32 v5, v2, s11, v4 bitop3:0xde
	v_bitop3_b32 v141, v2, s12, v4 bitop3:0xde
	s_cselect_b64 s[10:11], -1, 0
	s_ashr_i32 s71, s22, 31
	s_ashr_i32 s72, s41, 31
	v_or_b32_e32 v142, s2, v3
	s_mov_b32 s73, 0
	v_add_u32_e32 v143, 0, v5
	s_barrier
	s_branch .LBB0_2023

.LBB0_2034:
	s_add_u32 s37, s46, s13
	s_addc_u32 s43, s47, 0
	s_add_u32 s50, s37, 0x100
	s_addc_u32 s51, s43, 0
	s_and_b64 s[20:21], s[48:49], exec
	s_cselect_b32 s53, s17, s51
	s_cselect_b32 s52, s16, s50
	s_add_u32 s13, s44, s13
	s_addc_u32 s20, s45, 0
	s_add_u32 s13, s13, 0x100
	s_addc_u32 s50, s20, 0
	s_add_i32 s78, 0, 0x10000
	s_and_b64 s[20:21], s[48:49], exec
	s_cselect_b32 s55, s19, s50
	s_cselect_b32 s54, s18, s13
	s_add_i32 s20, 0, 0x14000
	s_add_u32 s58, s37, 0x40080
	s_addc_u32 s59, s43, 0
	s_add_i32 s77, s78, s64
	s_add_i32 m0, s65, 0xc000
	s_add_i32 s21, s65, 0xe000
	s_add_i32 s37, s77, 0x2000
	s_add_u32 s56, s54, 0x80000
	v_add_u32_e32 v152, s78, v141
	v_add_u32_e32 v168, s20, v141
	s_addc_u32 s57, s55, 0
	s_add_i32 s83, s20, s64
	ds_read_b128 v[136:139], v152
	ds_read_b128 v[144:147], v152 offset:1024
	ds_read_b128 v[148:151], v152 offset:2048
	ds_read_b128 v[152:155], v152 offset:3072
	ds_read_b128 v[156:159], v168
	ds_read_b128 v[160:163], v168 offset:1024
	ds_read_b128 v[164:167], v168 offset:2048
	ds_read_b128 v[168:171], v168 offset:3072
	s_add_i32 s82, s83, 0x2000
	s_add_i32 s87, 0, 0x18000
	s_add_i32 s86, 0, 0x1c000
	s_add_u32 s50, s52, 0x40000
	s_addc_u32 s51, s53, 0
	s_add_i32 s43, s87, s64
	s_add_i32 s13, s43, 0x2000
	s_add_u32 s48, s54, 0x80080
	s_addc_u32 s49, s55, 0
	s_add_i32 s20, s86, s64
	s_add_i32 s78, s20, 0x2000
	ds_read_b128 v[172:175], v143
	ds_read_b128 v[176:179], v143 offset:1024
	ds_read_b128 v[180:183], v143 offset:2048
	ds_read_b128 v[184:187], v143 offset:3072
	ds_read_b128 v[188:191], v143 offset:4096
	ds_read_b128 v[192:195], v143 offset:5120
	ds_read_b128 v[196:199], v143 offset:6144
	ds_read_b128 v[200:203], v143 offset:7168
	global_load_lds_dwordx4 v130, s[58:59]
	s_mov_b32 m0, s21
	s_nop 0
	global_load_lds_dwordx4 v132, s[58:59]
	s_waitcnt vmcnt(8)
	s_waitcnt lgkmcnt(0)
	s_barrier
	s_waitcnt lgkmcnt(0)
	v_mfma_f32_16x16x32_bf16 v[126:129], v[136:139], v[172:175], v[126:129]
	v_mfma_f32_16x16x32_bf16 v[122:125], v[148:151], v[172:175], v[122:125]
	v_mfma_f32_16x16x32_bf16 v[114:117], v[136:139], v[180:183], v[114:117]
	v_mfma_f32_16x16x32_bf16 v[106:109], v[148:151], v[180:183], v[106:109]
	v_mfma_f32_16x16x32_bf16 v[98:101], v[136:139], v[188:191], v[98:101]
	v_mfma_f32_16x16x32_bf16 v[90:93], v[148:151], v[188:191], v[90:93]
	v_mfma_f32_16x16x32_bf16 v[82:85], v[136:139], v[196:199], v[82:85]
	v_mfma_f32_16x16x32_bf16 v[74:77], v[148:151], v[196:199], v[74:77]
	v_mfma_f32_16x16x32_bf16 v[126:129], v[144:147], v[176:179], v[126:129]
	v_mfma_f32_16x16x32_bf16 v[122:125], v[152:155], v[176:179], v[122:125]
	v_mfma_f32_16x16x32_bf16 v[114:117], v[144:147], v[184:187], v[114:117]
	v_mfma_f32_16x16x32_bf16 v[106:109], v[152:155], v[184:187], v[106:109]
	v_mfma_f32_16x16x32_bf16 v[98:101], v[144:147], v[192:195], v[98:101]
	v_mfma_f32_16x16x32_bf16 v[90:93], v[152:155], v[192:195], v[90:93]
	v_mfma_f32_16x16x32_bf16 v[82:85], v[144:147], v[200:203], v[82:85]
	v_mfma_f32_16x16x32_bf16 v[74:77], v[152:155], v[200:203], v[74:77]
	v_mfma_f32_16x16x32_bf16 v[118:121], v[156:159], v[172:175], v[118:121]
	v_mfma_f32_16x16x32_bf16 v[110:113], v[164:167], v[172:175], v[110:113]
	v_mfma_f32_16x16x32_bf16 v[102:105], v[156:159], v[180:183], v[102:105]
	v_mfma_f32_16x16x32_bf16 v[94:97], v[164:167], v[180:183], v[94:97]
	v_mfma_f32_16x16x32_bf16 v[86:89], v[156:159], v[188:191], v[86:89]
	v_mfma_f32_16x16x32_bf16 v[78:81], v[164:167], v[188:191], v[78:81]
	v_mfma_f32_16x16x32_bf16 v[70:73], v[156:159], v[196:199], v[70:73]
	v_mfma_f32_16x16x32_bf16 v[66:69], v[164:167], v[196:199], v[66:69]
	v_mfma_f32_16x16x32_bf16 v[118:121], v[160:163], v[176:179], v[118:121]
	v_mfma_f32_16x16x32_bf16 v[110:113], v[168:171], v[176:179], v[110:113]
	v_mfma_f32_16x16x32_bf16 v[102:105], v[160:163], v[184:187], v[102:105]
	v_mfma_f32_16x16x32_bf16 v[94:97], v[168:171], v[184:187], v[94:97]
	v_mfma_f32_16x16x32_bf16 v[86:89], v[160:163], v[192:195], v[86:89]
	v_mfma_f32_16x16x32_bf16 v[78:81], v[168:171], v[192:195], v[78:81]
	v_mfma_f32_16x16x32_bf16 v[70:73], v[160:163], v[200:203], v[70:73]
	v_mfma_f32_16x16x32_bf16 v[66:69], v[168:171], v[200:203], v[66:69]
	s_barrier
	s_mov_b32 m0, s77
	v_lshl_add_u64 v[204:205], s[54:55], 0, v[0:1]
	ds_read_b128 v[172:175], v143 offset:16384
	ds_read_b128 v[176:179], v143 offset:17408
	ds_read_b128 v[180:183], v143 offset:18432
	ds_read_b128 v[184:187], v143 offset:19456
	ds_read_b128 v[188:191], v143 offset:20480
	ds_read_b128 v[192:195], v143 offset:21504
	ds_read_b128 v[196:199], v143 offset:22528
	ds_read_b128 v[200:203], v143 offset:23552
	global_load_lds_dwordx4 v[204:205], off
	v_lshl_add_u64 v[206:207], s[54:55], 0, v[134:135]
	s_mov_b32 m0, s37
	global_load_lds_dwordx4 v[206:207], off
	s_mov_b32 m0, s83
	v_lshl_add_u64 v[210:211], s[52:53], 0, v[132:133]
	global_load_lds_dwordx4 v0, s[56:57]
	s_mov_b32 m0, s82
	s_nop 0
	global_load_lds_dwordx4 v134, s[56:57]
	v_lshl_add_u64 v[208:209], s[52:53], 0, v[130:131]
	s_mov_b32 m0, s65
	s_nop 0
	global_load_lds_dwordx4 v[208:209], off
	s_mov_b32 m0, s66
	s_nop 0
	global_load_lds_dwordx4 v[210:211], off
	s_waitcnt vmcnt(8)
	s_waitcnt lgkmcnt(0)
	s_barrier
	s_waitcnt lgkmcnt(0)
	v_mfma_f32_16x16x32_bf16 v[62:65], v[136:139], v[172:175], v[62:65]
	v_mfma_f32_16x16x32_bf16 v[58:61], v[148:151], v[172:175], v[58:61]
	v_mfma_f32_16x16x32_bf16 v[50:53], v[136:139], v[180:183], v[50:53]
	v_mfma_f32_16x16x32_bf16 v[42:45], v[148:151], v[180:183], v[42:45]
	v_mfma_f32_16x16x32_bf16 v[34:37], v[136:139], v[188:191], v[34:37]
	v_mfma_f32_16x16x32_bf16 v[26:29], v[148:151], v[188:191], v[26:29]
	v_mfma_f32_16x16x32_bf16 v[18:21], v[136:139], v[196:199], v[18:21]
	v_mfma_f32_16x16x32_bf16 v[10:13], v[148:151], v[196:199], v[10:13]
	v_mfma_f32_16x16x32_bf16 v[62:65], v[144:147], v[176:179], v[62:65]
	v_mfma_f32_16x16x32_bf16 v[58:61], v[152:155], v[176:179], v[58:61]
	v_mfma_f32_16x16x32_bf16 v[50:53], v[144:147], v[184:187], v[50:53]
	v_mfma_f32_16x16x32_bf16 v[42:45], v[152:155], v[184:187], v[42:45]
	v_mfma_f32_16x16x32_bf16 v[34:37], v[144:147], v[192:195], v[34:37]
	v_mfma_f32_16x16x32_bf16 v[26:29], v[152:155], v[192:195], v[26:29]
	v_mfma_f32_16x16x32_bf16 v[18:21], v[144:147], v[200:203], v[18:21]
	v_mfma_f32_16x16x32_bf16 v[10:13], v[152:155], v[200:203], v[10:13]
	v_mfma_f32_16x16x32_bf16 v[54:57], v[156:159], v[172:175], v[54:57]
	v_mfma_f32_16x16x32_bf16 v[46:49], v[164:167], v[172:175], v[46:49]
	v_mfma_f32_16x16x32_bf16 v[38:41], v[156:159], v[180:183], v[38:41]
	v_mfma_f32_16x16x32_bf16 v[30:33], v[164:167], v[180:183], v[30:33]
	v_mfma_f32_16x16x32_bf16 v[22:25], v[156:159], v[188:191], v[22:25]
	v_mfma_f32_16x16x32_bf16 v[14:17], v[164:167], v[188:191], v[14:17]
	v_mfma_f32_16x16x32_bf16 v[6:9], v[156:159], v[196:199], v[6:9]
	v_mfma_f32_16x16x32_bf16 v[2:5], v[164:167], v[196:199], v[2:5]
	v_mfma_f32_16x16x32_bf16 v[54:57], v[160:163], v[176:179], v[54:57]
	v_mfma_f32_16x16x32_bf16 v[46:49], v[168:171], v[176:179], v[46:49]
	v_mfma_f32_16x16x32_bf16 v[38:41], v[160:163], v[184:187], v[38:41]
	v_mfma_f32_16x16x32_bf16 v[30:33], v[168:171], v[184:187], v[30:33]
	v_mfma_f32_16x16x32_bf16 v[22:25], v[160:163], v[192:195], v[22:25]
	v_mfma_f32_16x16x32_bf16 v[14:17], v[168:171], v[192:195], v[14:17]
	v_mfma_f32_16x16x32_bf16 v[6:9], v[160:163], v[200:203], v[6:9]
	v_mfma_f32_16x16x32_bf16 v[2:5], v[168:171], v[200:203], v[2:5]
	s_barrier
	v_add_u32_e32 v152, s87, v141
	v_add_u32_e32 v168, s86, v141
	ds_read_b128 v[136:139], v152
	ds_read_b128 v[144:147], v152 offset:1024
	ds_read_b128 v[148:151], v152 offset:2048
	ds_read_b128 v[152:155], v152 offset:3072
	ds_read_b128 v[156:159], v168
	ds_read_b128 v[160:163], v168 offset:1024
	ds_read_b128 v[164:167], v168 offset:2048
	ds_read_b128 v[168:171], v168 offset:3072
	s_mov_b32 m0, s67
	ds_read_b128 v[172:175], v143 offset:32768
	ds_read_b128 v[176:179], v143 offset:33792
	ds_read_b128 v[180:183], v143 offset:34816
	ds_read_b128 v[184:187], v143 offset:35840
	ds_read_b128 v[188:191], v143 offset:36864
	ds_read_b128 v[192:195], v143 offset:37888
	ds_read_b128 v[196:199], v143 offset:38912
	ds_read_b128 v[200:203], v143 offset:39936
	global_load_lds_dwordx4 v130, s[50:51]
	v_lshl_add_u64 v[214:215], s[50:51], 0, v[132:133]
	s_mov_b32 m0, s68
	s_nop 0
	global_load_lds_dwordx4 v[214:215], off
	s_waitcnt vmcnt(8)
	s_waitcnt lgkmcnt(0)
	s_barrier
	s_waitcnt lgkmcnt(0)
	v_mfma_f32_16x16x32_bf16 v[126:129], v[136:139], v[172:175], v[126:129]
	v_mfma_f32_16x16x32_bf16 v[122:125], v[148:151], v[172:175], v[122:125]
	v_mfma_f32_16x16x32_bf16 v[114:117], v[136:139], v[180:183], v[114:117]
	v_mfma_f32_16x16x32_bf16 v[106:109], v[148:151], v[180:183], v[106:109]
	v_mfma_f32_16x16x32_bf16 v[98:101], v[136:139], v[188:191], v[98:101]
	v_mfma_f32_16x16x32_bf16 v[90:93], v[148:151], v[188:191], v[90:93]
	v_mfma_f32_16x16x32_bf16 v[82:85], v[136:139], v[196:199], v[82:85]
	v_mfma_f32_16x16x32_bf16 v[74:77], v[148:151], v[196:199], v[74:77]
	v_mfma_f32_16x16x32_bf16 v[126:129], v[144:147], v[176:179], v[126:129]
	v_mfma_f32_16x16x32_bf16 v[122:125], v[152:155], v[176:179], v[122:125]
	v_mfma_f32_16x16x32_bf16 v[114:117], v[144:147], v[184:187], v[114:117]
	v_mfma_f32_16x16x32_bf16 v[106:109], v[152:155], v[184:187], v[106:109]
	v_mfma_f32_16x16x32_bf16 v[98:101], v[144:147], v[192:195], v[98:101]
	v_mfma_f32_16x16x32_bf16 v[90:93], v[152:155], v[192:195], v[90:93]
	v_mfma_f32_16x16x32_bf16 v[82:85], v[144:147], v[200:203], v[82:85]
	v_mfma_f32_16x16x32_bf16 v[74:77], v[152:155], v[200:203], v[74:77]
	v_mfma_f32_16x16x32_bf16 v[118:121], v[156:159], v[172:175], v[118:121]
	v_mfma_f32_16x16x32_bf16 v[110:113], v[164:167], v[172:175], v[110:113]
	v_mfma_f32_16x16x32_bf16 v[102:105], v[156:159], v[180:183], v[102:105]
	v_mfma_f32_16x16x32_bf16 v[94:97], v[164:167], v[180:183], v[94:97]
	v_mfma_f32_16x16x32_bf16 v[86:89], v[156:159], v[188:191], v[86:89]
	v_mfma_f32_16x16x32_bf16 v[78:81], v[164:167], v[188:191], v[78:81]
	v_mfma_f32_16x16x32_bf16 v[70:73], v[156:159], v[196:199], v[70:73]
	v_mfma_f32_16x16x32_bf16 v[66:69], v[164:167], v[196:199], v[66:69]
	v_mfma_f32_16x16x32_bf16 v[118:121], v[160:163], v[176:179], v[118:121]
	v_mfma_f32_16x16x32_bf16 v[110:113], v[168:171], v[176:179], v[110:113]
	v_mfma_f32_16x16x32_bf16 v[102:105], v[160:163], v[184:187], v[102:105]
	v_mfma_f32_16x16x32_bf16 v[94:97], v[168:171], v[184:187], v[94:97]
	v_mfma_f32_16x16x32_bf16 v[86:89], v[160:163], v[192:195], v[86:89]
	v_mfma_f32_16x16x32_bf16 v[78:81], v[168:171], v[192:195], v[78:81]
	v_mfma_f32_16x16x32_bf16 v[70:73], v[160:163], v[200:203], v[70:73]
	v_mfma_f32_16x16x32_bf16 v[66:69], v[168:171], v[200:203], v[66:69]
	s_barrier
	s_mov_b32 m0, s43
	v_lshl_add_u64 v[204:205], v[204:205], 0, s[24:25]
	ds_read_b128 v[172:175], v143 offset:49152
	ds_read_b128 v[176:179], v143 offset:50176
	ds_read_b128 v[180:183], v143 offset:51200
	ds_read_b128 v[184:187], v143 offset:52224
	ds_read_b128 v[188:191], v143 offset:53248
	ds_read_b128 v[192:195], v143 offset:54272
	ds_read_b128 v[196:199], v143 offset:55296
	ds_read_b128 v[200:203], v143 offset:56320
	global_load_lds_dwordx4 v[204:205], off
	v_lshl_add_u64 v[204:205], v[206:207], 0, s[24:25]
	s_mov_b32 m0, s13
	s_nop 0
	global_load_lds_dwordx4 v[204:205], off
	s_mov_b32 m0, s20
	s_nop 0
	global_load_lds_dwordx4 v0, s[48:49]
	s_mov_b32 m0, s78
	s_nop 0
	global_load_lds_dwordx4 v134, s[48:49]
	v_lshl_add_u64 v[204:205], v[208:209], 0, s[24:25]
	s_mov_b32 m0, s69
	s_nop 0
	global_load_lds_dwordx4 v[204:205], off
	v_lshl_add_u64 v[204:205], v[210:211], 0, s[24:25]
	s_mov_b32 m0, s70
	s_nop 0
	global_load_lds_dwordx4 v[204:205], off
	s_waitcnt vmcnt(8)
	s_waitcnt lgkmcnt(0)
	s_barrier
	s_waitcnt lgkmcnt(0)
	v_mfma_f32_16x16x32_bf16 v[62:65], v[136:139], v[172:175], v[62:65]
	v_mfma_f32_16x16x32_bf16 v[58:61], v[148:151], v[172:175], v[58:61]
	v_mfma_f32_16x16x32_bf16 v[50:53], v[136:139], v[180:183], v[50:53]
	v_mfma_f32_16x16x32_bf16 v[42:45], v[148:151], v[180:183], v[42:45]
	v_mfma_f32_16x16x32_bf16 v[34:37], v[136:139], v[188:191], v[34:37]
	v_mfma_f32_16x16x32_bf16 v[26:29], v[148:151], v[188:191], v[26:29]
	v_mfma_f32_16x16x32_bf16 v[18:21], v[136:139], v[196:199], v[18:21]
	v_mfma_f32_16x16x32_bf16 v[10:13], v[148:151], v[196:199], v[10:13]
	v_mfma_f32_16x16x32_bf16 v[62:65], v[144:147], v[176:179], v[62:65]
	v_mfma_f32_16x16x32_bf16 v[58:61], v[152:155], v[176:179], v[58:61]
	v_mfma_f32_16x16x32_bf16 v[50:53], v[144:147], v[184:187], v[50:53]
	v_mfma_f32_16x16x32_bf16 v[42:45], v[152:155], v[184:187], v[42:45]
	v_mfma_f32_16x16x32_bf16 v[34:37], v[144:147], v[192:195], v[34:37]
	v_mfma_f32_16x16x32_bf16 v[26:29], v[152:155], v[192:195], v[26:29]
	v_mfma_f32_16x16x32_bf16 v[18:21], v[144:147], v[200:203], v[18:21]
	v_mfma_f32_16x16x32_bf16 v[10:13], v[152:155], v[200:203], v[10:13]
	v_mfma_f32_16x16x32_bf16 v[54:57], v[156:159], v[172:175], v[54:57]
	v_mfma_f32_16x16x32_bf16 v[46:49], v[164:167], v[172:175], v[46:49]
	v_mfma_f32_16x16x32_bf16 v[38:41], v[156:159], v[180:183], v[38:41]
	v_mfma_f32_16x16x32_bf16 v[30:33], v[164:167], v[180:183], v[30:33]
	v_mfma_f32_16x16x32_bf16 v[22:25], v[156:159], v[188:191], v[22:25]
	v_mfma_f32_16x16x32_bf16 v[14:17], v[164:167], v[188:191], v[14:17]
	v_mfma_f32_16x16x32_bf16 v[6:9], v[156:159], v[196:199], v[6:9]
	v_mfma_f32_16x16x32_bf16 v[2:5], v[164:167], v[196:199], v[2:5]
	v_mfma_f32_16x16x32_bf16 v[54:57], v[160:163], v[176:179], v[54:57]
	v_mfma_f32_16x16x32_bf16 v[46:49], v[168:171], v[176:179], v[46:49]
	v_mfma_f32_16x16x32_bf16 v[38:41], v[160:163], v[184:187], v[38:41]
	v_mfma_f32_16x16x32_bf16 v[30:33], v[168:171], v[184:187], v[30:33]
	v_mfma_f32_16x16x32_bf16 v[22:25], v[160:163], v[192:195], v[22:25]
	v_mfma_f32_16x16x32_bf16 v[14:17], v[168:171], v[192:195], v[14:17]
	v_mfma_f32_16x16x32_bf16 v[6:9], v[160:163], v[200:203], v[6:9]
	v_mfma_f32_16x16x32_bf16 v[2:5], v[168:171], v[200:203], v[2:5]
	s_barrier
	s_movk_i32 s13, 0x100
	s_andn2_b64 vcc, exec, s[4:5]
	s_mov_b64 s[48:49], -1
	s_mov_b64 s[4:5], 0
	s_cbranch_vccz .LBB0_2034
	s_and_b64 vcc, exec, s[10:11]
	s_cbranch_vccz .LBB0_2037
	s_barrier

.LBB0_2134:
	s_add_u32 s58, s10, 0x28000000
	s_addc_u32 s59, s11, 0
	s_add_u32 s10, s10, 0x8000000
	s_addc_u32 s11, s11, 0
	s_and_b32 s4, s2, 3
	s_add_i32 m0, s49, 0x18000
	v_lshl_add_u64 v[8:9], v[8:9], 0, s[24:25]
	s_lshl_b32 s60, s3, 6
	s_lshl_b32 s5, s3, 13
	s_lshl_b32 s61, s4, 5
	s_lshl_b32 s16, s4, 12
	s_waitcnt vmcnt(2)
	s_barrier
	global_load_lds_dwordx4 v[8:9], off
	v_lshl_add_u64 v[6:7], v[6:7], 0, s[24:25]
	s_add_i32 m0, s49, 0x1a000
	s_add_i32 s62, s49, 0x8000
	s_add_i32 s63, s49, 0xa000
	global_load_lds_dwordx4 v[6:7], off
	v_lshl_add_u64 v[2:3], v[2:3], 0, s[24:25]
	s_mov_b32 m0, s62
	s_add_u32 s2, s6, 0x40080
	global_load_lds_dwordx4 v[2:3], off
	v_lshl_add_u64 v[2:3], v[4:5], 0, s[24:25]
	s_mov_b32 m0, s63
	s_addc_u32 s3, s7, 0
	global_load_lds_dwordx4 v[2:3], off
	s_add_i32 m0, s49, 0x1c000
	global_load_lds_dwordx4 v0, s[2:3]
	v_lshl_add_u64 v[2:3], s[2:3], 0, v[134:135]
	s_add_i32 m0, s49, 0x1e000
	v_bfe_u32 v172, v10, 4, 2
	global_load_lds_dwordx4 v[2:3], off
	v_and_b32_e32 v173, 15, v10
	v_lshlrev_b32_e32 v2, 4, v172
	v_lshlrev_b32_e32 v3, 2, v10
	v_lshl_or_b32 v2, v173, 6, v2
	v_and_b32_e32 v3, 32, v3
	v_bitop3_b32 v4, v2, s5, v3 bitop3:0xde
	v_bitop3_b32 v174, v2, s16, v3 bitop3:0xde
	v_lshlrev_b32_e32 v2, 14, v11
	v_and_b32_e32 v2, 0xffff8000, v2
	v_lshl_add_u32 v2, v12, 11, v2
	v_and_b32_e32 v3, 1, v11
	v_lshl_or_b32 v2, v3, 6, v2
	v_lshl_add_u32 v136, v13, 1, v2
	v_lshlrev_b32_e32 v2, 14, v14
	s_cmpk_lt_u32 s18, 0x100
	v_and_b32_e32 v2, 0xffff8000, v2
	s_waitcnt vmcnt(6)
	s_cselect_b64 s[16:17], -1, 0
	s_lshl_b32 s2, s4, 2
	v_lshl_add_u32 v2, v15, 11, v2
	v_and_b32_e32 v3, 1, v14
	s_add_i32 s69, s2, 0
	v_lshl_or_b32 v2, v3, 6, v2
	s_ashr_i32 s64, s60, 31
	s_and_b32 s65, s18, 0xffffff00
	s_ashr_i32 s66, s22, 31
	s_ashr_i32 s67, s41, 31
	s_add_i32 s68, s69, 0x20400
	s_add_i32 s69, s69, 0x21400
	v_mov_b32_e32 v137, v1
	v_lshl_add_u32 v138, v16, 1, v2
	v_mov_b32_e32 v139, v1
	s_mov_b32 s70, 0
	v_add_u32_e32 v175, 0, v4
	s_barrier
	s_branch .LBB0_2137

.LBB0_2148:
	s_add_u32 s6, s4, 0xfffc0080
	s_addc_u32 s7, s5, -1
	s_add_i32 s20, 0, 0x10000
	s_cmp_eq_u32 s72, 12
	s_cselect_b32 s51, s43, s7
	s_cselect_b32 s50, s42, s6
	s_cselect_b32 s7, s45, s47
	s_cselect_b32 s6, s44, s19
	s_add_i32 s37, 0, 0x14000
	v_add_u32_e32 v152, s20, v174
	v_add_u32_e32 v168, s37, v174
	ds_read_b128 v[140:143], v152
	ds_read_b128 v[144:147], v152 offset:1024
	ds_read_b128 v[148:151], v152 offset:2048
	ds_read_b128 v[152:155], v152 offset:3072
	ds_read_b128 v[156:159], v168
	ds_read_b128 v[160:163], v168 offset:1024
	ds_read_b128 v[164:167], v168 offset:2048
	ds_read_b128 v[168:171], v168 offset:3072
	s_add_i32 m0, s49, 0xc000
	ds_read_b128 v[176:179], v175
	ds_read_b128 v[180:183], v175 offset:1024
	ds_read_b128 v[184:187], v175 offset:2048
	ds_read_b128 v[188:191], v175 offset:3072
	ds_read_b128 v[192:195], v175 offset:4096
	ds_read_b128 v[196:199], v175 offset:5120
	ds_read_b128 v[200:203], v175 offset:6144
	ds_read_b128 v[204:207], v175 offset:7168
	global_load_lds_dwordx4 v136, s[4:5]
	s_add_i32 m0, s49, 0xe000
	s_nop 0
	global_load_lds_dwordx4 v138, s[4:5]
	s_waitcnt vmcnt(8)
	s_waitcnt lgkmcnt(0)
	s_barrier
	s_waitcnt lgkmcnt(0)
	v_mfma_f32_16x16x32_bf16 v[126:129], v[140:143], v[176:179], v[126:129]
	v_mfma_f32_16x16x32_bf16 v[122:125], v[148:151], v[176:179], v[122:125]
	v_mfma_f32_16x16x32_bf16 v[110:113], v[140:143], v[184:187], v[110:113]
	v_mfma_f32_16x16x32_bf16 v[106:109], v[148:151], v[184:187], v[106:109]
	v_mfma_f32_16x16x32_bf16 v[94:97], v[140:143], v[192:195], v[94:97]
	v_mfma_f32_16x16x32_bf16 v[90:93], v[148:151], v[192:195], v[90:93]
	v_mfma_f32_16x16x32_bf16 v[78:81], v[140:143], v[200:203], v[78:81]
	v_mfma_f32_16x16x32_bf16 v[74:77], v[148:151], v[200:203], v[74:77]
	v_mfma_f32_16x16x32_bf16 v[126:129], v[144:147], v[180:183], v[126:129]
	v_mfma_f32_16x16x32_bf16 v[122:125], v[152:155], v[180:183], v[122:125]
	v_mfma_f32_16x16x32_bf16 v[110:113], v[144:147], v[188:191], v[110:113]
	v_mfma_f32_16x16x32_bf16 v[106:109], v[152:155], v[188:191], v[106:109]
	v_mfma_f32_16x16x32_bf16 v[94:97], v[144:147], v[196:199], v[94:97]
	v_mfma_f32_16x16x32_bf16 v[90:93], v[152:155], v[196:199], v[90:93]
	v_mfma_f32_16x16x32_bf16 v[78:81], v[144:147], v[204:207], v[78:81]
	v_mfma_f32_16x16x32_bf16 v[74:77], v[152:155], v[204:207], v[74:77]
	v_mfma_f32_16x16x32_bf16 v[118:121], v[156:159], v[176:179], v[118:121]
	v_mfma_f32_16x16x32_bf16 v[114:117], v[164:167], v[176:179], v[114:117]
	v_mfma_f32_16x16x32_bf16 v[102:105], v[156:159], v[184:187], v[102:105]
	v_mfma_f32_16x16x32_bf16 v[98:101], v[164:167], v[184:187], v[98:101]
	v_mfma_f32_16x16x32_bf16 v[86:89], v[156:159], v[192:195], v[86:89]
	v_mfma_f32_16x16x32_bf16 v[82:85], v[164:167], v[192:195], v[82:85]
	v_mfma_f32_16x16x32_bf16 v[70:73], v[156:159], v[200:203], v[70:73]
	v_mfma_f32_16x16x32_bf16 v[66:69], v[164:167], v[200:203], v[66:69]
	v_mfma_f32_16x16x32_bf16 v[118:121], v[160:163], v[180:183], v[118:121]
	v_mfma_f32_16x16x32_bf16 v[114:117], v[168:171], v[180:183], v[114:117]
	v_mfma_f32_16x16x32_bf16 v[102:105], v[160:163], v[188:191], v[102:105]
	v_mfma_f32_16x16x32_bf16 v[98:101], v[168:171], v[188:191], v[98:101]
	v_mfma_f32_16x16x32_bf16 v[86:89], v[160:163], v[196:199], v[86:89]
	v_mfma_f32_16x16x32_bf16 v[82:85], v[168:171], v[196:199], v[82:85]
	v_mfma_f32_16x16x32_bf16 v[70:73], v[160:163], v[204:207], v[70:73]
	v_mfma_f32_16x16x32_bf16 v[66:69], v[168:171], v[204:207], v[66:69]
	s_barrier
	s_add_i32 s20, s20, s54
	v_lshl_add_u64 v[208:209], s[6:7], 0, v[0:1]
	s_mov_b32 m0, s20
	ds_read_b128 v[176:179], v175 offset:16384
	ds_read_b128 v[180:183], v175 offset:17408
	ds_read_b128 v[184:187], v175 offset:18432
	ds_read_b128 v[188:191], v175 offset:19456
	ds_read_b128 v[192:195], v175 offset:20480
	ds_read_b128 v[196:199], v175 offset:21504
	ds_read_b128 v[200:203], v175 offset:22528
	ds_read_b128 v[204:207], v175 offset:23552
	global_load_lds_dwordx4 v[208:209], off
	s_add_i32 m0, s20, 0x2000
	s_add_u32 s20, s6, 0x40000
	v_lshl_add_u64 v[210:211], s[6:7], 0, v[134:135]
	s_addc_u32 s21, s7, 0
	s_add_i32 s37, s37, s54
	global_load_lds_dwordx4 v[210:211], off
	s_mov_b32 m0, s37
	v_lshl_add_u64 v[216:217], s[50:51], 0, v[132:133]
	global_load_lds_dwordx4 v0, s[20:21]
	s_add_i32 m0, s37, 0x2000
	s_nop 0
	global_load_lds_dwordx4 v134, s[20:21]
	v_lshl_add_u64 v[214:215], s[50:51], 0, v[130:131]
	s_mov_b32 m0, s49
	s_nop 0
	global_load_lds_dwordx4 v[214:215], off
	s_mov_b32 m0, s55
	s_nop 0
	global_load_lds_dwordx4 v[216:217], off
	s_waitcnt vmcnt(8)
	s_waitcnt lgkmcnt(0)
	s_barrier
	s_waitcnt lgkmcnt(0)
	v_mfma_f32_16x16x32_bf16 v[62:65], v[140:143], v[176:179], v[62:65]
	v_mfma_f32_16x16x32_bf16 v[58:61], v[148:151], v[176:179], v[58:61]
	v_mfma_f32_16x16x32_bf16 v[46:49], v[140:143], v[184:187], v[46:49]
	v_mfma_f32_16x16x32_bf16 v[42:45], v[148:151], v[184:187], v[42:45]
	v_mfma_f32_16x16x32_bf16 v[30:33], v[140:143], v[192:195], v[30:33]
	v_mfma_f32_16x16x32_bf16 v[26:29], v[148:151], v[192:195], v[26:29]
	v_mfma_f32_16x16x32_bf16 v[14:17], v[140:143], v[200:203], v[14:17]
	v_mfma_f32_16x16x32_bf16 v[10:13], v[148:151], v[200:203], v[10:13]
	v_mfma_f32_16x16x32_bf16 v[62:65], v[144:147], v[180:183], v[62:65]
	v_mfma_f32_16x16x32_bf16 v[58:61], v[152:155], v[180:183], v[58:61]
	v_mfma_f32_16x16x32_bf16 v[46:49], v[144:147], v[188:191], v[46:49]
	v_mfma_f32_16x16x32_bf16 v[42:45], v[152:155], v[188:191], v[42:45]
	v_mfma_f32_16x16x32_bf16 v[30:33], v[144:147], v[196:199], v[30:33]
	v_mfma_f32_16x16x32_bf16 v[26:29], v[152:155], v[196:199], v[26:29]
	v_mfma_f32_16x16x32_bf16 v[14:17], v[144:147], v[204:207], v[14:17]
	v_mfma_f32_16x16x32_bf16 v[10:13], v[152:155], v[204:207], v[10:13]
	v_mfma_f32_16x16x32_bf16 v[54:57], v[156:159], v[176:179], v[54:57]
	v_mfma_f32_16x16x32_bf16 v[50:53], v[164:167], v[176:179], v[50:53]
	v_mfma_f32_16x16x32_bf16 v[38:41], v[156:159], v[184:187], v[38:41]
	v_mfma_f32_16x16x32_bf16 v[34:37], v[164:167], v[184:187], v[34:37]
	v_mfma_f32_16x16x32_bf16 v[22:25], v[156:159], v[192:195], v[22:25]
	v_mfma_f32_16x16x32_bf16 v[18:21], v[164:167], v[192:195], v[18:21]
	v_mfma_f32_16x16x32_bf16 v[6:9], v[156:159], v[200:203], v[6:9]
	v_mfma_f32_16x16x32_bf16 v[2:5], v[164:167], v[200:203], v[2:5]
	v_mfma_f32_16x16x32_bf16 v[54:57], v[160:163], v[180:183], v[54:57]
	v_mfma_f32_16x16x32_bf16 v[50:53], v[168:171], v[180:183], v[50:53]
	v_mfma_f32_16x16x32_bf16 v[38:41], v[160:163], v[188:191], v[38:41]
	v_mfma_f32_16x16x32_bf16 v[34:37], v[168:171], v[188:191], v[34:37]
	v_mfma_f32_16x16x32_bf16 v[22:25], v[160:163], v[196:199], v[22:25]
	v_mfma_f32_16x16x32_bf16 v[18:21], v[168:171], v[196:199], v[18:21]
	v_mfma_f32_16x16x32_bf16 v[6:9], v[160:163], v[204:207], v[6:9]
	v_mfma_f32_16x16x32_bf16 v[2:5], v[168:171], v[204:207], v[2:5]
	s_barrier
	s_add_i32 s37, 0, 0x18000
	s_add_i32 s73, 0, 0x1c000
	v_add_u32_e32 v152, s37, v174
	v_add_u32_e32 v168, s73, v174
	ds_read_b128 v[140:143], v152
	ds_read_b128 v[144:147], v152 offset:1024
	ds_read_b128 v[148:151], v152 offset:2048
	ds_read_b128 v[152:155], v152 offset:3072
	ds_read_b128 v[156:159], v168
	ds_read_b128 v[160:163], v168 offset:1024
	ds_read_b128 v[164:167], v168 offset:2048
	ds_read_b128 v[168:171], v168 offset:3072
	s_add_u32 s20, s50, 0x40000
	s_addc_u32 s21, s51, 0
	s_mov_b32 m0, s56
	ds_read_b128 v[176:179], v175 offset:32768
	ds_read_b128 v[180:183], v175 offset:33792
	ds_read_b128 v[184:187], v175 offset:34816
	ds_read_b128 v[188:191], v175 offset:35840
	ds_read_b128 v[192:195], v175 offset:36864
	ds_read_b128 v[196:199], v175 offset:37888
	ds_read_b128 v[200:203], v175 offset:38912
	ds_read_b128 v[204:207], v175 offset:39936
	global_load_lds_dwordx4 v130, s[20:21]
	v_lshl_add_u64 v[218:219], s[20:21], 0, v[132:133]
	s_mov_b32 m0, s57
	s_nop 0
	global_load_lds_dwordx4 v[218:219], off
	s_waitcnt vmcnt(8)
	s_waitcnt lgkmcnt(0)
	s_barrier
	s_waitcnt lgkmcnt(0)
	v_mfma_f32_16x16x32_bf16 v[126:129], v[140:143], v[176:179], v[126:129]
	v_mfma_f32_16x16x32_bf16 v[122:125], v[148:151], v[176:179], v[122:125]
	v_mfma_f32_16x16x32_bf16 v[110:113], v[140:143], v[184:187], v[110:113]
	v_mfma_f32_16x16x32_bf16 v[106:109], v[148:151], v[184:187], v[106:109]
	v_mfma_f32_16x16x32_bf16 v[94:97], v[140:143], v[192:195], v[94:97]
	v_mfma_f32_16x16x32_bf16 v[90:93], v[148:151], v[192:195], v[90:93]
	v_mfma_f32_16x16x32_bf16 v[78:81], v[140:143], v[200:203], v[78:81]
	v_mfma_f32_16x16x32_bf16 v[74:77], v[148:151], v[200:203], v[74:77]
	v_mfma_f32_16x16x32_bf16 v[126:129], v[144:147], v[180:183], v[126:129]
	v_mfma_f32_16x16x32_bf16 v[122:125], v[152:155], v[180:183], v[122:125]
	v_mfma_f32_16x16x32_bf16 v[110:113], v[144:147], v[188:191], v[110:113]
	v_mfma_f32_16x16x32_bf16 v[106:109], v[152:155], v[188:191], v[106:109]
	v_mfma_f32_16x16x32_bf16 v[94:97], v[144:147], v[196:199], v[94:97]
	v_mfma_f32_16x16x32_bf16 v[90:93], v[152:155], v[196:199], v[90:93]
	v_mfma_f32_16x16x32_bf16 v[78:81], v[144:147], v[204:207], v[78:81]
	v_mfma_f32_16x16x32_bf16 v[74:77], v[152:155], v[204:207], v[74:77]
	v_mfma_f32_16x16x32_bf16 v[118:121], v[156:159], v[176:179], v[118:121]
	v_mfma_f32_16x16x32_bf16 v[114:117], v[164:167], v[176:179], v[114:117]
	v_mfma_f32_16x16x32_bf16 v[102:105], v[156:159], v[184:187], v[102:105]
	v_mfma_f32_16x16x32_bf16 v[98:101], v[164:167], v[184:187], v[98:101]
	v_mfma_f32_16x16x32_bf16 v[86:89], v[156:159], v[192:195], v[86:89]
	v_mfma_f32_16x16x32_bf16 v[82:85], v[164:167], v[192:195], v[82:85]
	v_mfma_f32_16x16x32_bf16 v[70:73], v[156:159], v[200:203], v[70:73]
	v_mfma_f32_16x16x32_bf16 v[66:69], v[164:167], v[200:203], v[66:69]
	v_mfma_f32_16x16x32_bf16 v[118:121], v[160:163], v[180:183], v[118:121]
	v_mfma_f32_16x16x32_bf16 v[114:117], v[168:171], v[180:183], v[114:117]
	v_mfma_f32_16x16x32_bf16 v[102:105], v[160:163], v[188:191], v[102:105]
	v_mfma_f32_16x16x32_bf16 v[98:101], v[168:171], v[188:191], v[98:101]
	v_mfma_f32_16x16x32_bf16 v[86:89], v[160:163], v[196:199], v[86:89]
	v_mfma_f32_16x16x32_bf16 v[82:85], v[168:171], v[196:199], v[82:85]
	v_mfma_f32_16x16x32_bf16 v[70:73], v[160:163], v[204:207], v[70:73]
	v_mfma_f32_16x16x32_bf16 v[66:69], v[168:171], v[204:207], v[66:69]
	s_barrier
	s_add_i32 s20, s37, s54
	v_lshl_add_u64 v[208:209], v[208:209], 0, s[24:25]
	s_mov_b32 m0, s20
	ds_read_b128 v[176:179], v175 offset:49152
	ds_read_b128 v[180:183], v175 offset:50176
	ds_read_b128 v[184:187], v175 offset:51200
	ds_read_b128 v[188:191], v175 offset:52224
	ds_read_b128 v[192:195], v175 offset:53248
	ds_read_b128 v[196:199], v175 offset:54272
	ds_read_b128 v[200:203], v175 offset:55296
	ds_read_b128 v[204:207], v175 offset:56320
	global_load_lds_dwordx4 v[208:209], off
	s_add_i32 m0, s20, 0x2000
	s_add_u32 s6, s6, 0x40080
	v_lshl_add_u64 v[208:209], v[210:211], 0, s[24:25]
	s_addc_u32 s7, s7, 0
	s_add_i32 s20, s73, s54
	global_load_lds_dwordx4 v[208:209], off
	s_mov_b32 m0, s20
	s_nop 0
	global_load_lds_dwordx4 v0, s[6:7]
	s_add_i32 m0, s20, 0x2000
	s_nop 0
	global_load_lds_dwordx4 v134, s[6:7]
	v_lshl_add_u64 v[208:209], v[214:215], 0, s[24:25]
	s_mov_b32 m0, s62
	s_nop 0
	global_load_lds_dwordx4 v[208:209], off
	v_lshl_add_u64 v[208:209], v[216:217], 0, s[24:25]
	s_mov_b32 m0, s63
	s_nop 0
	global_load_lds_dwordx4 v[208:209], off
	s_waitcnt vmcnt(8)
	s_waitcnt lgkmcnt(0)
	s_barrier
	s_waitcnt lgkmcnt(0)
	v_mfma_f32_16x16x32_bf16 v[62:65], v[140:143], v[176:179], v[62:65]
	v_mfma_f32_16x16x32_bf16 v[58:61], v[148:151], v[176:179], v[58:61]
	v_mfma_f32_16x16x32_bf16 v[46:49], v[140:143], v[184:187], v[46:49]
	v_mfma_f32_16x16x32_bf16 v[42:45], v[148:151], v[184:187], v[42:45]
	v_mfma_f32_16x16x32_bf16 v[30:33], v[140:143], v[192:195], v[30:33]
	v_mfma_f32_16x16x32_bf16 v[26:29], v[148:151], v[192:195], v[26:29]
	v_mfma_f32_16x16x32_bf16 v[14:17], v[140:143], v[200:203], v[14:17]
	v_mfma_f32_16x16x32_bf16 v[10:13], v[148:151], v[200:203], v[10:13]
	v_mfma_f32_16x16x32_bf16 v[62:65], v[144:147], v[180:183], v[62:65]
	v_mfma_f32_16x16x32_bf16 v[58:61], v[152:155], v[180:183], v[58:61]
	v_mfma_f32_16x16x32_bf16 v[46:49], v[144:147], v[188:191], v[46:49]
	v_mfma_f32_16x16x32_bf16 v[42:45], v[152:155], v[188:191], v[42:45]
	v_mfma_f32_16x16x32_bf16 v[30:33], v[144:147], v[196:199], v[30:33]
	v_mfma_f32_16x16x32_bf16 v[26:29], v[152:155], v[196:199], v[26:29]
	v_mfma_f32_16x16x32_bf16 v[14:17], v[144:147], v[204:207], v[14:17]
	v_mfma_f32_16x16x32_bf16 v[10:13], v[152:155], v[204:207], v[10:13]
	v_mfma_f32_16x16x32_bf16 v[54:57], v[156:159], v[176:179], v[54:57]
	v_mfma_f32_16x16x32_bf16 v[50:53], v[164:167], v[176:179], v[50:53]
	v_mfma_f32_16x16x32_bf16 v[38:41], v[156:159], v[184:187], v[38:41]
	v_mfma_f32_16x16x32_bf16 v[34:37], v[164:167], v[184:187], v[34:37]
	v_mfma_f32_16x16x32_bf16 v[22:25], v[156:159], v[192:195], v[22:25]
	v_mfma_f32_16x16x32_bf16 v[18:21], v[164:167], v[192:195], v[18:21]
	v_mfma_f32_16x16x32_bf16 v[6:9], v[156:159], v[200:203], v[6:9]
	v_mfma_f32_16x16x32_bf16 v[2:5], v[164:167], v[200:203], v[2:5]
	v_mfma_f32_16x16x32_bf16 v[54:57], v[160:163], v[180:183], v[54:57]
	v_mfma_f32_16x16x32_bf16 v[50:53], v[168:171], v[180:183], v[50:53]
	v_mfma_f32_16x16x32_bf16 v[38:41], v[160:163], v[188:191], v[38:41]
	v_mfma_f32_16x16x32_bf16 v[34:37], v[168:171], v[188:191], v[34:37]
	v_mfma_f32_16x16x32_bf16 v[22:25], v[160:163], v[196:199], v[22:25]
	v_mfma_f32_16x16x32_bf16 v[18:21], v[168:171], v[196:199], v[18:21]
	v_mfma_f32_16x16x32_bf16 v[6:9], v[160:163], v[204:207], v[6:9]
	v_mfma_f32_16x16x32_bf16 v[2:5], v[168:171], v[204:207], v[2:5]
	s_barrier
	s_add_i32 s72, s72, 2
	s_add_u32 s4, s4, 0x100
	s_addc_u32 s5, s5, 0
	s_add_u32 s19, s19, 0x100
	s_addc_u32 s47, s47, 0
	s_cmp_gt_u32 s72, 13
	s_cbranch_scc0 .LBB0_2148
	s_and_b64 vcc, exec, s[16:17]
	s_cbranch_vccz .LBB0_2151
	s_barrier

.LBB0_2248:
	s_add_u32 s10, s10, 0x8000000
	s_addc_u32 s11, s11, 0
	s_and_b32 s60, s2, 3
	s_add_i32 m0, s56, 0x18000
	v_lshl_add_u64 v[8:9], v[8:9], 0, s[24:25]
	s_lshl_b32 s61, s3, 6
	s_lshl_b32 s4, s3, 13
	s_lshl_b32 s62, s60, 5
	s_lshl_b32 s5, s60, 12
	s_waitcnt vmcnt(2)
	s_barrier
	global_load_lds_dwordx4 v[8:9], off
	v_lshl_add_u64 v[6:7], v[6:7], 0, s[24:25]
	s_add_i32 m0, s56, 0x1a000
	s_add_i32 s63, s56, 0x8000
	s_add_i32 s64, s56, 0xa000
	global_load_lds_dwordx4 v[6:7], off
	v_lshl_add_u64 v[2:3], v[2:3], 0, s[24:25]
	s_mov_b32 m0, s63
	s_add_u32 s2, s46, 0x40080
	global_load_lds_dwordx4 v[2:3], off
	v_lshl_add_u64 v[2:3], v[4:5], 0, s[24:25]
	s_mov_b32 m0, s64
	s_addc_u32 s3, s47, 0
	global_load_lds_dwordx4 v[2:3], off
	s_add_i32 m0, s56, 0x1c000
	global_load_lds_dwordx4 v0, s[2:3]
	v_lshl_add_u64 v[2:3], s[2:3], 0, v[130:131]
	s_add_i32 m0, s56, 0x1e000
	v_bfe_u32 v140, v10, 4, 2
	global_load_lds_dwordx4 v[2:3], off
	v_and_b32_e32 v141, 15, v10
	v_lshlrev_b32_e32 v2, 4, v140
	v_lshlrev_b32_e32 v3, 2, v10
	v_lshl_or_b32 v2, v141, 6, v2
	v_and_b32_e32 v3, 32, v3
	v_bitop3_b32 v4, v2, s4, v3 bitop3:0xde
	v_bitop3_b32 v142, v2, s5, v3 bitop3:0xde
	v_lshlrev_b32_e32 v2, 14, v11
	v_and_b32_e32 v2, 0xffff8000, v2
	v_lshl_add_u32 v2, v12, 11, v2
	v_and_b32_e32 v3, 1, v11
	v_lshl_or_b32 v2, v3, 6, v2
	v_lshl_add_u32 v132, v13, 1, v2
	v_lshlrev_b32_e32 v2, 14, v14
	v_and_b32_e32 v2, 0xffff8000, v2
	s_waitcnt vmcnt(6)
	v_lshl_add_u32 v2, v15, 11, v2
	v_and_b32_e32 v3, 1, v14
	s_cmpk_lt_u32 s12, 0x100
	v_lshl_or_b32 v2, v3, 6, v2
	s_cselect_b64 s[12:13], -1, 0
	s_ashr_i32 s65, s41, 31
	s_ashr_i32 s66, s50, 31
	v_mov_b32_e32 v133, v1
	v_lshl_add_u32 v134, v16, 1, v2
	v_mov_b32_e32 v135, v1
	s_mov_b32 s67, 0
	v_add_u32_e32 v143, 0, v4
	s_barrier
	s_branch .LBB0_2251

.LBB0_2262:
	s_add_u32 s20, s44, 0xfffc0080
	s_addc_u32 s21, s45, -1
	s_add_i32 s37, 0, 0x10000
	s_cmp_eq_u32 s69, 12
	s_cselect_b32 s49, s5, s21
	s_cselect_b32 s48, s4, s20
	s_cselect_b32 s47, s19, s43
	s_cselect_b32 s46, s18, s17
	s_add_i32 s70, 0, 0x14000
	v_add_u32_e32 v152, s37, v142
	v_add_u32_e32 v168, s70, v142
	ds_read_b128 v[136:139], v152
	ds_read_b128 v[144:147], v152 offset:1024
	ds_read_b128 v[148:151], v152 offset:2048
	ds_read_b128 v[152:155], v152 offset:3072
	ds_read_b128 v[156:159], v168
	ds_read_b128 v[160:163], v168 offset:1024
	ds_read_b128 v[164:167], v168 offset:2048
	ds_read_b128 v[168:171], v168 offset:3072
	s_add_i32 m0, s56, 0xc000
	ds_read_b128 v[172:175], v143
	ds_read_b128 v[176:179], v143 offset:1024
	ds_read_b128 v[180:183], v143 offset:2048
	ds_read_b128 v[184:187], v143 offset:3072
	ds_read_b128 v[188:191], v143 offset:4096
	ds_read_b128 v[192:195], v143 offset:5120
	ds_read_b128 v[196:199], v143 offset:6144
	ds_read_b128 v[200:203], v143 offset:7168
	global_load_lds_dwordx4 v132, s[44:45]
	s_add_i32 m0, s56, 0xe000
	s_nop 0
	global_load_lds_dwordx4 v134, s[44:45]
	s_waitcnt vmcnt(8)
	s_waitcnt lgkmcnt(0)
	s_barrier
	s_waitcnt lgkmcnt(0)
	v_mfma_f32_16x16x32_bf16 v[126:129], v[136:139], v[172:175], v[126:129]
	v_mfma_f32_16x16x32_bf16 v[122:125], v[148:151], v[172:175], v[122:125]
	v_mfma_f32_16x16x32_bf16 v[110:113], v[136:139], v[180:183], v[110:113]
	v_mfma_f32_16x16x32_bf16 v[106:109], v[148:151], v[180:183], v[106:109]
	v_mfma_f32_16x16x32_bf16 v[94:97], v[136:139], v[188:191], v[94:97]
	v_mfma_f32_16x16x32_bf16 v[90:93], v[148:151], v[188:191], v[90:93]
	v_mfma_f32_16x16x32_bf16 v[78:81], v[136:139], v[196:199], v[78:81]
	v_mfma_f32_16x16x32_bf16 v[74:77], v[148:151], v[196:199], v[74:77]
	v_mfma_f32_16x16x32_bf16 v[126:129], v[144:147], v[176:179], v[126:129]
	v_mfma_f32_16x16x32_bf16 v[122:125], v[152:155], v[176:179], v[122:125]
	v_mfma_f32_16x16x32_bf16 v[110:113], v[144:147], v[184:187], v[110:113]
	v_mfma_f32_16x16x32_bf16 v[106:109], v[152:155], v[184:187], v[106:109]
	v_mfma_f32_16x16x32_bf16 v[94:97], v[144:147], v[192:195], v[94:97]
	v_mfma_f32_16x16x32_bf16 v[90:93], v[152:155], v[192:195], v[90:93]
	v_mfma_f32_16x16x32_bf16 v[78:81], v[144:147], v[200:203], v[78:81]
	v_mfma_f32_16x16x32_bf16 v[74:77], v[152:155], v[200:203], v[74:77]
	v_mfma_f32_16x16x32_bf16 v[118:121], v[156:159], v[172:175], v[118:121]
	v_mfma_f32_16x16x32_bf16 v[114:117], v[164:167], v[172:175], v[114:117]
	v_mfma_f32_16x16x32_bf16 v[102:105], v[156:159], v[180:183], v[102:105]
	v_mfma_f32_16x16x32_bf16 v[98:101], v[164:167], v[180:183], v[98:101]
	v_mfma_f32_16x16x32_bf16 v[86:89], v[156:159], v[188:191], v[86:89]
	v_mfma_f32_16x16x32_bf16 v[82:85], v[164:167], v[188:191], v[82:85]
	v_mfma_f32_16x16x32_bf16 v[70:73], v[156:159], v[196:199], v[70:73]
	v_mfma_f32_16x16x32_bf16 v[66:69], v[164:167], v[196:199], v[66:69]
	v_mfma_f32_16x16x32_bf16 v[118:121], v[160:163], v[176:179], v[118:121]
	v_mfma_f32_16x16x32_bf16 v[114:117], v[168:171], v[176:179], v[114:117]
	v_mfma_f32_16x16x32_bf16 v[102:105], v[160:163], v[184:187], v[102:105]
	v_mfma_f32_16x16x32_bf16 v[98:101], v[168:171], v[184:187], v[98:101]
	v_mfma_f32_16x16x32_bf16 v[86:89], v[160:163], v[192:195], v[86:89]
	v_mfma_f32_16x16x32_bf16 v[82:85], v[168:171], v[192:195], v[82:85]
	v_mfma_f32_16x16x32_bf16 v[70:73], v[160:163], v[200:203], v[70:73]
	v_mfma_f32_16x16x32_bf16 v[66:69], v[168:171], v[200:203], v[66:69]
	s_barrier
	s_add_i32 s20, s37, s55
	v_lshl_add_u64 v[204:205], s[46:47], 0, v[0:1]
	s_mov_b32 m0, s20
	ds_read_b128 v[172:175], v143 offset:16384
	ds_read_b128 v[176:179], v143 offset:17408
	ds_read_b128 v[180:183], v143 offset:18432
	ds_read_b128 v[184:187], v143 offset:19456
	ds_read_b128 v[188:191], v143 offset:20480
	ds_read_b128 v[192:195], v143 offset:21504
	ds_read_b128 v[196:199], v143 offset:22528
	ds_read_b128 v[200:203], v143 offset:23552
	global_load_lds_dwordx4 v[204:205], off
	s_add_i32 m0, s20, 0x2000
	s_add_u32 s20, s46, 0x40000
	v_lshl_add_u64 v[206:207], s[46:47], 0, v[130:131]
	s_addc_u32 s21, s47, 0
	s_add_i32 s37, s70, s55
	global_load_lds_dwordx4 v[206:207], off
	s_mov_b32 m0, s37
	v_lshl_add_u64 v[210:211], s[48:49], 0, v[130:131]
	global_load_lds_dwordx4 v0, s[20:21]
	s_add_i32 m0, s37, 0x2000
	s_nop 0
	global_load_lds_dwordx4 v130, s[20:21]
	v_lshl_add_u64 v[208:209], s[48:49], 0, v[0:1]
	s_mov_b32 m0, s56
	s_nop 0
	global_load_lds_dwordx4 v[208:209], off
	s_mov_b32 m0, s57
	s_nop 0
	global_load_lds_dwordx4 v[210:211], off
	s_waitcnt vmcnt(8)
	s_waitcnt lgkmcnt(0)
	s_barrier
	s_waitcnt lgkmcnt(0)
	v_mfma_f32_16x16x32_bf16 v[62:65], v[136:139], v[172:175], v[62:65]
	v_mfma_f32_16x16x32_bf16 v[58:61], v[148:151], v[172:175], v[58:61]
	v_mfma_f32_16x16x32_bf16 v[46:49], v[136:139], v[180:183], v[46:49]
	v_mfma_f32_16x16x32_bf16 v[42:45], v[148:151], v[180:183], v[42:45]
	v_mfma_f32_16x16x32_bf16 v[30:33], v[136:139], v[188:191], v[30:33]
	v_mfma_f32_16x16x32_bf16 v[26:29], v[148:151], v[188:191], v[26:29]
	v_mfma_f32_16x16x32_bf16 v[14:17], v[136:139], v[196:199], v[14:17]
	v_mfma_f32_16x16x32_bf16 v[10:13], v[148:151], v[196:199], v[10:13]
	v_mfma_f32_16x16x32_bf16 v[62:65], v[144:147], v[176:179], v[62:65]
	v_mfma_f32_16x16x32_bf16 v[58:61], v[152:155], v[176:179], v[58:61]
	v_mfma_f32_16x16x32_bf16 v[46:49], v[144:147], v[184:187], v[46:49]
	v_mfma_f32_16x16x32_bf16 v[42:45], v[152:155], v[184:187], v[42:45]
	v_mfma_f32_16x16x32_bf16 v[30:33], v[144:147], v[192:195], v[30:33]
	v_mfma_f32_16x16x32_bf16 v[26:29], v[152:155], v[192:195], v[26:29]
	v_mfma_f32_16x16x32_bf16 v[14:17], v[144:147], v[200:203], v[14:17]
	v_mfma_f32_16x16x32_bf16 v[10:13], v[152:155], v[200:203], v[10:13]
	v_mfma_f32_16x16x32_bf16 v[54:57], v[156:159], v[172:175], v[54:57]
	v_mfma_f32_16x16x32_bf16 v[50:53], v[164:167], v[172:175], v[50:53]
	v_mfma_f32_16x16x32_bf16 v[38:41], v[156:159], v[180:183], v[38:41]
	v_mfma_f32_16x16x32_bf16 v[34:37], v[164:167], v[180:183], v[34:37]
	v_mfma_f32_16x16x32_bf16 v[22:25], v[156:159], v[188:191], v[22:25]
	v_mfma_f32_16x16x32_bf16 v[18:21], v[164:167], v[188:191], v[18:21]
	v_mfma_f32_16x16x32_bf16 v[6:9], v[156:159], v[196:199], v[6:9]
	v_mfma_f32_16x16x32_bf16 v[2:5], v[164:167], v[196:199], v[2:5]
	v_mfma_f32_16x16x32_bf16 v[54:57], v[160:163], v[176:179], v[54:57]
	v_mfma_f32_16x16x32_bf16 v[50:53], v[168:171], v[176:179], v[50:53]
	v_mfma_f32_16x16x32_bf16 v[38:41], v[160:163], v[184:187], v[38:41]
	v_mfma_f32_16x16x32_bf16 v[34:37], v[168:171], v[184:187], v[34:37]
	v_mfma_f32_16x16x32_bf16 v[22:25], v[160:163], v[192:195], v[22:25]
	v_mfma_f32_16x16x32_bf16 v[18:21], v[168:171], v[192:195], v[18:21]
	v_mfma_f32_16x16x32_bf16 v[6:9], v[160:163], v[200:203], v[6:9]
	v_mfma_f32_16x16x32_bf16 v[2:5], v[168:171], v[200:203], v[2:5]
	s_barrier
	s_add_i32 s37, 0, 0x18000
	s_add_i32 s70, 0, 0x1c000
	v_add_u32_e32 v152, s37, v142
	v_add_u32_e32 v168, s70, v142
	ds_read_b128 v[136:139], v152
	ds_read_b128 v[144:147], v152 offset:1024
	ds_read_b128 v[148:151], v152 offset:2048
	ds_read_b128 v[152:155], v152 offset:3072
	ds_read_b128 v[156:159], v168
	ds_read_b128 v[160:163], v168 offset:1024
	ds_read_b128 v[164:167], v168 offset:2048
	ds_read_b128 v[168:171], v168 offset:3072
	s_add_u32 s20, s48, 0x40000
	s_addc_u32 s21, s49, 0
	s_mov_b32 m0, s58
	ds_read_b128 v[172:175], v143 offset:32768
	ds_read_b128 v[176:179], v143 offset:33792
	ds_read_b128 v[180:183], v143 offset:34816
	ds_read_b128 v[184:187], v143 offset:35840
	ds_read_b128 v[188:191], v143 offset:36864
	ds_read_b128 v[192:195], v143 offset:37888
	ds_read_b128 v[196:199], v143 offset:38912
	ds_read_b128 v[200:203], v143 offset:39936
	global_load_lds_dwordx4 v0, s[20:21]
	v_lshl_add_u64 v[214:215], s[20:21], 0, v[130:131]
	s_mov_b32 m0, s59
	s_nop 0
	global_load_lds_dwordx4 v[214:215], off
	s_waitcnt vmcnt(8)
	s_waitcnt lgkmcnt(0)
	s_barrier
	s_waitcnt lgkmcnt(0)
	v_mfma_f32_16x16x32_bf16 v[126:129], v[136:139], v[172:175], v[126:129]
	v_mfma_f32_16x16x32_bf16 v[122:125], v[148:151], v[172:175], v[122:125]
	v_mfma_f32_16x16x32_bf16 v[110:113], v[136:139], v[180:183], v[110:113]
	v_mfma_f32_16x16x32_bf16 v[106:109], v[148:151], v[180:183], v[106:109]
	v_mfma_f32_16x16x32_bf16 v[94:97], v[136:139], v[188:191], v[94:97]
	v_mfma_f32_16x16x32_bf16 v[90:93], v[148:151], v[188:191], v[90:93]
	v_mfma_f32_16x16x32_bf16 v[78:81], v[136:139], v[196:199], v[78:81]
	v_mfma_f32_16x16x32_bf16 v[74:77], v[148:151], v[196:199], v[74:77]
	v_mfma_f32_16x16x32_bf16 v[126:129], v[144:147], v[176:179], v[126:129]
	v_mfma_f32_16x16x32_bf16 v[122:125], v[152:155], v[176:179], v[122:125]
	v_mfma_f32_16x16x32_bf16 v[110:113], v[144:147], v[184:187], v[110:113]
	v_mfma_f32_16x16x32_bf16 v[106:109], v[152:155], v[184:187], v[106:109]
	v_mfma_f32_16x16x32_bf16 v[94:97], v[144:147], v[192:195], v[94:97]
	v_mfma_f32_16x16x32_bf16 v[90:93], v[152:155], v[192:195], v[90:93]
	v_mfma_f32_16x16x32_bf16 v[78:81], v[144:147], v[200:203], v[78:81]
	v_mfma_f32_16x16x32_bf16 v[74:77], v[152:155], v[200:203], v[74:77]
	v_mfma_f32_16x16x32_bf16 v[118:121], v[156:159], v[172:175], v[118:121]
	v_mfma_f32_16x16x32_bf16 v[114:117], v[164:167], v[172:175], v[114:117]
	v_mfma_f32_16x16x32_bf16 v[102:105], v[156:159], v[180:183], v[102:105]
	v_mfma_f32_16x16x32_bf16 v[98:101], v[164:167], v[180:183], v[98:101]
	v_mfma_f32_16x16x32_bf16 v[86:89], v[156:159], v[188:191], v[86:89]
	v_mfma_f32_16x16x32_bf16 v[82:85], v[164:167], v[188:191], v[82:85]
	v_mfma_f32_16x16x32_bf16 v[70:73], v[156:159], v[196:199], v[70:73]
	v_mfma_f32_16x16x32_bf16 v[66:69], v[164:167], v[196:199], v[66:69]
	v_mfma_f32_16x16x32_bf16 v[118:121], v[160:163], v[176:179], v[118:121]
	v_mfma_f32_16x16x32_bf16 v[114:117], v[168:171], v[176:179], v[114:117]
	v_mfma_f32_16x16x32_bf16 v[102:105], v[160:163], v[184:187], v[102:105]
	v_mfma_f32_16x16x32_bf16 v[98:101], v[168:171], v[184:187], v[98:101]
	v_mfma_f32_16x16x32_bf16 v[86:89], v[160:163], v[192:195], v[86:89]
	v_mfma_f32_16x16x32_bf16 v[82:85], v[168:171], v[192:195], v[82:85]
	v_mfma_f32_16x16x32_bf16 v[70:73], v[160:163], v[200:203], v[70:73]
	v_mfma_f32_16x16x32_bf16 v[66:69], v[168:171], v[200:203], v[66:69]
	s_barrier
	s_add_i32 s20, s37, s55
	v_lshl_add_u64 v[204:205], v[204:205], 0, s[24:25]
	s_mov_b32 m0, s20
	ds_read_b128 v[172:175], v143 offset:49152
	ds_read_b128 v[176:179], v143 offset:50176
	ds_read_b128 v[180:183], v143 offset:51200
	ds_read_b128 v[184:187], v143 offset:52224
	ds_read_b128 v[188:191], v143 offset:53248
	ds_read_b128 v[192:195], v143 offset:54272
	ds_read_b128 v[196:199], v143 offset:55296
	ds_read_b128 v[200:203], v143 offset:56320
	global_load_lds_dwordx4 v[204:205], off
	s_add_i32 m0, s20, 0x2000
	s_add_u32 s20, s46, 0x40080
	v_lshl_add_u64 v[204:205], v[206:207], 0, s[24:25]
	s_addc_u32 s21, s47, 0
	s_add_i32 s37, s70, s55
	global_load_lds_dwordx4 v[204:205], off
	s_mov_b32 m0, s37
	s_nop 0
	global_load_lds_dwordx4 v0, s[20:21]
	s_add_i32 m0, s37, 0x2000
	s_nop 0
	global_load_lds_dwordx4 v130, s[20:21]
	v_lshl_add_u64 v[204:205], v[208:209], 0, s[24:25]
	s_mov_b32 m0, s63
	s_nop 0
	global_load_lds_dwordx4 v[204:205], off
	v_lshl_add_u64 v[204:205], v[210:211], 0, s[24:25]
	s_mov_b32 m0, s64
	s_nop 0
	global_load_lds_dwordx4 v[204:205], off
	s_waitcnt vmcnt(8)
	s_waitcnt lgkmcnt(0)
	s_barrier
	s_waitcnt lgkmcnt(0)
	v_mfma_f32_16x16x32_bf16 v[62:65], v[136:139], v[172:175], v[62:65]
	v_mfma_f32_16x16x32_bf16 v[58:61], v[148:151], v[172:175], v[58:61]
	v_mfma_f32_16x16x32_bf16 v[46:49], v[136:139], v[180:183], v[46:49]
	v_mfma_f32_16x16x32_bf16 v[42:45], v[148:151], v[180:183], v[42:45]
	v_mfma_f32_16x16x32_bf16 v[30:33], v[136:139], v[188:191], v[30:33]
	v_mfma_f32_16x16x32_bf16 v[26:29], v[148:151], v[188:191], v[26:29]
	v_mfma_f32_16x16x32_bf16 v[14:17], v[136:139], v[196:199], v[14:17]
	v_mfma_f32_16x16x32_bf16 v[10:13], v[148:151], v[196:199], v[10:13]
	v_mfma_f32_16x16x32_bf16 v[62:65], v[144:147], v[176:179], v[62:65]
	v_mfma_f32_16x16x32_bf16 v[58:61], v[152:155], v[176:179], v[58:61]
	v_mfma_f32_16x16x32_bf16 v[46:49], v[144:147], v[184:187], v[46:49]
	v_mfma_f32_16x16x32_bf16 v[42:45], v[152:155], v[184:187], v[42:45]
	v_mfma_f32_16x16x32_bf16 v[30:33], v[144:147], v[192:195], v[30:33]
	v_mfma_f32_16x16x32_bf16 v[26:29], v[152:155], v[192:195], v[26:29]
	v_mfma_f32_16x16x32_bf16 v[14:17], v[144:147], v[200:203], v[14:17]
	v_mfma_f32_16x16x32_bf16 v[10:13], v[152:155], v[200:203], v[10:13]
	v_mfma_f32_16x16x32_bf16 v[54:57], v[156:159], v[172:175], v[54:57]
	v_mfma_f32_16x16x32_bf16 v[50:53], v[164:167], v[172:175], v[50:53]
	v_mfma_f32_16x16x32_bf16 v[38:41], v[156:159], v[180:183], v[38:41]
	v_mfma_f32_16x16x32_bf16 v[34:37], v[164:167], v[180:183], v[34:37]
	v_mfma_f32_16x16x32_bf16 v[22:25], v[156:159], v[188:191], v[22:25]
	v_mfma_f32_16x16x32_bf16 v[18:21], v[164:167], v[188:191], v[18:21]
	v_mfma_f32_16x16x32_bf16 v[6:9], v[156:159], v[196:199], v[6:9]
	v_mfma_f32_16x16x32_bf16 v[2:5], v[164:167], v[196:199], v[2:5]
	v_mfma_f32_16x16x32_bf16 v[54:57], v[160:163], v[176:179], v[54:57]
	v_mfma_f32_16x16x32_bf16 v[50:53], v[168:171], v[176:179], v[50:53]
	v_mfma_f32_16x16x32_bf16 v[38:41], v[160:163], v[184:187], v[38:41]
	v_mfma_f32_16x16x32_bf16 v[34:37], v[168:171], v[184:187], v[34:37]
	v_mfma_f32_16x16x32_bf16 v[22:25], v[160:163], v[192:195], v[22:25]
	v_mfma_f32_16x16x32_bf16 v[18:21], v[168:171], v[192:195], v[18:21]
	v_mfma_f32_16x16x32_bf16 v[6:9], v[160:163], v[200:203], v[6:9]
	v_mfma_f32_16x16x32_bf16 v[2:5], v[168:171], v[200:203], v[2:5]
	s_barrier
	s_add_i32 s69, s69, 2
	s_add_u32 s44, s44, 0x100
	s_addc_u32 s45, s45, 0
	s_add_u32 s17, s17, 0x100
	s_addc_u32 s43, s43, 0
	s_cmp_gt_u32 s69, 13
	s_cbranch_scc0 .LBB0_2262
	s_and_b64 vcc, exec, s[12:13]
	s_cbranch_vccz .LBB0_2265
	s_barrier

.LBB0_2416:
	s_add_u32 s40, s18, 0x10000000
	s_addc_u32 s41, s19, 0
	s_add_u32 s18, s18, 0x8000000
	s_addc_u32 s19, s19, 0
	s_lshl_b32 s2, s2, 5
	s_and_b32 s2, s2, 0x60
	s_add_i32 m0, s57, 0x18000
	v_lshl_add_u64 v[8:9], v[8:9], 0, s[24:25]
	s_lshl_b32 s7, s3, 13
	s_lshl_b32 s20, s2, 7
	s_waitcnt vmcnt(2)
	s_barrier
	global_load_lds_dwordx4 v[8:9], off
	v_lshl_add_u64 v[6:7], v[6:7], 0, s[24:25]
	s_add_i32 m0, s57, 0x1a000
	s_add_i32 s61, s57, 0x8000
	s_add_i32 s62, s57, 0xa000
	global_load_lds_dwordx4 v[6:7], off
	v_lshl_add_u64 v[2:3], v[2:3], 0, s[24:25]
	s_mov_b32 m0, s61
	s_add_u32 s4, s8, 0x40080
	global_load_lds_dwordx4 v[2:3], off
	v_lshl_add_u64 v[2:3], v[4:5], 0, s[24:25]
	s_mov_b32 m0, s62
	s_addc_u32 s5, s9, 0
	global_load_lds_dwordx4 v[2:3], off
	s_add_i32 m0, s57, 0x1c000
	global_load_lds_dwordx4 v0, s[4:5]
	v_lshl_add_u64 v[2:3], s[4:5], 0, v[134:135]
	s_add_i32 m0, s57, 0x1e000
	s_cmpk_lt_u32 s44, 0x100
	global_load_lds_dwordx4 v[2:3], off
	v_lshrrev_b32_e32 v3, 1, v10
	v_and_b32_e32 v3, 24, v3
	v_and_b32_e32 v2, 15, v10
	v_lshlrev_b32_e32 v4, 1, v3
	v_lshl_or_b32 v146, s3, 6, v2
	v_lshl_or_b32 v2, v2, 6, v4
	v_lshlrev_b32_e32 v4, 2, v10
	v_and_b32_e32 v4, 32, v4
	v_bitop3_b32 v5, v2, s7, v4 bitop3:0xde
	v_bitop3_b32 v147, v2, s20, v4 bitop3:0xde
	v_lshlrev_b32_e32 v2, 14, v11
	v_and_b32_e32 v2, 0xffff8000, v2
	v_or_b32_e32 v148, s2, v3
	v_lshl_add_u32 v2, v12, 11, v2
	v_and_b32_e32 v3, 1, v11
	v_lshl_or_b32 v2, v3, 6, v2
	v_lshl_add_u32 v136, v13, 1, v2
	v_lshlrev_b32_e32 v2, 14, v14
	v_and_b32_e32 v2, 0xffff8000, v2
	s_waitcnt vmcnt(6)
	v_lshl_add_u32 v2, v15, 11, v2
	v_and_b32_e32 v3, 1, v14
	v_lshl_or_b32 v2, v3, 6, v2
	s_cselect_b64 s[44:45], -1, 0
	s_ashr_i32 s63, s13, 31
	s_ashr_i32 s64, s22, 31
	v_mov_b32_e32 v137, v1
	v_lshl_add_u32 v138, v16, 1, v2
	v_mov_b32_e32 v139, v1
	s_mov_b32 s65, 0
	v_add_u32_e32 v149, 0, v5
	s_barrier
	s_branch .LBB0_2419

.LBB0_2428:
	s_add_u32 s8, s4, 0xfffc0080
	s_addc_u32 s9, s5, -1
	s_add_i32 s20, 0, 0x10000
	s_cmp_eq_u32 s70, 12
	s_cselect_b32 s53, s49, s9
	s_cselect_b32 s52, s48, s8
	v_add_u32_e32 v144, s20, v147
	s_cselect_b32 s9, s7, s69
	s_cselect_b32 s8, s47, s68
	s_add_i32 s37, 0, 0x14000
	ds_read_b128 v[140:143], v144
	ds_read_b128 v[150:153], v144 offset:1024
	ds_read_b128 v[154:157], v144 offset:2048
	ds_read_b128 v[158:161], v144 offset:3072
	v_add_u32_e32 v144, s37, v147
	ds_read_b128 v[162:165], v144
	ds_read_b128 v[166:169], v144 offset:1024
	ds_read_b128 v[170:173], v144 offset:2048
	ds_read_b128 v[174:177], v144 offset:3072
	s_add_i32 m0, s57, 0xc000
	ds_read_b128 v[178:181], v149
	ds_read_b128 v[182:185], v149 offset:1024
	ds_read_b128 v[186:189], v149 offset:2048
	ds_read_b128 v[190:193], v149 offset:3072
	ds_read_b128 v[194:197], v149 offset:4096
	ds_read_b128 v[198:201], v149 offset:5120
	ds_read_b128 v[202:205], v149 offset:6144
	ds_read_b128 v[206:209], v149 offset:7168
	global_load_lds_dwordx4 v136, s[4:5]
	s_add_i32 m0, s57, 0xe000
	s_nop 0
	global_load_lds_dwordx4 v138, s[4:5]
	s_waitcnt vmcnt(8)
	s_waitcnt lgkmcnt(0)
	s_barrier
	s_waitcnt lgkmcnt(0)
	v_mfma_f32_16x16x32_bf16 v[126:129], v[140:143], v[178:181], v[126:129]
	v_mfma_f32_16x16x32_bf16 v[122:125], v[154:157], v[178:181], v[122:125]
	v_mfma_f32_16x16x32_bf16 v[110:113], v[140:143], v[186:189], v[110:113]
	v_mfma_f32_16x16x32_bf16 v[106:109], v[154:157], v[186:189], v[106:109]
	v_mfma_f32_16x16x32_bf16 v[94:97], v[140:143], v[194:197], v[94:97]
	v_mfma_f32_16x16x32_bf16 v[90:93], v[154:157], v[194:197], v[90:93]
	v_mfma_f32_16x16x32_bf16 v[78:81], v[140:143], v[202:205], v[78:81]
	v_mfma_f32_16x16x32_bf16 v[74:77], v[154:157], v[202:205], v[74:77]
	v_mfma_f32_16x16x32_bf16 v[126:129], v[150:153], v[182:185], v[126:129]
	v_mfma_f32_16x16x32_bf16 v[122:125], v[158:161], v[182:185], v[122:125]
	v_mfma_f32_16x16x32_bf16 v[110:113], v[150:153], v[190:193], v[110:113]
	v_mfma_f32_16x16x32_bf16 v[106:109], v[158:161], v[190:193], v[106:109]
	v_mfma_f32_16x16x32_bf16 v[94:97], v[150:153], v[198:201], v[94:97]
	v_mfma_f32_16x16x32_bf16 v[90:93], v[158:161], v[198:201], v[90:93]
	v_mfma_f32_16x16x32_bf16 v[78:81], v[150:153], v[206:209], v[78:81]
	v_mfma_f32_16x16x32_bf16 v[74:77], v[158:161], v[206:209], v[74:77]
	v_mfma_f32_16x16x32_bf16 v[118:121], v[162:165], v[178:181], v[118:121]
	v_mfma_f32_16x16x32_bf16 v[114:117], v[170:173], v[178:181], v[114:117]
	v_mfma_f32_16x16x32_bf16 v[102:105], v[162:165], v[186:189], v[102:105]
	v_mfma_f32_16x16x32_bf16 v[98:101], v[170:173], v[186:189], v[98:101]
	v_mfma_f32_16x16x32_bf16 v[86:89], v[162:165], v[194:197], v[86:89]
	v_mfma_f32_16x16x32_bf16 v[82:85], v[170:173], v[194:197], v[82:85]
	v_mfma_f32_16x16x32_bf16 v[70:73], v[162:165], v[202:205], v[70:73]
	v_mfma_f32_16x16x32_bf16 v[66:69], v[170:173], v[202:205], v[66:69]
	v_mfma_f32_16x16x32_bf16 v[118:121], v[166:169], v[182:185], v[118:121]
	v_mfma_f32_16x16x32_bf16 v[114:117], v[174:177], v[182:185], v[114:117]
	v_mfma_f32_16x16x32_bf16 v[102:105], v[166:169], v[190:193], v[102:105]
	v_mfma_f32_16x16x32_bf16 v[98:101], v[174:177], v[190:193], v[98:101]
	v_mfma_f32_16x16x32_bf16 v[86:89], v[166:169], v[198:201], v[86:89]
	v_mfma_f32_16x16x32_bf16 v[82:85], v[174:177], v[198:201], v[82:85]
	v_mfma_f32_16x16x32_bf16 v[70:73], v[166:169], v[206:209], v[70:73]
	v_mfma_f32_16x16x32_bf16 v[66:69], v[174:177], v[206:209], v[66:69]
	s_barrier
	s_add_i32 s20, s20, s56
	v_lshl_add_u64 v[144:145], s[8:9], 0, v[0:1]
	s_mov_b32 m0, s20
	ds_read_b128 v[178:181], v149 offset:16384
	ds_read_b128 v[182:185], v149 offset:17408
	ds_read_b128 v[186:189], v149 offset:18432
	ds_read_b128 v[190:193], v149 offset:19456
	ds_read_b128 v[194:197], v149 offset:20480
	ds_read_b128 v[198:201], v149 offset:21504
	ds_read_b128 v[202:205], v149 offset:22528
	ds_read_b128 v[206:209], v149 offset:23552
	global_load_lds_dwordx4 v[144:145], off
	s_add_i32 m0, s20, 0x2000
	s_add_u32 s20, s8, 0x40000
	v_lshl_add_u64 v[210:211], s[8:9], 0, v[134:135]
	s_addc_u32 s21, s9, 0
	s_add_i32 s37, s37, s56
	global_load_lds_dwordx4 v[210:211], off
	s_mov_b32 m0, s37
	v_lshl_add_u64 v[216:217], s[52:53], 0, v[132:133]
	global_load_lds_dwordx4 v0, s[20:21]
	s_add_i32 m0, s37, 0x2000
	s_nop 0
	global_load_lds_dwordx4 v134, s[20:21]
	v_lshl_add_u64 v[214:215], s[52:53], 0, v[130:131]
	s_mov_b32 m0, s57
	s_nop 0
	global_load_lds_dwordx4 v[214:215], off
	s_mov_b32 m0, s58
	s_nop 0
	global_load_lds_dwordx4 v[216:217], off
	s_waitcnt vmcnt(8)
	s_waitcnt lgkmcnt(0)
	s_barrier
	s_waitcnt lgkmcnt(0)
	v_mfma_f32_16x16x32_bf16 v[62:65], v[140:143], v[178:181], v[62:65]
	v_mfma_f32_16x16x32_bf16 v[58:61], v[154:157], v[178:181], v[58:61]
	v_mfma_f32_16x16x32_bf16 v[46:49], v[140:143], v[186:189], v[46:49]
	v_mfma_f32_16x16x32_bf16 v[42:45], v[154:157], v[186:189], v[42:45]
	v_mfma_f32_16x16x32_bf16 v[30:33], v[140:143], v[194:197], v[30:33]
	v_mfma_f32_16x16x32_bf16 v[26:29], v[154:157], v[194:197], v[26:29]
	v_mfma_f32_16x16x32_bf16 v[14:17], v[140:143], v[202:205], v[14:17]
	v_mfma_f32_16x16x32_bf16 v[10:13], v[154:157], v[202:205], v[10:13]
	v_mfma_f32_16x16x32_bf16 v[62:65], v[150:153], v[182:185], v[62:65]
	v_mfma_f32_16x16x32_bf16 v[58:61], v[158:161], v[182:185], v[58:61]
	v_mfma_f32_16x16x32_bf16 v[46:49], v[150:153], v[190:193], v[46:49]
	v_mfma_f32_16x16x32_bf16 v[42:45], v[158:161], v[190:193], v[42:45]
	v_mfma_f32_16x16x32_bf16 v[30:33], v[150:153], v[198:201], v[30:33]
	v_mfma_f32_16x16x32_bf16 v[26:29], v[158:161], v[198:201], v[26:29]
	v_mfma_f32_16x16x32_bf16 v[14:17], v[150:153], v[206:209], v[14:17]
	v_mfma_f32_16x16x32_bf16 v[10:13], v[158:161], v[206:209], v[10:13]
	v_mfma_f32_16x16x32_bf16 v[54:57], v[162:165], v[178:181], v[54:57]
	v_mfma_f32_16x16x32_bf16 v[50:53], v[170:173], v[178:181], v[50:53]
	v_mfma_f32_16x16x32_bf16 v[38:41], v[162:165], v[186:189], v[38:41]
	v_mfma_f32_16x16x32_bf16 v[34:37], v[170:173], v[186:189], v[34:37]
	v_mfma_f32_16x16x32_bf16 v[22:25], v[162:165], v[194:197], v[22:25]
	v_mfma_f32_16x16x32_bf16 v[18:21], v[170:173], v[194:197], v[18:21]
	v_mfma_f32_16x16x32_bf16 v[6:9], v[162:165], v[202:205], v[6:9]
	v_mfma_f32_16x16x32_bf16 v[2:5], v[170:173], v[202:205], v[2:5]
	v_mfma_f32_16x16x32_bf16 v[54:57], v[166:169], v[182:185], v[54:57]
	v_mfma_f32_16x16x32_bf16 v[50:53], v[174:177], v[182:185], v[50:53]
	v_mfma_f32_16x16x32_bf16 v[38:41], v[166:169], v[190:193], v[38:41]
	v_mfma_f32_16x16x32_bf16 v[34:37], v[174:177], v[190:193], v[34:37]
	v_mfma_f32_16x16x32_bf16 v[22:25], v[166:169], v[198:201], v[22:25]
	v_mfma_f32_16x16x32_bf16 v[18:21], v[174:177], v[198:201], v[18:21]
	v_mfma_f32_16x16x32_bf16 v[6:9], v[166:169], v[206:209], v[6:9]
	v_mfma_f32_16x16x32_bf16 v[2:5], v[174:177], v[206:209], v[2:5]
	s_barrier
	s_add_i32 s37, 0, 0x18000
	s_add_i32 s71, 0, 0x1c000
	v_add_u32_e32 v158, s37, v147
	v_add_u32_e32 v174, s71, v147
	ds_read_b128 v[140:143], v158
	ds_read_b128 v[150:153], v158 offset:1024
	ds_read_b128 v[154:157], v158 offset:2048
	ds_read_b128 v[158:161], v158 offset:3072
	ds_read_b128 v[162:165], v174
	ds_read_b128 v[166:169], v174 offset:1024
	ds_read_b128 v[170:173], v174 offset:2048
	ds_read_b128 v[174:177], v174 offset:3072
	s_add_u32 s20, s52, 0x40000
	s_addc_u32 s21, s53, 0
	s_mov_b32 m0, s59
	ds_read_b128 v[178:181], v149 offset:32768
	ds_read_b128 v[182:185], v149 offset:33792
	ds_read_b128 v[186:189], v149 offset:34816
	ds_read_b128 v[190:193], v149 offset:35840
	ds_read_b128 v[194:197], v149 offset:36864
	ds_read_b128 v[198:201], v149 offset:37888
	ds_read_b128 v[202:205], v149 offset:38912
	ds_read_b128 v[206:209], v149 offset:39936
	global_load_lds_dwordx4 v130, s[20:21]
	v_lshl_add_u64 v[218:219], s[20:21], 0, v[132:133]
	s_mov_b32 m0, s60
	s_nop 0
	global_load_lds_dwordx4 v[218:219], off
	s_waitcnt vmcnt(8)
	s_waitcnt lgkmcnt(0)
	s_barrier
	s_waitcnt lgkmcnt(0)
	v_mfma_f32_16x16x32_bf16 v[126:129], v[140:143], v[178:181], v[126:129]
	v_mfma_f32_16x16x32_bf16 v[122:125], v[154:157], v[178:181], v[122:125]
	v_mfma_f32_16x16x32_bf16 v[110:113], v[140:143], v[186:189], v[110:113]
	v_mfma_f32_16x16x32_bf16 v[106:109], v[154:157], v[186:189], v[106:109]
	v_mfma_f32_16x16x32_bf16 v[94:97], v[140:143], v[194:197], v[94:97]
	v_mfma_f32_16x16x32_bf16 v[90:93], v[154:157], v[194:197], v[90:93]
	v_mfma_f32_16x16x32_bf16 v[78:81], v[140:143], v[202:205], v[78:81]
	v_mfma_f32_16x16x32_bf16 v[74:77], v[154:157], v[202:205], v[74:77]
	v_mfma_f32_16x16x32_bf16 v[126:129], v[150:153], v[182:185], v[126:129]
	v_mfma_f32_16x16x32_bf16 v[122:125], v[158:161], v[182:185], v[122:125]
	v_mfma_f32_16x16x32_bf16 v[110:113], v[150:153], v[190:193], v[110:113]
	v_mfma_f32_16x16x32_bf16 v[106:109], v[158:161], v[190:193], v[106:109]
	v_mfma_f32_16x16x32_bf16 v[94:97], v[150:153], v[198:201], v[94:97]
	v_mfma_f32_16x16x32_bf16 v[90:93], v[158:161], v[198:201], v[90:93]
	v_mfma_f32_16x16x32_bf16 v[78:81], v[150:153], v[206:209], v[78:81]
	v_mfma_f32_16x16x32_bf16 v[74:77], v[158:161], v[206:209], v[74:77]
	v_mfma_f32_16x16x32_bf16 v[118:121], v[162:165], v[178:181], v[118:121]
	v_mfma_f32_16x16x32_bf16 v[114:117], v[170:173], v[178:181], v[114:117]
	v_mfma_f32_16x16x32_bf16 v[102:105], v[162:165], v[186:189], v[102:105]
	v_mfma_f32_16x16x32_bf16 v[98:101], v[170:173], v[186:189], v[98:101]
	v_mfma_f32_16x16x32_bf16 v[86:89], v[162:165], v[194:197], v[86:89]
	v_mfma_f32_16x16x32_bf16 v[82:85], v[170:173], v[194:197], v[82:85]
	v_mfma_f32_16x16x32_bf16 v[70:73], v[162:165], v[202:205], v[70:73]
	v_mfma_f32_16x16x32_bf16 v[66:69], v[170:173], v[202:205], v[66:69]
	v_mfma_f32_16x16x32_bf16 v[118:121], v[166:169], v[182:185], v[118:121]
	v_mfma_f32_16x16x32_bf16 v[114:117], v[174:177], v[182:185], v[114:117]
	v_mfma_f32_16x16x32_bf16 v[102:105], v[166:169], v[190:193], v[102:105]
	v_mfma_f32_16x16x32_bf16 v[98:101], v[174:177], v[190:193], v[98:101]
	v_mfma_f32_16x16x32_bf16 v[86:89], v[166:169], v[198:201], v[86:89]
	v_mfma_f32_16x16x32_bf16 v[82:85], v[174:177], v[198:201], v[82:85]
	v_mfma_f32_16x16x32_bf16 v[70:73], v[166:169], v[206:209], v[70:73]
	v_mfma_f32_16x16x32_bf16 v[66:69], v[174:177], v[206:209], v[66:69]
	s_barrier
	s_add_i32 s20, s37, s56
	v_lshl_add_u64 v[144:145], v[144:145], 0, s[24:25]
	s_mov_b32 m0, s20
	ds_read_b128 v[178:181], v149 offset:49152
	ds_read_b128 v[182:185], v149 offset:50176
	ds_read_b128 v[186:189], v149 offset:51200
	ds_read_b128 v[190:193], v149 offset:52224
	ds_read_b128 v[194:197], v149 offset:53248
	ds_read_b128 v[198:201], v149 offset:54272
	ds_read_b128 v[202:205], v149 offset:55296
	ds_read_b128 v[206:209], v149 offset:56320
	global_load_lds_dwordx4 v[144:145], off
	s_add_i32 m0, s20, 0x2000
	s_add_u32 s8, s8, 0x40080
	v_lshl_add_u64 v[144:145], v[210:211], 0, s[24:25]
	s_addc_u32 s9, s9, 0
	s_add_i32 s20, s71, s56
	global_load_lds_dwordx4 v[144:145], off
	s_mov_b32 m0, s20
	s_nop 0
	global_load_lds_dwordx4 v0, s[8:9]
	s_add_i32 m0, s20, 0x2000
	s_nop 0
	global_load_lds_dwordx4 v134, s[8:9]
	v_lshl_add_u64 v[144:145], v[214:215], 0, s[24:25]
	s_mov_b32 m0, s61
	s_nop 0
	global_load_lds_dwordx4 v[144:145], off
	v_lshl_add_u64 v[144:145], v[216:217], 0, s[24:25]
	s_mov_b32 m0, s62
	s_nop 0
	global_load_lds_dwordx4 v[144:145], off
	s_waitcnt vmcnt(8)
	s_waitcnt lgkmcnt(0)
	s_barrier
	s_waitcnt lgkmcnt(0)
	v_mfma_f32_16x16x32_bf16 v[62:65], v[140:143], v[178:181], v[62:65]
	v_mfma_f32_16x16x32_bf16 v[58:61], v[154:157], v[178:181], v[58:61]
	v_mfma_f32_16x16x32_bf16 v[46:49], v[140:143], v[186:189], v[46:49]
	v_mfma_f32_16x16x32_bf16 v[42:45], v[154:157], v[186:189], v[42:45]
	v_mfma_f32_16x16x32_bf16 v[30:33], v[140:143], v[194:197], v[30:33]
	v_mfma_f32_16x16x32_bf16 v[26:29], v[154:157], v[194:197], v[26:29]
	v_mfma_f32_16x16x32_bf16 v[14:17], v[140:143], v[202:205], v[14:17]
	v_mfma_f32_16x16x32_bf16 v[10:13], v[154:157], v[202:205], v[10:13]
	v_mfma_f32_16x16x32_bf16 v[62:65], v[150:153], v[182:185], v[62:65]
	v_mfma_f32_16x16x32_bf16 v[58:61], v[158:161], v[182:185], v[58:61]
	v_mfma_f32_16x16x32_bf16 v[46:49], v[150:153], v[190:193], v[46:49]
	v_mfma_f32_16x16x32_bf16 v[42:45], v[158:161], v[190:193], v[42:45]
	v_mfma_f32_16x16x32_bf16 v[30:33], v[150:153], v[198:201], v[30:33]
	v_mfma_f32_16x16x32_bf16 v[26:29], v[158:161], v[198:201], v[26:29]
	v_mfma_f32_16x16x32_bf16 v[14:17], v[150:153], v[206:209], v[14:17]
	v_mfma_f32_16x16x32_bf16 v[10:13], v[158:161], v[206:209], v[10:13]
	v_mfma_f32_16x16x32_bf16 v[54:57], v[162:165], v[178:181], v[54:57]
	v_mfma_f32_16x16x32_bf16 v[50:53], v[170:173], v[178:181], v[50:53]
	v_mfma_f32_16x16x32_bf16 v[38:41], v[162:165], v[186:189], v[38:41]
	v_mfma_f32_16x16x32_bf16 v[34:37], v[170:173], v[186:189], v[34:37]
	v_mfma_f32_16x16x32_bf16 v[22:25], v[162:165], v[194:197], v[22:25]
	v_mfma_f32_16x16x32_bf16 v[18:21], v[170:173], v[194:197], v[18:21]
	v_mfma_f32_16x16x32_bf16 v[6:9], v[162:165], v[202:205], v[6:9]
	v_mfma_f32_16x16x32_bf16 v[2:5], v[170:173], v[202:205], v[2:5]
	v_mfma_f32_16x16x32_bf16 v[54:57], v[166:169], v[182:185], v[54:57]
	v_mfma_f32_16x16x32_bf16 v[50:53], v[174:177], v[182:185], v[50:53]
	v_mfma_f32_16x16x32_bf16 v[38:41], v[166:169], v[190:193], v[38:41]
	v_mfma_f32_16x16x32_bf16 v[34:37], v[174:177], v[190:193], v[34:37]
	v_mfma_f32_16x16x32_bf16 v[22:25], v[166:169], v[198:201], v[22:25]
	v_mfma_f32_16x16x32_bf16 v[18:21], v[174:177], v[198:201], v[18:21]
	v_mfma_f32_16x16x32_bf16 v[6:9], v[166:169], v[206:209], v[6:9]
	v_mfma_f32_16x16x32_bf16 v[2:5], v[174:177], v[206:209], v[2:5]
	s_barrier
	s_add_i32 s70, s70, 2
	s_add_u32 s4, s4, 0x100
	s_addc_u32 s5, s5, 0
	s_add_u32 s68, s68, 0x100
	s_addc_u32 s69, s69, 0
	s_cmp_gt_u32 s70, 13
	s_cbranch_scc0 .LBB0_2428
	s_and_b64 vcc, exec, s[44:45]
	s_cbranch_vccz .LBB0_2431
	s_barrier

.LBB0_2528:
	s_add_u32 s16, s10, 0x30000000
	s_addc_u32 s17, s11, 0
	s_and_b64 s[4:5], exec, s[42:43]
	s_cselect_b32 s17, s17, s9
	s_cselect_b32 s16, s16, s8
	s_add_u32 s10, s10, 0x8000000
	s_addc_u32 s11, s11, 0
	s_and_b32 s62, s2, 3
	s_add_i32 m0, s58, 0x18000
	v_lshl_add_u64 v[8:9], v[8:9], 0, s[24:25]
	s_lshl_b32 s63, s3, 6
	s_lshl_b32 s4, s3, 13
	s_lshl_b32 s64, s62, 5
	s_lshl_b32 s5, s62, 12
	s_waitcnt vmcnt(2)
	s_barrier
	global_load_lds_dwordx4 v[8:9], off
	v_lshl_add_u64 v[6:7], v[6:7], 0, s[24:25]
	s_add_i32 m0, s58, 0x1a000
	s_add_i32 s65, s58, 0x8000
	s_add_i32 s66, s58, 0xa000
	global_load_lds_dwordx4 v[6:7], off
	v_lshl_add_u64 v[2:3], v[2:3], 0, s[24:25]
	s_mov_b32 m0, s65
	s_add_u32 s2, s48, 0x100080
	global_load_lds_dwordx4 v[2:3], off
	v_lshl_add_u64 v[2:3], v[4:5], 0, s[24:25]
	s_mov_b32 m0, s66
	s_addc_u32 s3, s49, 0
	global_load_lds_dwordx4 v[2:3], off
	s_add_i32 m0, s58, 0x1c000
	global_load_lds_dwordx4 v0, s[2:3]
	v_lshl_add_u64 v[2:3], s[2:3], 0, v[130:131]
	s_add_i32 m0, s58, 0x1e000
	v_bfe_u32 v140, v10, 4, 2
	global_load_lds_dwordx4 v[2:3], off
	v_and_b32_e32 v141, 15, v10
	v_lshlrev_b32_e32 v2, 4, v140
	v_lshlrev_b32_e32 v3, 2, v10
	v_lshl_or_b32 v2, v141, 6, v2
	v_and_b32_e32 v3, 32, v3
	v_bitop3_b32 v4, v2, s4, v3 bitop3:0xde
	v_bitop3_b32 v142, v2, s5, v3 bitop3:0xde
	v_lshlrev_b32_e32 v2, 16, v11
	v_and_b32_e32 v2, 0xfffe0000, v2
	v_lshl_add_u32 v2, v12, 13, v2
	v_and_b32_e32 v3, 1, v11
	v_lshl_or_b32 v2, v3, 6, v2
	v_lshl_add_u32 v132, v13, 1, v2
	v_lshlrev_b32_e32 v2, 16, v14
	v_and_b32_e32 v2, 0xfffe0000, v2
	s_waitcnt vmcnt(6)
	v_lshl_add_u32 v2, v15, 13, v2
	v_and_b32_e32 v3, 1, v14
	s_cmpk_lt_u32 s18, 0x100
	v_lshl_or_b32 v2, v3, 6, v2
	s_cselect_b64 s[18:19], -1, 0
	s_ashr_i32 s67, s13, 31
	s_ashr_i32 s68, s52, 31
	v_mov_b32_e32 v133, v1
	v_lshl_add_u32 v134, v16, 1, v2
	v_mov_b32_e32 v135, v1
	s_mov_b32 s69, 0
	v_add_u32_e32 v143, 0, v4
	s_barrier
	s_branch .LBB0_2531

.LBB0_2540:
	s_add_u32 s20, s4, 0xfff00080
	s_addc_u32 s21, s5, -1
	s_add_i32 s37, 0, 0x10000
	s_cmp_eq_u32 s73, 60
	s_cselect_b32 s51, s43, s21
	s_cselect_b32 s50, s42, s20
	s_cselect_b32 s49, s41, s72
	s_cselect_b32 s48, s47, s71
	s_add_i32 s77, 0, 0x14000
	v_add_u32_e32 v152, s37, v142
	v_add_u32_e32 v168, s77, v142
	ds_read_b128 v[136:139], v152
	ds_read_b128 v[144:147], v152 offset:1024
	ds_read_b128 v[148:151], v152 offset:2048
	ds_read_b128 v[152:155], v152 offset:3072
	ds_read_b128 v[156:159], v168
	ds_read_b128 v[160:163], v168 offset:1024
	ds_read_b128 v[164:167], v168 offset:2048
	ds_read_b128 v[168:171], v168 offset:3072
	s_add_i32 m0, s58, 0xc000
	ds_read_b128 v[172:175], v143
	ds_read_b128 v[176:179], v143 offset:1024
	ds_read_b128 v[180:183], v143 offset:2048
	ds_read_b128 v[184:187], v143 offset:3072
	ds_read_b128 v[188:191], v143 offset:4096
	ds_read_b128 v[192:195], v143 offset:5120
	ds_read_b128 v[196:199], v143 offset:6144
	ds_read_b128 v[200:203], v143 offset:7168
	global_load_lds_dwordx4 v132, s[4:5]
	s_add_i32 m0, s58, 0xe000
	s_nop 0
	global_load_lds_dwordx4 v134, s[4:5]
	s_waitcnt vmcnt(8)
	s_waitcnt lgkmcnt(0)
	s_barrier
	s_waitcnt lgkmcnt(0)
	v_mfma_f32_16x16x32_bf16 v[126:129], v[136:139], v[172:175], v[126:129]
	v_mfma_f32_16x16x32_bf16 v[122:125], v[148:151], v[172:175], v[122:125]
	v_mfma_f32_16x16x32_bf16 v[110:113], v[136:139], v[180:183], v[110:113]
	v_mfma_f32_16x16x32_bf16 v[106:109], v[148:151], v[180:183], v[106:109]
	v_mfma_f32_16x16x32_bf16 v[94:97], v[136:139], v[188:191], v[94:97]
	v_mfma_f32_16x16x32_bf16 v[90:93], v[148:151], v[188:191], v[90:93]
	v_mfma_f32_16x16x32_bf16 v[78:81], v[136:139], v[196:199], v[78:81]
	v_mfma_f32_16x16x32_bf16 v[74:77], v[148:151], v[196:199], v[74:77]
	v_mfma_f32_16x16x32_bf16 v[126:129], v[144:147], v[176:179], v[126:129]
	v_mfma_f32_16x16x32_bf16 v[122:125], v[152:155], v[176:179], v[122:125]
	v_mfma_f32_16x16x32_bf16 v[110:113], v[144:147], v[184:187], v[110:113]
	v_mfma_f32_16x16x32_bf16 v[106:109], v[152:155], v[184:187], v[106:109]
	v_mfma_f32_16x16x32_bf16 v[94:97], v[144:147], v[192:195], v[94:97]
	v_mfma_f32_16x16x32_bf16 v[90:93], v[152:155], v[192:195], v[90:93]
	v_mfma_f32_16x16x32_bf16 v[78:81], v[144:147], v[200:203], v[78:81]
	v_mfma_f32_16x16x32_bf16 v[74:77], v[152:155], v[200:203], v[74:77]
	v_mfma_f32_16x16x32_bf16 v[118:121], v[156:159], v[172:175], v[118:121]
	v_mfma_f32_16x16x32_bf16 v[114:117], v[164:167], v[172:175], v[114:117]
	v_mfma_f32_16x16x32_bf16 v[102:105], v[156:159], v[180:183], v[102:105]
	v_mfma_f32_16x16x32_bf16 v[98:101], v[164:167], v[180:183], v[98:101]
	v_mfma_f32_16x16x32_bf16 v[86:89], v[156:159], v[188:191], v[86:89]
	v_mfma_f32_16x16x32_bf16 v[82:85], v[164:167], v[188:191], v[82:85]
	v_mfma_f32_16x16x32_bf16 v[70:73], v[156:159], v[196:199], v[70:73]
	v_mfma_f32_16x16x32_bf16 v[66:69], v[164:167], v[196:199], v[66:69]
	v_mfma_f32_16x16x32_bf16 v[118:121], v[160:163], v[176:179], v[118:121]
	v_mfma_f32_16x16x32_bf16 v[114:117], v[168:171], v[176:179], v[114:117]
	v_mfma_f32_16x16x32_bf16 v[102:105], v[160:163], v[184:187], v[102:105]
	v_mfma_f32_16x16x32_bf16 v[98:101], v[168:171], v[184:187], v[98:101]
	v_mfma_f32_16x16x32_bf16 v[86:89], v[160:163], v[192:195], v[86:89]
	v_mfma_f32_16x16x32_bf16 v[82:85], v[168:171], v[192:195], v[82:85]
	v_mfma_f32_16x16x32_bf16 v[70:73], v[160:163], v[200:203], v[70:73]
	v_mfma_f32_16x16x32_bf16 v[66:69], v[168:171], v[200:203], v[66:69]
	s_barrier
	s_add_i32 s20, s37, s57
	v_lshl_add_u64 v[204:205], s[48:49], 0, v[0:1]
	s_mov_b32 m0, s20
	ds_read_b128 v[172:175], v143 offset:16384
	ds_read_b128 v[176:179], v143 offset:17408
	ds_read_b128 v[180:183], v143 offset:18432
	ds_read_b128 v[184:187], v143 offset:19456
	ds_read_b128 v[188:191], v143 offset:20480
	ds_read_b128 v[192:195], v143 offset:21504
	ds_read_b128 v[196:199], v143 offset:22528
	ds_read_b128 v[200:203], v143 offset:23552
	global_load_lds_dwordx4 v[204:205], off
	s_add_i32 m0, s20, 0x2000
	s_add_u32 s20, s48, 0x100000
	v_lshl_add_u64 v[206:207], s[48:49], 0, v[130:131]
	s_addc_u32 s21, s49, 0
	s_add_i32 s37, s77, s57
	global_load_lds_dwordx4 v[206:207], off
	s_mov_b32 m0, s37
	v_lshl_add_u64 v[210:211], s[50:51], 0, v[130:131]
	global_load_lds_dwordx4 v0, s[20:21]
	s_add_i32 m0, s37, 0x2000
	s_nop 0
	global_load_lds_dwordx4 v130, s[20:21]
	v_lshl_add_u64 v[208:209], s[50:51], 0, v[0:1]
	s_mov_b32 m0, s58
	s_nop 0
	global_load_lds_dwordx4 v[208:209], off
	s_mov_b32 m0, s59
	s_nop 0
	global_load_lds_dwordx4 v[210:211], off
	s_waitcnt vmcnt(8)
	s_waitcnt lgkmcnt(0)
	s_barrier
	s_waitcnt lgkmcnt(0)
	v_mfma_f32_16x16x32_bf16 v[62:65], v[136:139], v[172:175], v[62:65]
	v_mfma_f32_16x16x32_bf16 v[58:61], v[148:151], v[172:175], v[58:61]
	v_mfma_f32_16x16x32_bf16 v[46:49], v[136:139], v[180:183], v[46:49]
	v_mfma_f32_16x16x32_bf16 v[42:45], v[148:151], v[180:183], v[42:45]
	v_mfma_f32_16x16x32_bf16 v[30:33], v[136:139], v[188:191], v[30:33]
	v_mfma_f32_16x16x32_bf16 v[26:29], v[148:151], v[188:191], v[26:29]
	v_mfma_f32_16x16x32_bf16 v[14:17], v[136:139], v[196:199], v[14:17]
	v_mfma_f32_16x16x32_bf16 v[10:13], v[148:151], v[196:199], v[10:13]
	v_mfma_f32_16x16x32_bf16 v[62:65], v[144:147], v[176:179], v[62:65]
	v_mfma_f32_16x16x32_bf16 v[58:61], v[152:155], v[176:179], v[58:61]
	v_mfma_f32_16x16x32_bf16 v[46:49], v[144:147], v[184:187], v[46:49]
	v_mfma_f32_16x16x32_bf16 v[42:45], v[152:155], v[184:187], v[42:45]
	v_mfma_f32_16x16x32_bf16 v[30:33], v[144:147], v[192:195], v[30:33]
	v_mfma_f32_16x16x32_bf16 v[26:29], v[152:155], v[192:195], v[26:29]
	v_mfma_f32_16x16x32_bf16 v[14:17], v[144:147], v[200:203], v[14:17]
	v_mfma_f32_16x16x32_bf16 v[10:13], v[152:155], v[200:203], v[10:13]
	v_mfma_f32_16x16x32_bf16 v[54:57], v[156:159], v[172:175], v[54:57]
	v_mfma_f32_16x16x32_bf16 v[50:53], v[164:167], v[172:175], v[50:53]
	v_mfma_f32_16x16x32_bf16 v[38:41], v[156:159], v[180:183], v[38:41]
	v_mfma_f32_16x16x32_bf16 v[34:37], v[164:167], v[180:183], v[34:37]
	v_mfma_f32_16x16x32_bf16 v[22:25], v[156:159], v[188:191], v[22:25]
	v_mfma_f32_16x16x32_bf16 v[18:21], v[164:167], v[188:191], v[18:21]
	v_mfma_f32_16x16x32_bf16 v[6:9], v[156:159], v[196:199], v[6:9]
	v_mfma_f32_16x16x32_bf16 v[2:5], v[164:167], v[196:199], v[2:5]
	v_mfma_f32_16x16x32_bf16 v[54:57], v[160:163], v[176:179], v[54:57]
	v_mfma_f32_16x16x32_bf16 v[50:53], v[168:171], v[176:179], v[50:53]
	v_mfma_f32_16x16x32_bf16 v[38:41], v[160:163], v[184:187], v[38:41]
	v_mfma_f32_16x16x32_bf16 v[34:37], v[168:171], v[184:187], v[34:37]
	v_mfma_f32_16x16x32_bf16 v[22:25], v[160:163], v[192:195], v[22:25]
	v_mfma_f32_16x16x32_bf16 v[18:21], v[168:171], v[192:195], v[18:21]
	v_mfma_f32_16x16x32_bf16 v[6:9], v[160:163], v[200:203], v[6:9]
	v_mfma_f32_16x16x32_bf16 v[2:5], v[168:171], v[200:203], v[2:5]
	s_barrier
	s_add_i32 s37, 0, 0x18000
	s_add_i32 s77, 0, 0x1c000
	v_add_u32_e32 v152, s37, v142
	v_add_u32_e32 v168, s77, v142
	ds_read_b128 v[136:139], v152
	ds_read_b128 v[144:147], v152 offset:1024
	ds_read_b128 v[148:151], v152 offset:2048
	ds_read_b128 v[152:155], v152 offset:3072
	ds_read_b128 v[156:159], v168
	ds_read_b128 v[160:163], v168 offset:1024
	ds_read_b128 v[164:167], v168 offset:2048
	ds_read_b128 v[168:171], v168 offset:3072
	s_add_u32 s20, s50, 0x100000
	s_addc_u32 s21, s51, 0
	s_mov_b32 m0, s60
	ds_read_b128 v[172:175], v143 offset:32768
	ds_read_b128 v[176:179], v143 offset:33792
	ds_read_b128 v[180:183], v143 offset:34816
	ds_read_b128 v[184:187], v143 offset:35840
	ds_read_b128 v[188:191], v143 offset:36864
	ds_read_b128 v[192:195], v143 offset:37888
	ds_read_b128 v[196:199], v143 offset:38912
	ds_read_b128 v[200:203], v143 offset:39936
	global_load_lds_dwordx4 v0, s[20:21]
	v_lshl_add_u64 v[214:215], s[20:21], 0, v[130:131]
	s_mov_b32 m0, s61
	s_nop 0
	global_load_lds_dwordx4 v[214:215], off
	s_waitcnt vmcnt(8)
	s_waitcnt lgkmcnt(0)
	s_barrier
	s_waitcnt lgkmcnt(0)
	v_mfma_f32_16x16x32_bf16 v[126:129], v[136:139], v[172:175], v[126:129]
	v_mfma_f32_16x16x32_bf16 v[122:125], v[148:151], v[172:175], v[122:125]
	v_mfma_f32_16x16x32_bf16 v[110:113], v[136:139], v[180:183], v[110:113]
	v_mfma_f32_16x16x32_bf16 v[106:109], v[148:151], v[180:183], v[106:109]
	v_mfma_f32_16x16x32_bf16 v[94:97], v[136:139], v[188:191], v[94:97]
	v_mfma_f32_16x16x32_bf16 v[90:93], v[148:151], v[188:191], v[90:93]
	v_mfma_f32_16x16x32_bf16 v[78:81], v[136:139], v[196:199], v[78:81]
	v_mfma_f32_16x16x32_bf16 v[74:77], v[148:151], v[196:199], v[74:77]
	v_mfma_f32_16x16x32_bf16 v[126:129], v[144:147], v[176:179], v[126:129]
	v_mfma_f32_16x16x32_bf16 v[122:125], v[152:155], v[176:179], v[122:125]
	v_mfma_f32_16x16x32_bf16 v[110:113], v[144:147], v[184:187], v[110:113]
	v_mfma_f32_16x16x32_bf16 v[106:109], v[152:155], v[184:187], v[106:109]
	v_mfma_f32_16x16x32_bf16 v[94:97], v[144:147], v[192:195], v[94:97]
	v_mfma_f32_16x16x32_bf16 v[90:93], v[152:155], v[192:195], v[90:93]
	v_mfma_f32_16x16x32_bf16 v[78:81], v[144:147], v[200:203], v[78:81]
	v_mfma_f32_16x16x32_bf16 v[74:77], v[152:155], v[200:203], v[74:77]
	v_mfma_f32_16x16x32_bf16 v[118:121], v[156:159], v[172:175], v[118:121]
	v_mfma_f32_16x16x32_bf16 v[114:117], v[164:167], v[172:175], v[114:117]
	v_mfma_f32_16x16x32_bf16 v[102:105], v[156:159], v[180:183], v[102:105]
	v_mfma_f32_16x16x32_bf16 v[98:101], v[164:167], v[180:183], v[98:101]
	v_mfma_f32_16x16x32_bf16 v[86:89], v[156:159], v[188:191], v[86:89]
	v_mfma_f32_16x16x32_bf16 v[82:85], v[164:167], v[188:191], v[82:85]
	v_mfma_f32_16x16x32_bf16 v[70:73], v[156:159], v[196:199], v[70:73]
	v_mfma_f32_16x16x32_bf16 v[66:69], v[164:167], v[196:199], v[66:69]
	v_mfma_f32_16x16x32_bf16 v[118:121], v[160:163], v[176:179], v[118:121]
	v_mfma_f32_16x16x32_bf16 v[114:117], v[168:171], v[176:179], v[114:117]
	v_mfma_f32_16x16x32_bf16 v[102:105], v[160:163], v[184:187], v[102:105]
	v_mfma_f32_16x16x32_bf16 v[98:101], v[168:171], v[184:187], v[98:101]
	v_mfma_f32_16x16x32_bf16 v[86:89], v[160:163], v[192:195], v[86:89]
	v_mfma_f32_16x16x32_bf16 v[82:85], v[168:171], v[192:195], v[82:85]
	v_mfma_f32_16x16x32_bf16 v[70:73], v[160:163], v[200:203], v[70:73]
	v_mfma_f32_16x16x32_bf16 v[66:69], v[168:171], v[200:203], v[66:69]
	s_barrier
	s_add_i32 s20, s37, s57
	v_lshl_add_u64 v[204:205], v[204:205], 0, s[24:25]
	s_mov_b32 m0, s20
	ds_read_b128 v[172:175], v143 offset:49152
	ds_read_b128 v[176:179], v143 offset:50176
	ds_read_b128 v[180:183], v143 offset:51200
	ds_read_b128 v[184:187], v143 offset:52224
	ds_read_b128 v[188:191], v143 offset:53248
	ds_read_b128 v[192:195], v143 offset:54272
	ds_read_b128 v[196:199], v143 offset:55296
	ds_read_b128 v[200:203], v143 offset:56320
	global_load_lds_dwordx4 v[204:205], off
	s_add_i32 m0, s20, 0x2000
	s_add_u32 s20, s48, 0x100080
	v_lshl_add_u64 v[204:205], v[206:207], 0, s[24:25]
	s_addc_u32 s21, s49, 0
	s_add_i32 s37, s77, s57
	global_load_lds_dwordx4 v[204:205], off
	s_mov_b32 m0, s37
	s_nop 0
	global_load_lds_dwordx4 v0, s[20:21]
	s_add_i32 m0, s37, 0x2000
	s_nop 0
	global_load_lds_dwordx4 v130, s[20:21]
	v_lshl_add_u64 v[204:205], v[208:209], 0, s[24:25]
	s_mov_b32 m0, s65
	s_nop 0
	global_load_lds_dwordx4 v[204:205], off
	v_lshl_add_u64 v[204:205], v[210:211], 0, s[24:25]
	s_mov_b32 m0, s66
	s_nop 0
	global_load_lds_dwordx4 v[204:205], off
	s_waitcnt vmcnt(8)
	s_waitcnt lgkmcnt(0)
	s_barrier
	s_waitcnt lgkmcnt(0)
	v_mfma_f32_16x16x32_bf16 v[62:65], v[136:139], v[172:175], v[62:65]
	v_mfma_f32_16x16x32_bf16 v[58:61], v[148:151], v[172:175], v[58:61]
	v_mfma_f32_16x16x32_bf16 v[46:49], v[136:139], v[180:183], v[46:49]
	v_mfma_f32_16x16x32_bf16 v[42:45], v[148:151], v[180:183], v[42:45]
	v_mfma_f32_16x16x32_bf16 v[30:33], v[136:139], v[188:191], v[30:33]
	v_mfma_f32_16x16x32_bf16 v[26:29], v[148:151], v[188:191], v[26:29]
	v_mfma_f32_16x16x32_bf16 v[14:17], v[136:139], v[196:199], v[14:17]
	v_mfma_f32_16x16x32_bf16 v[10:13], v[148:151], v[196:199], v[10:13]
	v_mfma_f32_16x16x32_bf16 v[62:65], v[144:147], v[176:179], v[62:65]
	v_mfma_f32_16x16x32_bf16 v[58:61], v[152:155], v[176:179], v[58:61]
	v_mfma_f32_16x16x32_bf16 v[46:49], v[144:147], v[184:187], v[46:49]
	v_mfma_f32_16x16x32_bf16 v[42:45], v[152:155], v[184:187], v[42:45]
	v_mfma_f32_16x16x32_bf16 v[30:33], v[144:147], v[192:195], v[30:33]
	v_mfma_f32_16x16x32_bf16 v[26:29], v[152:155], v[192:195], v[26:29]
	v_mfma_f32_16x16x32_bf16 v[14:17], v[144:147], v[200:203], v[14:17]
	v_mfma_f32_16x16x32_bf16 v[10:13], v[152:155], v[200:203], v[10:13]
	v_mfma_f32_16x16x32_bf16 v[54:57], v[156:159], v[172:175], v[54:57]
	v_mfma_f32_16x16x32_bf16 v[50:53], v[164:167], v[172:175], v[50:53]
	v_mfma_f32_16x16x32_bf16 v[38:41], v[156:159], v[180:183], v[38:41]
	v_mfma_f32_16x16x32_bf16 v[34:37], v[164:167], v[180:183], v[34:37]
	v_mfma_f32_16x16x32_bf16 v[22:25], v[156:159], v[188:191], v[22:25]
	v_mfma_f32_16x16x32_bf16 v[18:21], v[164:167], v[188:191], v[18:21]
	v_mfma_f32_16x16x32_bf16 v[6:9], v[156:159], v[196:199], v[6:9]
	v_mfma_f32_16x16x32_bf16 v[2:5], v[164:167], v[196:199], v[2:5]
	v_mfma_f32_16x16x32_bf16 v[54:57], v[160:163], v[176:179], v[54:57]
	v_mfma_f32_16x16x32_bf16 v[50:53], v[168:171], v[176:179], v[50:53]
	v_mfma_f32_16x16x32_bf16 v[38:41], v[160:163], v[184:187], v[38:41]
	v_mfma_f32_16x16x32_bf16 v[34:37], v[168:171], v[184:187], v[34:37]
	v_mfma_f32_16x16x32_bf16 v[22:25], v[160:163], v[192:195], v[22:25]
	v_mfma_f32_16x16x32_bf16 v[18:21], v[168:171], v[192:195], v[18:21]
	v_mfma_f32_16x16x32_bf16 v[6:9], v[160:163], v[200:203], v[6:9]
	v_mfma_f32_16x16x32_bf16 v[2:5], v[168:171], v[200:203], v[2:5]
	s_barrier
	s_add_i32 s73, s73, 2
	s_add_u32 s4, s4, 0x100
	s_addc_u32 s5, s5, 0
	s_add_u32 s71, s71, 0x100
	s_addc_u32 s72, s72, 0
	s_cmp_gt_u32 s73, 61
	s_cbranch_scc0 .LBB0_2540
	s_and_b64 vcc, exec, s[18:19]
	s_cbranch_vccz .LBB0_2543
	s_barrier
